# GEMM K-loops: per-segment s_setprio flips removed, one static s_setprio 1 for waves 4-7 around each K-loop
# speedup vs baseline: 1.0066x; 1.0027x over previous
; #define PG8_STAGE(bufoff, gbase, voff) do { _Pragma("unroll") for (int _i = 0; _i < 2; ++_i) \
;         __builtin_amdgcn_global_load_lds((const unsigned*)((const char*)(gbase) + (voff)[_i]), (PG8_LAS unsigned*)(lds + (bufoff) + ldsw + _i * 8192), 16, 0, 0); } while (0)
; #define PG8_LDA(dst, b, h) do { _Pragma("unroll") for (int m = 0; m < 4; ++m) _Pragma("unroll") for (int k = 0; k < 2; ++k) dst[m][k] = *(const PG8_LAS bf16x8*)(lds + PG8_SA(b, h) + aoff + m * 2048 + k * 1024); } while (0)
; #define PG8_LDB(dst, b, h) do { _Pragma("unroll") for (int n = 0; n < 2; ++n) _Pragma("unroll") for (int k = 0; k < 2; ++k) dst[n][k] = *(const PG8_LAS bf16x8*)(lds + PG8_SB(b, h) + boff + n * 2048 + k * 1024); } while (0)
; #define PG8_SCHED __builtin_amdgcn_sched_barrier(0)
; template <class Epi, class Sched, bool ALIGN_EPI = false, bool SP2 = false>
; __device__ __forceinline__ void gemm_phase(PG8_LAS unsigned char* lds, const Gemm g, const Sched& S, const Epi& E, int wid_in) {
;     ...
;         const bool has_next = S.next(ui + 1, nxt);
;         const char* nA = has_next ? (const char*)g.A + (size_t)nxt.pm * tstep + (size_t)nxt.kt0 * kstep : cA; const char* nB = has_next ? (const char*)g.Bt + (size_t)nxt.pn * tstep + (size_t)nxt.kt0 * kstep : cB;
;         const int nt = cur.nkt;
;         for (int t = 0; t < nt; t += 2) {
;             const bool last = (t == nt - 2);
;             const char* a1 = cA + (size_t)(t + 1) * kstep;
;             const char* a2 = last ? nA : cA + (size_t)(t + 2) * kstep; const char* b2 = last ? nB : cB + (size_t)(t + 2) * kstep;
;             const char* a3 = a2 + kstep; const char* b3 = b2 + kstep;
;             if (last && has_next) S.a_ready(nxt);
;             if constexpr (SP2) {
;             PG8_LDB(B0, 0, 0); PG8_LDB(B1, 0, 1); PG8_SCHED; PG8_LDA(At, 0, 0); PG8_STAGE(PG8_SA(1, 1), a1 + hstep, voffA);
;     ...
; #pragma unroll
;         for (int a = 0; a < 2; ++a)
; #pragma unroll
;             for (int b = 0; b < 2; ++b)
; #pragma unroll
;                 for (int m = 0; m < 4; ++m)
; #pragma unroll
;                     for (int n = 0; n < 2; ++n) acc[a][b][m][n] = (f32x4){0.f, 0.f, 0.f, 0.f};
.LBB0_277:
	s_ashr_i32 s19, s18, 31
	s_lshl_b64 s[22:23], s[18:19], 20
	s_add_u32 s22, s0, s22
	s_addc_u32 s23, s1, s23
	s_and_b64 s[24:25], s[20:21], exec
	s_cselect_b32 s11, s23, s27
	s_cselect_b32 s19, s22, s26
	s_ashr_i32 s17, s16, 31
	s_lshl_b64 s[24:25], s[16:17], 20
	s_add_u32 s24, s34, s24
	s_addc_u32 s25, s35, s25
	s_and_b64 s[30:31], s[20:21], exec
	s_cselect_b32 s17, s25, s29
	s_cselect_b32 s62, s24, s28
	s_add_u32 s64, s28, 0x100
	s_addc_u32 s65, s29, 0
	s_add_u32 s26, s26, 0x80080
	v_mov_b32_e32 v2, 0
	s_addc_u32 s27, s27, 0
	s_mov_b32 s63, -2
	v_mov_b32_e32 v3, v2
	v_mov_b32_e32 v4, v2
	v_mov_b32_e32 v5, v2
	v_mov_b32_e32 v6, v2
	v_mov_b32_e32 v7, v2
	v_mov_b32_e32 v8, v2
	v_mov_b32_e32 v9, v2
	v_mov_b32_e32 v10, v2
	v_mov_b32_e32 v11, v2
	v_mov_b32_e32 v12, v2
	v_mov_b32_e32 v13, v2
	v_mov_b32_e32 v14, v2
	v_mov_b32_e32 v15, v2
	v_mov_b32_e32 v16, v2
	v_mov_b32_e32 v17, v2
	v_mov_b32_e32 v26, v2
	v_mov_b32_e32 v27, v2
	v_mov_b32_e32 v28, v2
	v_mov_b32_e32 v29, v2
	v_mov_b32_e32 v30, v2
	v_mov_b32_e32 v31, v2
	v_mov_b32_e32 v32, v2
	v_mov_b32_e32 v33, v2
	v_mov_b32_e32 v42, v2
	v_mov_b32_e32 v43, v2
	v_mov_b32_e32 v44, v2
	v_mov_b32_e32 v45, v2
	v_mov_b32_e32 v46, v2
	v_mov_b32_e32 v47, v2
	v_mov_b32_e32 v48, v2
	v_mov_b32_e32 v49, v2
	v_mov_b32_e32 v18, v2
	v_mov_b32_e32 v19, v2
	v_mov_b32_e32 v20, v2
	v_mov_b32_e32 v21, v2
	v_mov_b32_e32 v22, v2
	v_mov_b32_e32 v23, v2
	v_mov_b32_e32 v24, v2
	v_mov_b32_e32 v25, v2
	v_mov_b32_e32 v34, v2
	v_mov_b32_e32 v35, v2
	v_mov_b32_e32 v36, v2
	v_mov_b32_e32 v37, v2
	v_mov_b32_e32 v38, v2
	v_mov_b32_e32 v39, v2
	v_mov_b32_e32 v40, v2
	v_mov_b32_e32 v41, v2
	v_mov_b32_e32 v50, v2
	v_mov_b32_e32 v51, v2
	v_mov_b32_e32 v52, v2
	v_mov_b32_e32 v53, v2
	v_mov_b32_e32 v54, v2
	v_mov_b32_e32 v55, v2
	v_mov_b32_e32 v56, v2
	v_mov_b32_e32 v57, v2
	v_mov_b32_e32 v58, v2
	v_mov_b32_e32 v59, v2
	v_mov_b32_e32 v60, v2
	v_mov_b32_e32 v61, v2
	v_mov_b32_e32 v62, v2
	v_mov_b32_e32 v63, v2
	v_mov_b32_e32 v64, v2
	v_mov_b32_e32 v65, v2
	v_mov_b32_e32 v66, v2
	v_mov_b32_e32 v67, v2
	v_mov_b32_e32 v68, v2
	v_mov_b32_e32 v69, v2
	v_mov_b32_e32 v70, v2
	v_mov_b32_e32 v71, v2
	v_mov_b32_e32 v72, v2
	v_mov_b32_e32 v73, v2
	v_mov_b32_e32 v74, v2
	v_mov_b32_e32 v75, v2
	v_mov_b32_e32 v76, v2
	v_mov_b32_e32 v77, v2
	v_mov_b32_e32 v78, v2
	v_mov_b32_e32 v79, v2
	v_mov_b32_e32 v80, v2
	v_mov_b32_e32 v81, v2
	v_mov_b32_e32 v90, v2
	v_mov_b32_e32 v91, v2
	v_mov_b32_e32 v92, v2
	v_mov_b32_e32 v93, v2
	v_mov_b32_e32 v94, v2
	v_mov_b32_e32 v95, v2
	v_mov_b32_e32 v96, v2
	v_mov_b32_e32 v97, v2
	v_mov_b32_e32 v106, v2
	v_mov_b32_e32 v107, v2
	v_mov_b32_e32 v108, v2
	v_mov_b32_e32 v109, v2
	v_mov_b32_e32 v110, v2
	v_mov_b32_e32 v111, v2
	v_mov_b32_e32 v112, v2
	v_mov_b32_e32 v113, v2
	v_mov_b32_e32 v82, v2
	v_mov_b32_e32 v83, v2
	v_mov_b32_e32 v84, v2
	v_mov_b32_e32 v85, v2
	v_mov_b32_e32 v86, v2
	v_mov_b32_e32 v87, v2
	v_mov_b32_e32 v88, v2
	v_mov_b32_e32 v89, v2
	v_mov_b32_e32 v98, v2
	v_mov_b32_e32 v99, v2
	v_mov_b32_e32 v100, v2
	v_mov_b32_e32 v101, v2
	v_mov_b32_e32 v102, v2
	v_mov_b32_e32 v103, v2
	v_mov_b32_e32 v104, v2
	v_mov_b32_e32 v105, v2
	v_mov_b32_e32 v114, v2
	v_mov_b32_e32 v115, v2
	v_mov_b32_e32 v116, v2
	v_mov_b32_e32 v117, v2
	v_mov_b32_e32 v118, v2
	v_mov_b32_e32 v119, v2
	v_mov_b32_e32 v120, v2
	v_mov_b32_e32 v121, v2
	v_mov_b32_e32 v122, v2
	v_mov_b32_e32 v123, v2
	v_mov_b32_e32 v124, v2
	v_mov_b32_e32 v125, v2
	v_mov_b32_e32 v126, v2
	v_mov_b32_e32 v127, v2
	v_mov_b32_e32 v128, v2
	v_mov_b32_e32 v129, v2
	s_cmp_ge_u32 s47, 4
	s_cbranch_scc0 .Lprio_skip_0
	s_setprio 1
.Lprio_skip_0:
.LBB0_278:
	s_add_u32 s28, s26, 0xfff80080
	s_addc_u32 s29, s27, -1
	s_add_i32 s40, 0, 0x10000
	s_cmp_eq_u32 s63, 28
	s_cselect_b32 s31, s11, s29
	s_cselect_b32 s30, s19, s28
	s_cselect_b32 s29, s17, s65
	s_cselect_b32 s28, s62, s64
	s_add_i32 s41, 0, 0x14000
	v_add_u32_e32 v154, s40, v140
	v_add_u32_e32 v170, s41, v140
	ds_read_b128 v[142:145], v154
	ds_read_b128 v[146:149], v154 offset:1024
	ds_read_b128 v[150:153], v154 offset:2048
	ds_read_b128 v[154:157], v154 offset:3072
	ds_read_b128 v[158:161], v170
	ds_read_b128 v[162:165], v170 offset:1024
	ds_read_b128 v[166:169], v170 offset:2048
	ds_read_b128 v[170:173], v170 offset:3072
	v_lshl_add_u64 v[220:221], s[26:27], 0, v[138:139]
	s_add_i32 m0, s13, 0xc000
	ds_read_b128 v[174:177], v141
	ds_read_b128 v[178:181], v141 offset:1024
	ds_read_b128 v[182:185], v141 offset:2048
	ds_read_b128 v[186:189], v141 offset:3072
	ds_read_b128 v[190:193], v141 offset:4096
	ds_read_b128 v[208:211], v141 offset:5120
	ds_read_b128 v[212:215], v141 offset:6144
	ds_read_b128 v[216:219], v141 offset:7168
	global_load_lds_dwordx4 v[220:221], off
	v_lshl_add_u64 v[220:221], s[26:27], 0, v[136:137]
	s_add_i32 m0, s13, 0xe000
	s_nop 0
	global_load_lds_dwordx4 v[220:221], off
	s_waitcnt vmcnt(8)
	s_waitcnt lgkmcnt(0)
	s_barrier
; #define PG8_STAGE(bufoff, gbase, voff) do { _Pragma("unroll") for (int _i = 0; _i < 2; ++_i) \
;         __builtin_amdgcn_global_load_lds((const unsigned*)((const char*)(gbase) + (voff)[_i]), (PG8_LAS unsigned*)(lds + (bufoff) + ldsw + _i * 8192), 16, 0, 0); } while (0)
; #define PG8_LDA(dst, b, h) do { _Pragma("unroll") for (int m = 0; m < 4; ++m) _Pragma("unroll") for (int k = 0; k < 2; ++k) dst[m][k] = *(const PG8_LAS bf16x8*)(lds + PG8_SA(b, h) + aoff + m * 2048 + k * 1024); } while (0)
; #define PG8_MMA(ai, bj, At, Bt) do { __builtin_amdgcn_s_setprio(1); _Pragma("unroll") for (int m = 0; m < 4; ++m) _Pragma("unroll") for (int n = 0; n < 2; ++n) _Pragma("unroll") for (int k = 0; k < 2; ++k) \
;         acc[ai][bj][m][n] = __builtin_amdgcn_mfma_f32_16x16x32_bf16(Bt[n][k], At[m][k], acc[ai][bj][m][n], 0, 0, 0); __builtin_amdgcn_s_setprio(0); } while (0)
; #define PG8_WAIT_V(n) asm volatile("s_waitcnt vmcnt(" #n ")" ::: "memory")
; #define PG8_WAIT_L(n) asm volatile("s_waitcnt lgkmcnt(" #n ")" ::: "memory")
; #define PG8_BAR __builtin_amdgcn_s_barrier()
; #define PG8_SCHED __builtin_amdgcn_sched_barrier(0)
; template <class Epi, class Sched, bool ALIGN_EPI = false, bool SP2 = false>
; __device__ __forceinline__ void gemm_phase(PG8_LAS unsigned char* lds, const Gemm g, const Sched& S, const Epi& E, int wid_in) {
;     ...
;             PG8_WAIT_V(8); PG8_WAIT_L(0); PG8_BAR; PG8_MMA(0, 0, At, B0); PG8_MMA(0, 1, At, B1); PG8_BAR; PG8_SCHED;
;             PG8_LDA(At, 0, 1); PG8_STAGE(PG8_SB(0, 0), b2, voffB); PG8_STAGE(PG8_SB(0, 1), b2 + hstep, voffB); PG8_STAGE(PG8_SA(0, 0), a2, voffA);
;             PG8_WAIT_V(8); PG8_WAIT_L(0); PG8_BAR; PG8_MMA(1, 0, At, B0); PG8_MMA(1, 1, At, B1); PG8_BAR; PG8_SCHED;
	s_waitcnt lgkmcnt(0)
	v_mfma_f32_16x16x32_bf16 v[126:129], v[142:145], v[174:177], v[126:129]
	v_mfma_f32_16x16x32_bf16 v[122:125], v[150:153], v[174:177], v[122:125]
	v_mfma_f32_16x16x32_bf16 v[118:121], v[142:145], v[182:185], v[118:121]
	v_mfma_f32_16x16x32_bf16 v[114:117], v[150:153], v[182:185], v[114:117]
	v_mfma_f32_16x16x32_bf16 v[102:105], v[142:145], v[190:193], v[102:105]
	v_mfma_f32_16x16x32_bf16 v[98:101], v[150:153], v[190:193], v[98:101]
	v_mfma_f32_16x16x32_bf16 v[86:89], v[142:145], v[212:215], v[86:89]
	v_mfma_f32_16x16x32_bf16 v[82:85], v[150:153], v[212:215], v[82:85]
	v_mfma_f32_16x16x32_bf16 v[126:129], v[146:149], v[178:181], v[126:129]
	v_mfma_f32_16x16x32_bf16 v[122:125], v[154:157], v[178:181], v[122:125]
	v_mfma_f32_16x16x32_bf16 v[118:121], v[146:149], v[186:189], v[118:121]
	v_mfma_f32_16x16x32_bf16 v[114:117], v[154:157], v[186:189], v[114:117]
	v_mfma_f32_16x16x32_bf16 v[102:105], v[146:149], v[208:211], v[102:105]
	v_mfma_f32_16x16x32_bf16 v[98:101], v[154:157], v[208:211], v[98:101]
	v_mfma_f32_16x16x32_bf16 v[86:89], v[146:149], v[216:219], v[86:89]
	v_mfma_f32_16x16x32_bf16 v[82:85], v[154:157], v[216:219], v[82:85]
	v_mfma_f32_16x16x32_bf16 v[110:113], v[158:161], v[174:177], v[110:113]
	v_mfma_f32_16x16x32_bf16 v[106:109], v[166:169], v[174:177], v[106:109]
	v_mfma_f32_16x16x32_bf16 v[94:97], v[158:161], v[182:185], v[94:97]
	v_mfma_f32_16x16x32_bf16 v[90:93], v[166:169], v[182:185], v[90:93]
	v_mfma_f32_16x16x32_bf16 v[78:81], v[158:161], v[190:193], v[78:81]
	v_mfma_f32_16x16x32_bf16 v[74:77], v[166:169], v[190:193], v[74:77]
	v_mfma_f32_16x16x32_bf16 v[70:73], v[158:161], v[212:215], v[70:73]
	v_mfma_f32_16x16x32_bf16 v[66:69], v[166:169], v[212:215], v[66:69]
	v_mfma_f32_16x16x32_bf16 v[110:113], v[162:165], v[178:181], v[110:113]
	v_mfma_f32_16x16x32_bf16 v[106:109], v[170:173], v[178:181], v[106:109]
	v_mfma_f32_16x16x32_bf16 v[94:97], v[162:165], v[186:189], v[94:97]
	v_mfma_f32_16x16x32_bf16 v[90:93], v[170:173], v[186:189], v[90:93]
	v_mfma_f32_16x16x32_bf16 v[78:81], v[162:165], v[208:211], v[78:81]
	v_mfma_f32_16x16x32_bf16 v[74:77], v[170:173], v[208:211], v[74:77]
	v_mfma_f32_16x16x32_bf16 v[70:73], v[162:165], v[216:219], v[70:73]
	v_mfma_f32_16x16x32_bf16 v[66:69], v[170:173], v[216:219], v[66:69]
	s_barrier
	s_add_i32 s40, s40, s59
	v_lshl_add_u64 v[220:221], s[28:29], 0, v[0:1]
	s_mov_b32 m0, s40
	ds_read_b128 v[174:177], v141 offset:16384
	ds_read_b128 v[178:181], v141 offset:17408
	ds_read_b128 v[182:185], v141 offset:18432
	ds_read_b128 v[186:189], v141 offset:19456
	ds_read_b128 v[190:193], v141 offset:20480
	ds_read_b128 v[208:211], v141 offset:21504
	ds_read_b128 v[212:215], v141 offset:22528
	ds_read_b128 v[216:219], v141 offset:23552
	global_load_lds_dwordx4 v[220:221], off
	s_add_i32 m0, s40, 0x2000
	s_add_u32 s72, s28, 0x80000
	v_lshl_add_u64 v[222:223], s[28:29], 0, v[134:135]
	s_addc_u32 s73, s29, 0
	s_add_i32 s40, s41, s59
	global_load_lds_dwordx4 v[222:223], off
	v_lshl_add_u64 v[224:225], s[72:73], 0, v[0:1]
	s_mov_b32 m0, s40
	v_lshl_add_u64 v[226:227], s[30:31], 0, v[132:133]
	global_load_lds_dwordx4 v[224:225], off
	v_lshl_add_u64 v[224:225], s[72:73], 0, v[134:135]
	s_add_i32 m0, s40, 0x2000
	s_nop 0
	global_load_lds_dwordx4 v[224:225], off
	v_lshl_add_u64 v[224:225], s[30:31], 0, v[130:131]
	s_mov_b32 m0, s13
	s_nop 0
	global_load_lds_dwordx4 v[224:225], off
	s_mov_b32 m0, s36
	s_nop 0
	global_load_lds_dwordx4 v[226:227], off
	s_waitcnt vmcnt(8)
	s_waitcnt lgkmcnt(0)
	s_barrier
	s_waitcnt lgkmcnt(0)
	v_mfma_f32_16x16x32_bf16 v[62:65], v[142:145], v[174:177], v[62:65]
	v_mfma_f32_16x16x32_bf16 v[58:61], v[150:153], v[174:177], v[58:61]
	v_mfma_f32_16x16x32_bf16 v[54:57], v[142:145], v[182:185], v[54:57]
	v_mfma_f32_16x16x32_bf16 v[50:53], v[150:153], v[182:185], v[50:53]
	v_mfma_f32_16x16x32_bf16 v[38:41], v[142:145], v[190:193], v[38:41]
	v_mfma_f32_16x16x32_bf16 v[34:37], v[150:153], v[190:193], v[34:37]
	v_mfma_f32_16x16x32_bf16 v[22:25], v[142:145], v[212:215], v[22:25]
	v_mfma_f32_16x16x32_bf16 v[18:21], v[150:153], v[212:215], v[18:21]
	v_mfma_f32_16x16x32_bf16 v[62:65], v[146:149], v[178:181], v[62:65]
	v_mfma_f32_16x16x32_bf16 v[58:61], v[154:157], v[178:181], v[58:61]
	v_mfma_f32_16x16x32_bf16 v[54:57], v[146:149], v[186:189], v[54:57]
	v_mfma_f32_16x16x32_bf16 v[50:53], v[154:157], v[186:189], v[50:53]
	v_mfma_f32_16x16x32_bf16 v[38:41], v[146:149], v[208:211], v[38:41]
	v_mfma_f32_16x16x32_bf16 v[34:37], v[154:157], v[208:211], v[34:37]
	v_mfma_f32_16x16x32_bf16 v[22:25], v[146:149], v[216:219], v[22:25]
	v_mfma_f32_16x16x32_bf16 v[18:21], v[154:157], v[216:219], v[18:21]
	v_mfma_f32_16x16x32_bf16 v[46:49], v[158:161], v[174:177], v[46:49]
	v_mfma_f32_16x16x32_bf16 v[42:45], v[166:169], v[174:177], v[42:45]
	v_mfma_f32_16x16x32_bf16 v[30:33], v[158:161], v[182:185], v[30:33]
	v_mfma_f32_16x16x32_bf16 v[26:29], v[166:169], v[182:185], v[26:29]
	v_mfma_f32_16x16x32_bf16 v[14:17], v[158:161], v[190:193], v[14:17]
	v_mfma_f32_16x16x32_bf16 v[10:13], v[166:169], v[190:193], v[10:13]
	v_mfma_f32_16x16x32_bf16 v[6:9], v[158:161], v[212:215], v[6:9]
	v_mfma_f32_16x16x32_bf16 v[2:5], v[166:169], v[212:215], v[2:5]
	v_mfma_f32_16x16x32_bf16 v[46:49], v[162:165], v[178:181], v[46:49]
	v_mfma_f32_16x16x32_bf16 v[42:45], v[170:173], v[178:181], v[42:45]
	v_mfma_f32_16x16x32_bf16 v[30:33], v[162:165], v[186:189], v[30:33]
	v_mfma_f32_16x16x32_bf16 v[26:29], v[170:173], v[186:189], v[26:29]
	v_mfma_f32_16x16x32_bf16 v[14:17], v[162:165], v[208:211], v[14:17]
	v_mfma_f32_16x16x32_bf16 v[10:13], v[170:173], v[208:211], v[10:13]
	v_mfma_f32_16x16x32_bf16 v[6:9], v[162:165], v[216:219], v[6:9]
	v_mfma_f32_16x16x32_bf16 v[2:5], v[170:173], v[216:219], v[2:5]
	s_barrier
; #define PG8_STAGE(bufoff, gbase, voff) do { _Pragma("unroll") for (int _i = 0; _i < 2; ++_i) \
;         __builtin_amdgcn_global_load_lds((const unsigned*)((const char*)(gbase) + (voff)[_i]), (PG8_LAS unsigned*)(lds + (bufoff) + ldsw + _i * 8192), 16, 0, 0); } while (0)
; #define PG8_LDA(dst, b, h) do { _Pragma("unroll") for (int m = 0; m < 4; ++m) _Pragma("unroll") for (int k = 0; k < 2; ++k) dst[m][k] = *(const PG8_LAS bf16x8*)(lds + PG8_SA(b, h) + aoff + m * 2048 + k * 1024); } while (0)
; #define PG8_LDB(dst, b, h) do { _Pragma("unroll") for (int n = 0; n < 2; ++n) _Pragma("unroll") for (int k = 0; k < 2; ++k) dst[n][k] = *(const PG8_LAS bf16x8*)(lds + PG8_SB(b, h) + boff + n * 2048 + k * 1024); } while (0)
; #define PG8_MMA(ai, bj, At, Bt) do { __builtin_amdgcn_s_setprio(1); _Pragma("unroll") for (int m = 0; m < 4; ++m) _Pragma("unroll") for (int n = 0; n < 2; ++n) _Pragma("unroll") for (int k = 0; k < 2; ++k) \
;         acc[ai][bj][m][n] = __builtin_amdgcn_mfma_f32_16x16x32_bf16(Bt[n][k], At[m][k], acc[ai][bj][m][n], 0, 0, 0); __builtin_amdgcn_s_setprio(0); } while (0)
; #define PG8_WAIT_V(n) asm volatile("s_waitcnt vmcnt(" #n ")" ::: "memory")
; #define PG8_WAIT_L(n) asm volatile("s_waitcnt lgkmcnt(" #n ")" ::: "memory")
; #define PG8_BAR __builtin_amdgcn_s_barrier()
; #define PG8_SCHED __builtin_amdgcn_sched_barrier(0)
; template <class Epi, class Sched, bool ALIGN_EPI = false, bool SP2 = false>
; __device__ __forceinline__ void gemm_phase(PG8_LAS unsigned char* lds, const Gemm g, const Sched& S, const Epi& E, int wid_in) {
;     ...
;             PG8_LDB(B0, 1, 0); PG8_LDB(B1, 1, 1); PG8_SCHED; PG8_LDA(At, 1, 0); PG8_STAGE(PG8_SA(0, 1), a2 + hstep, voffA);
;             PG8_WAIT_V(8); PG8_WAIT_L(0); PG8_BAR; PG8_MMA(0, 0, At, B0); PG8_MMA(0, 1, At, B1); PG8_BAR; PG8_SCHED;
	s_add_i32 s40, 0, 0x18000
	s_add_i32 s41, 0, 0x1c000
	v_add_u32_e32 v154, s40, v140
	v_add_u32_e32 v170, s41, v140
	ds_read_b128 v[142:145], v154
	ds_read_b128 v[146:149], v154 offset:1024
	ds_read_b128 v[150:153], v154 offset:2048
	ds_read_b128 v[154:157], v154 offset:3072
	ds_read_b128 v[158:161], v170
	ds_read_b128 v[162:165], v170 offset:1024
	ds_read_b128 v[166:169], v170 offset:2048
	ds_read_b128 v[170:173], v170 offset:3072
	s_add_u32 s30, s30, 0x80000
	s_addc_u32 s31, s31, 0
	s_mov_b32 m0, s37
	v_lshl_add_u64 v[228:229], s[30:31], 0, v[130:131]
	ds_read_b128 v[174:177], v141 offset:32768
	ds_read_b128 v[178:181], v141 offset:33792
	ds_read_b128 v[182:185], v141 offset:34816
	ds_read_b128 v[186:189], v141 offset:35840
	ds_read_b128 v[190:193], v141 offset:36864
	ds_read_b128 v[208:211], v141 offset:37888
	ds_read_b128 v[212:215], v141 offset:38912
	ds_read_b128 v[216:219], v141 offset:39936
	global_load_lds_dwordx4 v[228:229], off
	v_lshl_add_u64 v[228:229], s[30:31], 0, v[132:133]
	s_mov_b32 m0, s38
	s_nop 0
	global_load_lds_dwordx4 v[228:229], off
	s_waitcnt vmcnt(8)
	s_waitcnt lgkmcnt(0)
	s_barrier
	s_waitcnt lgkmcnt(0)
	v_mfma_f32_16x16x32_bf16 v[126:129], v[142:145], v[174:177], v[126:129]
	v_mfma_f32_16x16x32_bf16 v[122:125], v[150:153], v[174:177], v[122:125]
	v_mfma_f32_16x16x32_bf16 v[118:121], v[142:145], v[182:185], v[118:121]
	v_mfma_f32_16x16x32_bf16 v[114:117], v[150:153], v[182:185], v[114:117]
	v_mfma_f32_16x16x32_bf16 v[102:105], v[142:145], v[190:193], v[102:105]
	v_mfma_f32_16x16x32_bf16 v[98:101], v[150:153], v[190:193], v[98:101]
	v_mfma_f32_16x16x32_bf16 v[86:89], v[142:145], v[212:215], v[86:89]
	v_mfma_f32_16x16x32_bf16 v[82:85], v[150:153], v[212:215], v[82:85]
	v_mfma_f32_16x16x32_bf16 v[126:129], v[146:149], v[178:181], v[126:129]
	v_mfma_f32_16x16x32_bf16 v[122:125], v[154:157], v[178:181], v[122:125]
	v_mfma_f32_16x16x32_bf16 v[118:121], v[146:149], v[186:189], v[118:121]
	v_mfma_f32_16x16x32_bf16 v[114:117], v[154:157], v[186:189], v[114:117]
	v_mfma_f32_16x16x32_bf16 v[102:105], v[146:149], v[208:211], v[102:105]
	v_mfma_f32_16x16x32_bf16 v[98:101], v[154:157], v[208:211], v[98:101]
	v_mfma_f32_16x16x32_bf16 v[86:89], v[146:149], v[216:219], v[86:89]
	v_mfma_f32_16x16x32_bf16 v[82:85], v[154:157], v[216:219], v[82:85]
	v_mfma_f32_16x16x32_bf16 v[110:113], v[158:161], v[174:177], v[110:113]
	v_mfma_f32_16x16x32_bf16 v[106:109], v[166:169], v[174:177], v[106:109]
	v_mfma_f32_16x16x32_bf16 v[94:97], v[158:161], v[182:185], v[94:97]
	v_mfma_f32_16x16x32_bf16 v[90:93], v[166:169], v[182:185], v[90:93]
	v_mfma_f32_16x16x32_bf16 v[78:81], v[158:161], v[190:193], v[78:81]
	v_mfma_f32_16x16x32_bf16 v[74:77], v[166:169], v[190:193], v[74:77]
	v_mfma_f32_16x16x32_bf16 v[70:73], v[158:161], v[212:215], v[70:73]
	v_mfma_f32_16x16x32_bf16 v[66:69], v[166:169], v[212:215], v[66:69]
	v_mfma_f32_16x16x32_bf16 v[110:113], v[162:165], v[178:181], v[110:113]
	v_mfma_f32_16x16x32_bf16 v[106:109], v[170:173], v[178:181], v[106:109]
	v_mfma_f32_16x16x32_bf16 v[94:97], v[162:165], v[186:189], v[94:97]
	v_mfma_f32_16x16x32_bf16 v[90:93], v[170:173], v[186:189], v[90:93]
	v_mfma_f32_16x16x32_bf16 v[78:81], v[162:165], v[208:211], v[78:81]
	v_mfma_f32_16x16x32_bf16 v[74:77], v[170:173], v[208:211], v[74:77]
	v_mfma_f32_16x16x32_bf16 v[70:73], v[162:165], v[216:219], v[70:73]
	v_mfma_f32_16x16x32_bf16 v[66:69], v[170:173], v[216:219], v[66:69]
	s_barrier
; #define PG8_STAGE(bufoff, gbase, voff) do { _Pragma("unroll") for (int _i = 0; _i < 2; ++_i) \
;         __builtin_amdgcn_global_load_lds((const unsigned*)((const char*)(gbase) + (voff)[_i]), (PG8_LAS unsigned*)(lds + (bufoff) + ldsw + _i * 8192), 16, 0, 0); } while (0)
; #define PG8_LDA(dst, b, h) do { _Pragma("unroll") for (int m = 0; m < 4; ++m) _Pragma("unroll") for (int k = 0; k < 2; ++k) dst[m][k] = *(const PG8_LAS bf16x8*)(lds + PG8_SA(b, h) + aoff + m * 2048 + k * 1024); } while (0)
; #define PG8_WAIT_V(n) asm volatile("s_waitcnt vmcnt(" #n ")" ::: "memory")
; #define PG8_WAIT_L(n) asm volatile("s_waitcnt lgkmcnt(" #n ")" ::: "memory")
; #define PG8_BAR __builtin_amdgcn_s_barrier()
; template <class Epi, class Sched, bool ALIGN_EPI = false, bool SP2 = false>
; __device__ __forceinline__ void gemm_phase(PG8_LAS unsigned char* lds, const Gemm g, const Sched& S, const Epi& E, int wid_in) {
;     ...
;         for (int t = 0; t < nt; t += 2) {
;             const bool last = (t == nt - 2);
;             const char* a1 = cA + (size_t)(t + 1) * kstep;
;             const char* a2 = last ? nA : cA + (size_t)(t + 2) * kstep; const char* b2 = last ? nB : cB + (size_t)(t + 2) * kstep;
;             const char* a3 = a2 + kstep; const char* b3 = b2 + kstep;
;             if (last && has_next) S.a_ready(nxt);
;             if constexpr (SP2) {
;             PG8_LDB(B0, 0, 0); PG8_LDB(B1, 0, 1); PG8_SCHED; PG8_LDA(At, 0, 0); PG8_STAGE(PG8_SA(1, 1), a1 + hstep, voffA);
;             PG8_WAIT_V(8); PG8_WAIT_L(0); PG8_BAR; PG8_MMA(0, 0, At, B0); PG8_MMA(0, 1, At, B1); PG8_BAR; PG8_SCHED;
;             PG8_LDA(At, 0, 1); PG8_STAGE(PG8_SB(0, 0), b2, voffB); PG8_STAGE(PG8_SB(0, 1), b2 + hstep, voffB); PG8_STAGE(PG8_SA(0, 0), a2, voffA);
;             PG8_WAIT_V(8); PG8_WAIT_L(0); PG8_BAR; PG8_MMA(1, 0, At, B0); PG8_MMA(1, 1, At, B1); PG8_BAR; PG8_SCHED;
;             PG8_LDB(B0, 1, 0); PG8_LDB(B1, 1, 1); PG8_SCHED; PG8_LDA(At, 1, 0); PG8_STAGE(PG8_SA(0, 1), a2 + hstep, voffA);
;             PG8_WAIT_V(8); PG8_WAIT_L(0); PG8_BAR; PG8_MMA(0, 0, At, B0); PG8_MMA(0, 1, At, B1); PG8_BAR; PG8_SCHED;
;             PG8_LDA(At, 1, 1); PG8_STAGE(PG8_SB(1, 0), b3, voffB); PG8_STAGE(PG8_SB(1, 1), b3 + hstep, voffB); PG8_STAGE(PG8_SA(1, 0), a3, voffA);
;             PG8_WAIT_V(8); PG8_WAIT_L(0); PG8_BAR; PG8_MMA(1, 0, At, B0); PG8_MMA(1, 1, At, B1); PG8_BAR; PG8_SCHED;
	s_add_i32 s30, s40, s59
	v_lshl_add_u64 v[220:221], v[220:221], 0, s[94:95]
	s_mov_b32 m0, s30
	ds_read_b128 v[174:177], v141 offset:49152
	ds_read_b128 v[178:181], v141 offset:50176
	ds_read_b128 v[182:185], v141 offset:51200
	ds_read_b128 v[186:189], v141 offset:52224
	ds_read_b128 v[190:193], v141 offset:53248
	ds_read_b128 v[208:211], v141 offset:54272
	ds_read_b128 v[212:215], v141 offset:55296
	ds_read_b128 v[216:219], v141 offset:56320
	global_load_lds_dwordx4 v[220:221], off
	s_add_i32 m0, s30, 0x2000
	s_add_u32 s28, s28, 0x80080
	v_lshl_add_u64 v[220:221], v[222:223], 0, s[94:95]
	s_addc_u32 s29, s29, 0
	s_add_i32 s30, s41, s59
	global_load_lds_dwordx4 v[220:221], off
	v_lshl_add_u64 v[220:221], s[28:29], 0, v[0:1]
	s_mov_b32 m0, s30
	s_nop 0
	global_load_lds_dwordx4 v[220:221], off
	v_lshl_add_u64 v[220:221], s[28:29], 0, v[134:135]
	s_add_i32 m0, s30, 0x2000
	s_nop 0
	global_load_lds_dwordx4 v[220:221], off
	v_lshl_add_u64 v[220:221], v[224:225], 0, s[94:95]
	s_mov_b32 m0, s52
	s_nop 0
	global_load_lds_dwordx4 v[220:221], off
	v_lshl_add_u64 v[220:221], v[226:227], 0, s[94:95]
	s_mov_b32 m0, s53
	s_nop 0
	global_load_lds_dwordx4 v[220:221], off
	s_waitcnt vmcnt(8)
	s_waitcnt lgkmcnt(0)
	s_barrier
	s_waitcnt lgkmcnt(0)
	v_mfma_f32_16x16x32_bf16 v[62:65], v[142:145], v[174:177], v[62:65]
	v_mfma_f32_16x16x32_bf16 v[58:61], v[150:153], v[174:177], v[58:61]
	v_mfma_f32_16x16x32_bf16 v[54:57], v[142:145], v[182:185], v[54:57]
	v_mfma_f32_16x16x32_bf16 v[50:53], v[150:153], v[182:185], v[50:53]
	v_mfma_f32_16x16x32_bf16 v[38:41], v[142:145], v[190:193], v[38:41]
	v_mfma_f32_16x16x32_bf16 v[34:37], v[150:153], v[190:193], v[34:37]
	v_mfma_f32_16x16x32_bf16 v[22:25], v[142:145], v[212:215], v[22:25]
	v_mfma_f32_16x16x32_bf16 v[18:21], v[150:153], v[212:215], v[18:21]
	v_mfma_f32_16x16x32_bf16 v[62:65], v[146:149], v[178:181], v[62:65]
	v_mfma_f32_16x16x32_bf16 v[58:61], v[154:157], v[178:181], v[58:61]
	v_mfma_f32_16x16x32_bf16 v[54:57], v[146:149], v[186:189], v[54:57]
	v_mfma_f32_16x16x32_bf16 v[50:53], v[154:157], v[186:189], v[50:53]
	v_mfma_f32_16x16x32_bf16 v[38:41], v[146:149], v[208:211], v[38:41]
	v_mfma_f32_16x16x32_bf16 v[34:37], v[154:157], v[208:211], v[34:37]
	v_mfma_f32_16x16x32_bf16 v[22:25], v[146:149], v[216:219], v[22:25]
	v_mfma_f32_16x16x32_bf16 v[18:21], v[154:157], v[216:219], v[18:21]
	v_mfma_f32_16x16x32_bf16 v[46:49], v[158:161], v[174:177], v[46:49]
	v_mfma_f32_16x16x32_bf16 v[42:45], v[166:169], v[174:177], v[42:45]
	v_mfma_f32_16x16x32_bf16 v[30:33], v[158:161], v[182:185], v[30:33]
	v_mfma_f32_16x16x32_bf16 v[26:29], v[166:169], v[182:185], v[26:29]
	v_mfma_f32_16x16x32_bf16 v[14:17], v[158:161], v[190:193], v[14:17]
	v_mfma_f32_16x16x32_bf16 v[10:13], v[166:169], v[190:193], v[10:13]
	v_mfma_f32_16x16x32_bf16 v[6:9], v[158:161], v[212:215], v[6:9]
	v_mfma_f32_16x16x32_bf16 v[2:5], v[166:169], v[212:215], v[2:5]
	v_mfma_f32_16x16x32_bf16 v[46:49], v[162:165], v[178:181], v[46:49]
	v_mfma_f32_16x16x32_bf16 v[42:45], v[170:173], v[178:181], v[42:45]
	v_mfma_f32_16x16x32_bf16 v[30:33], v[162:165], v[186:189], v[30:33]
	v_mfma_f32_16x16x32_bf16 v[26:29], v[170:173], v[186:189], v[26:29]
	v_mfma_f32_16x16x32_bf16 v[14:17], v[162:165], v[208:211], v[14:17]
	v_mfma_f32_16x16x32_bf16 v[10:13], v[170:173], v[208:211], v[10:13]
	v_mfma_f32_16x16x32_bf16 v[6:9], v[162:165], v[216:219], v[6:9]
	v_mfma_f32_16x16x32_bf16 v[2:5], v[170:173], v[216:219], v[2:5]
	s_barrier
	s_add_i32 s63, s63, 2
	s_add_u32 s64, s64, 0x100
	s_addc_u32 s65, s65, 0
	s_add_u32 s26, s26, 0x100
	s_addc_u32 s27, s27, 0
	s_cmp_gt_u32 s63, 29
	s_cbranch_scc0 .LBB0_278
	s_setprio 0
	s_and_b64 vcc, exec, s[14:15]
	s_cbranch_vccz .LBB0_281
	s_barrier

; #define PG8_STAGE(bufoff, gbase, voff) do { _Pragma("unroll") for (int _i = 0; _i < 2; ++_i) \
;         __builtin_amdgcn_global_load_lds((const unsigned*)((const char*)(gbase) + (voff)[_i]), (PG8_LAS unsigned*)(lds + (bufoff) + ldsw + _i * 8192), 16, 0, 0); } while (0)
; #define PG8_LDA(dst, b, h) do { _Pragma("unroll") for (int m = 0; m < 4; ++m) _Pragma("unroll") for (int k = 0; k < 2; ++k) dst[m][k] = *(const PG8_LAS bf16x8*)(lds + PG8_SA(b, h) + aoff + m * 2048 + k * 1024); } while (0)
; #define PG8_LDB(dst, b, h) do { _Pragma("unroll") for (int n = 0; n < 2; ++n) _Pragma("unroll") for (int k = 0; k < 2; ++k) dst[n][k] = *(const PG8_LAS bf16x8*)(lds + PG8_SB(b, h) + boff + n * 2048 + k * 1024); } while (0)
; #define PG8_SCHED __builtin_amdgcn_sched_barrier(0)
; template <class Epi, class Sched, bool ALIGN_EPI = false, bool SP2 = false>
; __device__ __forceinline__ void gemm_phase(PG8_LAS unsigned char* lds, const Gemm g, const Sched& S, const Epi& E, int wid_in) {
;     ...
;     for (;;) {
;         const bool has_next = S.next(ui + 1, nxt);
;         const char* nA = has_next ? (const char*)g.A + (size_t)nxt.pm * tstep + (size_t)nxt.kt0 * kstep : cA; const char* nB = has_next ? (const char*)g.Bt + (size_t)nxt.pn * tstep + (size_t)nxt.kt0 * kstep : cB;
;         const int nt = cur.nkt;
;         for (int t = 0; t < nt; t += 2) {
;             const bool last = (t == nt - 2);
;             const char* a1 = cA + (size_t)(t + 1) * kstep;
;             const char* a2 = last ? nA : cA + (size_t)(t + 2) * kstep; const char* b2 = last ? nB : cB + (size_t)(t + 2) * kstep;
;             const char* a3 = a2 + kstep; const char* b3 = b2 + kstep;
;             if (last && has_next) S.a_ready(nxt);
;             if constexpr (SP2) {
;             PG8_LDB(B0, 0, 0); PG8_LDB(B1, 0, 1); PG8_SCHED; PG8_LDA(At, 0, 0); PG8_STAGE(PG8_SA(1, 1), a1 + hstep, voffA);
;     ...
; #pragma unroll
;         for (int a = 0; a < 2; ++a)
; #pragma unroll
;             for (int b = 0; b < 2; ++b)
; #pragma unroll
;                 for (int m = 0; m < 4; ++m)
; #pragma unroll
;                     for (int n = 0; n < 2; ++n) acc[a][b][m][n] = (f32x4){0.f, 0.f, 0.f, 0.f};
.LBB0_847:
	s_ashr_i32 s19, s18, 31
	s_lshl_b64 s[22:23], s[18:19], 19
	s_add_u32 s17, s38, s22
	s_addc_u32 s19, s39, s23
	s_ashr_i32 s15, s14, 31
	s_lshl_b64 s[24:25], s[14:15], 7
	s_add_u32 s22, s17, s24
	s_addc_u32 s23, s19, s25
	s_and_b64 s[36:37], s[20:21], exec
	s_cselect_b32 s15, s23, s35
	s_cselect_b32 s19, s22, s34
	s_ashr_i32 s17, s16, 31
	s_lshl_b64 s[36:37], s[16:17], 19
	s_add_u32 s17, s52, s36
	s_addc_u32 s27, s53, s37
	s_add_u32 s24, s17, s24
	s_addc_u32 s25, s27, s25
	s_and_b64 s[36:37], s[20:21], exec
	s_cselect_b32 s17, s25, s31
	s_cselect_b32 s27, s24, s30
	s_add_i32 vcc_lo, s1, -2
	s_add_u32 vcc_hi, s30, 0x100
	s_addc_u32 s63, s31, 0
	s_add_u32 s30, s34, 0x40080
	v_mov_b32_e32 v2, 0
	s_addc_u32 s31, s35, 0
	s_mov_b32 s34, 0
	v_mov_b32_e32 v3, v2
	v_mov_b32_e32 v4, v2
	v_mov_b32_e32 v5, v2
	v_mov_b32_e32 v6, v2
	v_mov_b32_e32 v7, v2
	v_mov_b32_e32 v8, v2
	v_mov_b32_e32 v9, v2
	v_mov_b32_e32 v10, v2
	v_mov_b32_e32 v11, v2
	v_mov_b32_e32 v12, v2
	v_mov_b32_e32 v13, v2
	v_mov_b32_e32 v14, v2
	v_mov_b32_e32 v15, v2
	v_mov_b32_e32 v16, v2
	v_mov_b32_e32 v17, v2
	v_mov_b32_e32 v26, v2
	v_mov_b32_e32 v27, v2
	v_mov_b32_e32 v28, v2
	v_mov_b32_e32 v29, v2
	v_mov_b32_e32 v30, v2
	v_mov_b32_e32 v31, v2
	v_mov_b32_e32 v32, v2
	v_mov_b32_e32 v33, v2
	v_mov_b32_e32 v42, v2
	v_mov_b32_e32 v43, v2
	v_mov_b32_e32 v44, v2
	v_mov_b32_e32 v45, v2
	v_mov_b32_e32 v46, v2
	v_mov_b32_e32 v47, v2
	v_mov_b32_e32 v48, v2
	v_mov_b32_e32 v49, v2
	v_mov_b32_e32 v18, v2
	v_mov_b32_e32 v19, v2
	v_mov_b32_e32 v20, v2
	v_mov_b32_e32 v21, v2
	v_mov_b32_e32 v22, v2
	v_mov_b32_e32 v23, v2
	v_mov_b32_e32 v24, v2
	v_mov_b32_e32 v25, v2
	v_mov_b32_e32 v34, v2
	v_mov_b32_e32 v35, v2
	v_mov_b32_e32 v36, v2
	v_mov_b32_e32 v37, v2
	v_mov_b32_e32 v38, v2
	v_mov_b32_e32 v39, v2
	v_mov_b32_e32 v40, v2
	v_mov_b32_e32 v41, v2
	v_mov_b32_e32 v50, v2
	v_mov_b32_e32 v51, v2
	v_mov_b32_e32 v52, v2
	v_mov_b32_e32 v53, v2
	v_mov_b32_e32 v54, v2
	v_mov_b32_e32 v55, v2
	v_mov_b32_e32 v56, v2
	v_mov_b32_e32 v57, v2
	v_mov_b32_e32 v58, v2
	v_mov_b32_e32 v59, v2
	v_mov_b32_e32 v60, v2
	v_mov_b32_e32 v61, v2
	v_mov_b32_e32 v62, v2
	v_mov_b32_e32 v63, v2
	v_mov_b32_e32 v64, v2
	v_mov_b32_e32 v65, v2
	v_mov_b32_e32 v66, v2
	v_mov_b32_e32 v67, v2
	v_mov_b32_e32 v68, v2
	v_mov_b32_e32 v69, v2
	v_mov_b32_e32 v70, v2
	v_mov_b32_e32 v71, v2
	v_mov_b32_e32 v72, v2
	v_mov_b32_e32 v73, v2
	v_mov_b32_e32 v74, v2
	v_mov_b32_e32 v75, v2
	v_mov_b32_e32 v76, v2
	v_mov_b32_e32 v77, v2
	v_mov_b32_e32 v78, v2
	v_mov_b32_e32 v79, v2
	v_mov_b32_e32 v80, v2
	v_mov_b32_e32 v81, v2
	v_mov_b32_e32 v90, v2
	v_mov_b32_e32 v91, v2
	v_mov_b32_e32 v92, v2
	v_mov_b32_e32 v93, v2
	v_mov_b32_e32 v94, v2
	v_mov_b32_e32 v95, v2
	v_mov_b32_e32 v96, v2
	v_mov_b32_e32 v97, v2
	v_mov_b32_e32 v106, v2
	v_mov_b32_e32 v107, v2
	v_mov_b32_e32 v108, v2
	v_mov_b32_e32 v109, v2
	v_mov_b32_e32 v110, v2
	v_mov_b32_e32 v111, v2
	v_mov_b32_e32 v112, v2
	v_mov_b32_e32 v113, v2
	v_mov_b32_e32 v82, v2
	v_mov_b32_e32 v83, v2
	v_mov_b32_e32 v84, v2
	v_mov_b32_e32 v85, v2
	v_mov_b32_e32 v86, v2
	v_mov_b32_e32 v87, v2
	v_mov_b32_e32 v88, v2
	v_mov_b32_e32 v89, v2
	v_mov_b32_e32 v98, v2
	v_mov_b32_e32 v99, v2
	v_mov_b32_e32 v100, v2
	v_mov_b32_e32 v101, v2
	v_mov_b32_e32 v102, v2
	v_mov_b32_e32 v103, v2
	v_mov_b32_e32 v104, v2
	v_mov_b32_e32 v105, v2
	v_mov_b32_e32 v114, v2
	v_mov_b32_e32 v115, v2
	v_mov_b32_e32 v116, v2
	v_mov_b32_e32 v117, v2
	v_mov_b32_e32 v118, v2
	v_mov_b32_e32 v119, v2
	v_mov_b32_e32 v120, v2
	v_mov_b32_e32 v121, v2
	v_mov_b32_e32 v122, v2
	v_mov_b32_e32 v123, v2
	v_mov_b32_e32 v124, v2
	v_mov_b32_e32 v125, v2
	v_mov_b32_e32 v126, v2
	v_mov_b32_e32 v127, v2
	v_mov_b32_e32 v128, v2
	v_mov_b32_e32 v129, v2
	s_cmp_ge_u32 s47, 4
	s_cbranch_scc0 .Lprio_skip_1
	s_setprio 1
.Lprio_skip_1:
.LBB0_848:
	s_add_i32 s56, s34, 2
	s_add_u32 s35, s30, 0xfffc0080
	s_addc_u32 s36, s31, -1
	s_add_i32 s40, 0, 0x10000
	s_cmp_eq_u32 vcc_lo, s34
	s_cselect_b32 s37, s15, s36
	s_cselect_b32 s36, s19, s35
	s_cselect_b32 s35, s17, s63
	s_cselect_b32 s34, s27, vcc_hi
	s_add_i32 s42, 0, 0x14000
	v_add_u32_e32 v142, s40, v188
	v_add_u32_e32 v158, s42, v188
	ds_read_b128 v[130:133], v142
	ds_read_b128 v[134:137], v142 offset:1024
	ds_read_b128 v[138:141], v142 offset:2048
	ds_read_b128 v[142:145], v142 offset:3072
	ds_read_b128 v[146:149], v158
	ds_read_b128 v[150:153], v158 offset:1024
	ds_read_b128 v[154:157], v158 offset:2048
	ds_read_b128 v[158:161], v158 offset:3072
	v_lshl_add_u64 v[220:221], s[30:31], 0, v[170:171]
	s_add_i32 m0, s29, 0xc000
	ds_read_b128 v[172:175], v189
	ds_read_b128 v[176:179], v189 offset:1024
	ds_read_b128 v[180:183], v189 offset:2048
	ds_read_b128 v[184:187], v189 offset:3072
	ds_read_b128 v[190:193], v189 offset:4096
	ds_read_b128 v[208:211], v189 offset:5120
	ds_read_b128 v[212:215], v189 offset:6144
	ds_read_b128 v[216:219], v189 offset:7168
	global_load_lds_dwordx4 v[220:221], off
	v_lshl_add_u64 v[220:221], s[30:31], 0, v[168:169]
	s_add_i32 m0, s29, 0xe000
	s_nop 0
	global_load_lds_dwordx4 v[220:221], off
	s_waitcnt vmcnt(8)
	s_waitcnt lgkmcnt(0)
	s_barrier
; #define PG8_STAGE(bufoff, gbase, voff) do { _Pragma("unroll") for (int _i = 0; _i < 2; ++_i) \
;         __builtin_amdgcn_global_load_lds((const unsigned*)((const char*)(gbase) + (voff)[_i]), (PG8_LAS unsigned*)(lds + (bufoff) + ldsw + _i * 8192), 16, 0, 0); } while (0)
; #define PG8_LDA(dst, b, h) do { _Pragma("unroll") for (int m = 0; m < 4; ++m) _Pragma("unroll") for (int k = 0; k < 2; ++k) dst[m][k] = *(const PG8_LAS bf16x8*)(lds + PG8_SA(b, h) + aoff + m * 2048 + k * 1024); } while (0)
; #define PG8_MMA(ai, bj, At, Bt) do { __builtin_amdgcn_s_setprio(1); _Pragma("unroll") for (int m = 0; m < 4; ++m) _Pragma("unroll") for (int n = 0; n < 2; ++n) _Pragma("unroll") for (int k = 0; k < 2; ++k) \
;         acc[ai][bj][m][n] = __builtin_amdgcn_mfma_f32_16x16x32_bf16(Bt[n][k], At[m][k], acc[ai][bj][m][n], 0, 0, 0); __builtin_amdgcn_s_setprio(0); } while (0)
; #define PG8_WAIT_V(n) asm volatile("s_waitcnt vmcnt(" #n ")" ::: "memory")
; #define PG8_WAIT_L(n) asm volatile("s_waitcnt lgkmcnt(" #n ")" ::: "memory")
; #define PG8_BAR __builtin_amdgcn_s_barrier()
; #define PG8_SCHED __builtin_amdgcn_sched_barrier(0)
; template <class Epi, class Sched, bool ALIGN_EPI = false, bool SP2 = false>
; __device__ __forceinline__ void gemm_phase(PG8_LAS unsigned char* lds, const Gemm g, const Sched& S, const Epi& E, int wid_in) {
;     ...
;             PG8_WAIT_V(8); PG8_WAIT_L(0); PG8_BAR; PG8_MMA(0, 0, At, B0); PG8_MMA(0, 1, At, B1); PG8_BAR; PG8_SCHED;
;             PG8_LDA(At, 0, 1); PG8_STAGE(PG8_SB(0, 0), b2, voffB); PG8_STAGE(PG8_SB(0, 1), b2 + hstep, voffB); PG8_STAGE(PG8_SA(0, 0), a2, voffA);
;             PG8_WAIT_V(8); PG8_WAIT_L(0); PG8_BAR; PG8_MMA(1, 0, At, B0); PG8_MMA(1, 1, At, B1); PG8_BAR; PG8_SCHED;
	s_waitcnt lgkmcnt(0)
	v_mfma_f32_16x16x32_bf16 v[126:129], v[130:133], v[172:175], v[126:129]
	v_mfma_f32_16x16x32_bf16 v[122:125], v[138:141], v[172:175], v[122:125]
	v_mfma_f32_16x16x32_bf16 v[118:121], v[130:133], v[180:183], v[118:121]
	v_mfma_f32_16x16x32_bf16 v[114:117], v[138:141], v[180:183], v[114:117]
	v_mfma_f32_16x16x32_bf16 v[102:105], v[130:133], v[190:193], v[102:105]
	v_mfma_f32_16x16x32_bf16 v[98:101], v[138:141], v[190:193], v[98:101]
	v_mfma_f32_16x16x32_bf16 v[86:89], v[130:133], v[212:215], v[86:89]
	v_mfma_f32_16x16x32_bf16 v[82:85], v[138:141], v[212:215], v[82:85]
	v_mfma_f32_16x16x32_bf16 v[126:129], v[134:137], v[176:179], v[126:129]
	v_mfma_f32_16x16x32_bf16 v[122:125], v[142:145], v[176:179], v[122:125]
	v_mfma_f32_16x16x32_bf16 v[118:121], v[134:137], v[184:187], v[118:121]
	v_mfma_f32_16x16x32_bf16 v[114:117], v[142:145], v[184:187], v[114:117]
	v_mfma_f32_16x16x32_bf16 v[102:105], v[134:137], v[208:211], v[102:105]
	v_mfma_f32_16x16x32_bf16 v[98:101], v[142:145], v[208:211], v[98:101]
	v_mfma_f32_16x16x32_bf16 v[86:89], v[134:137], v[216:219], v[86:89]
	v_mfma_f32_16x16x32_bf16 v[82:85], v[142:145], v[216:219], v[82:85]
	v_mfma_f32_16x16x32_bf16 v[110:113], v[146:149], v[172:175], v[110:113]
	v_mfma_f32_16x16x32_bf16 v[106:109], v[154:157], v[172:175], v[106:109]
	v_mfma_f32_16x16x32_bf16 v[94:97], v[146:149], v[180:183], v[94:97]
	v_mfma_f32_16x16x32_bf16 v[90:93], v[154:157], v[180:183], v[90:93]
	v_mfma_f32_16x16x32_bf16 v[78:81], v[146:149], v[190:193], v[78:81]
	v_mfma_f32_16x16x32_bf16 v[74:77], v[154:157], v[190:193], v[74:77]
	v_mfma_f32_16x16x32_bf16 v[70:73], v[146:149], v[212:215], v[70:73]
	v_mfma_f32_16x16x32_bf16 v[66:69], v[154:157], v[212:215], v[66:69]
	v_mfma_f32_16x16x32_bf16 v[110:113], v[150:153], v[176:179], v[110:113]
	v_mfma_f32_16x16x32_bf16 v[106:109], v[158:161], v[176:179], v[106:109]
	v_mfma_f32_16x16x32_bf16 v[94:97], v[150:153], v[184:187], v[94:97]
	v_mfma_f32_16x16x32_bf16 v[90:93], v[158:161], v[184:187], v[90:93]
	v_mfma_f32_16x16x32_bf16 v[78:81], v[150:153], v[208:211], v[78:81]
	v_mfma_f32_16x16x32_bf16 v[74:77], v[158:161], v[208:211], v[74:77]
	v_mfma_f32_16x16x32_bf16 v[70:73], v[150:153], v[216:219], v[70:73]
	v_mfma_f32_16x16x32_bf16 v[66:69], v[158:161], v[216:219], v[66:69]
	s_barrier
	s_add_i32 s40, s40, s59
	v_lshl_add_u64 v[220:221], s[34:35], 0, v[0:1]
	s_mov_b32 m0, s40
	ds_read_b128 v[172:175], v189 offset:16384
	ds_read_b128 v[176:179], v189 offset:17408
	ds_read_b128 v[180:183], v189 offset:18432
	ds_read_b128 v[184:187], v189 offset:19456
	ds_read_b128 v[190:193], v189 offset:20480
	ds_read_b128 v[208:211], v189 offset:21504
	ds_read_b128 v[212:215], v189 offset:22528
	ds_read_b128 v[216:219], v189 offset:23552
	global_load_lds_dwordx4 v[220:221], off
	s_add_i32 m0, s40, 0x2000
	s_add_u32 s40, s34, 0x40000
	v_lshl_add_u64 v[222:223], s[34:35], 0, v[166:167]
	s_addc_u32 s41, s35, 0
	s_add_i32 s42, s42, s59
	global_load_lds_dwordx4 v[222:223], off
	v_lshl_add_u64 v[224:225], s[40:41], 0, v[0:1]
	s_mov_b32 m0, s42
	v_lshl_add_u64 v[226:227], s[36:37], 0, v[164:165]
	global_load_lds_dwordx4 v[224:225], off
	v_lshl_add_u64 v[224:225], s[40:41], 0, v[166:167]
	s_add_i32 m0, s42, 0x2000
	s_nop 0
	global_load_lds_dwordx4 v[224:225], off
	v_lshl_add_u64 v[224:225], s[36:37], 0, v[162:163]
	s_mov_b32 m0, s29
	s_nop 0
	global_load_lds_dwordx4 v[224:225], off
	s_mov_b32 m0, s64
	s_nop 0
	global_load_lds_dwordx4 v[226:227], off
	s_waitcnt vmcnt(8)
	s_waitcnt lgkmcnt(0)
	s_barrier
	s_waitcnt lgkmcnt(0)
	v_mfma_f32_16x16x32_bf16 v[62:65], v[130:133], v[172:175], v[62:65]
	v_mfma_f32_16x16x32_bf16 v[58:61], v[138:141], v[172:175], v[58:61]
	v_mfma_f32_16x16x32_bf16 v[54:57], v[130:133], v[180:183], v[54:57]
	v_mfma_f32_16x16x32_bf16 v[50:53], v[138:141], v[180:183], v[50:53]
	v_mfma_f32_16x16x32_bf16 v[38:41], v[130:133], v[190:193], v[38:41]
	v_mfma_f32_16x16x32_bf16 v[34:37], v[138:141], v[190:193], v[34:37]
	v_mfma_f32_16x16x32_bf16 v[22:25], v[130:133], v[212:215], v[22:25]
	v_mfma_f32_16x16x32_bf16 v[18:21], v[138:141], v[212:215], v[18:21]
	v_mfma_f32_16x16x32_bf16 v[62:65], v[134:137], v[176:179], v[62:65]
	v_mfma_f32_16x16x32_bf16 v[58:61], v[142:145], v[176:179], v[58:61]
	v_mfma_f32_16x16x32_bf16 v[54:57], v[134:137], v[184:187], v[54:57]
	v_mfma_f32_16x16x32_bf16 v[50:53], v[142:145], v[184:187], v[50:53]
	v_mfma_f32_16x16x32_bf16 v[38:41], v[134:137], v[208:211], v[38:41]
	v_mfma_f32_16x16x32_bf16 v[34:37], v[142:145], v[208:211], v[34:37]
	v_mfma_f32_16x16x32_bf16 v[22:25], v[134:137], v[216:219], v[22:25]
	v_mfma_f32_16x16x32_bf16 v[18:21], v[142:145], v[216:219], v[18:21]
	v_mfma_f32_16x16x32_bf16 v[46:49], v[146:149], v[172:175], v[46:49]
	v_mfma_f32_16x16x32_bf16 v[42:45], v[154:157], v[172:175], v[42:45]
	v_mfma_f32_16x16x32_bf16 v[30:33], v[146:149], v[180:183], v[30:33]
	v_mfma_f32_16x16x32_bf16 v[26:29], v[154:157], v[180:183], v[26:29]
	v_mfma_f32_16x16x32_bf16 v[14:17], v[146:149], v[190:193], v[14:17]
	v_mfma_f32_16x16x32_bf16 v[10:13], v[154:157], v[190:193], v[10:13]
	v_mfma_f32_16x16x32_bf16 v[6:9], v[146:149], v[212:215], v[6:9]
	v_mfma_f32_16x16x32_bf16 v[2:5], v[154:157], v[212:215], v[2:5]
	v_mfma_f32_16x16x32_bf16 v[46:49], v[150:153], v[176:179], v[46:49]
	v_mfma_f32_16x16x32_bf16 v[42:45], v[158:161], v[176:179], v[42:45]
	v_mfma_f32_16x16x32_bf16 v[30:33], v[150:153], v[184:187], v[30:33]
	v_mfma_f32_16x16x32_bf16 v[26:29], v[158:161], v[184:187], v[26:29]
	v_mfma_f32_16x16x32_bf16 v[14:17], v[150:153], v[208:211], v[14:17]
	v_mfma_f32_16x16x32_bf16 v[10:13], v[158:161], v[208:211], v[10:13]
	v_mfma_f32_16x16x32_bf16 v[6:9], v[150:153], v[216:219], v[6:9]
	v_mfma_f32_16x16x32_bf16 v[2:5], v[158:161], v[216:219], v[2:5]
	s_barrier
; #define PG8_STAGE(bufoff, gbase, voff) do { _Pragma("unroll") for (int _i = 0; _i < 2; ++_i) \
;         __builtin_amdgcn_global_load_lds((const unsigned*)((const char*)(gbase) + (voff)[_i]), (PG8_LAS unsigned*)(lds + (bufoff) + ldsw + _i * 8192), 16, 0, 0); } while (0)
; #define PG8_LDA(dst, b, h) do { _Pragma("unroll") for (int m = 0; m < 4; ++m) _Pragma("unroll") for (int k = 0; k < 2; ++k) dst[m][k] = *(const PG8_LAS bf16x8*)(lds + PG8_SA(b, h) + aoff + m * 2048 + k * 1024); } while (0)
; #define PG8_LDB(dst, b, h) do { _Pragma("unroll") for (int n = 0; n < 2; ++n) _Pragma("unroll") for (int k = 0; k < 2; ++k) dst[n][k] = *(const PG8_LAS bf16x8*)(lds + PG8_SB(b, h) + boff + n * 2048 + k * 1024); } while (0)
; #define PG8_MMA(ai, bj, At, Bt) do { __builtin_amdgcn_s_setprio(1); _Pragma("unroll") for (int m = 0; m < 4; ++m) _Pragma("unroll") for (int n = 0; n < 2; ++n) _Pragma("unroll") for (int k = 0; k < 2; ++k) \
;         acc[ai][bj][m][n] = __builtin_amdgcn_mfma_f32_16x16x32_bf16(Bt[n][k], At[m][k], acc[ai][bj][m][n], 0, 0, 0); __builtin_amdgcn_s_setprio(0); } while (0)
; #define PG8_WAIT_V(n) asm volatile("s_waitcnt vmcnt(" #n ")" ::: "memory")
; #define PG8_WAIT_L(n) asm volatile("s_waitcnt lgkmcnt(" #n ")" ::: "memory")
; #define PG8_BAR __builtin_amdgcn_s_barrier()
; #define PG8_SCHED __builtin_amdgcn_sched_barrier(0)
; template <class Epi, class Sched, bool ALIGN_EPI = false, bool SP2 = false>
; __device__ __forceinline__ void gemm_phase(PG8_LAS unsigned char* lds, const Gemm g, const Sched& S, const Epi& E, int wid_in) {
;     ...
;             PG8_LDB(B0, 1, 0); PG8_LDB(B1, 1, 1); PG8_SCHED; PG8_LDA(At, 1, 0); PG8_STAGE(PG8_SA(0, 1), a2 + hstep, voffA);
;             PG8_WAIT_V(8); PG8_WAIT_L(0); PG8_BAR; PG8_MMA(0, 0, At, B0); PG8_MMA(0, 1, At, B1); PG8_BAR; PG8_SCHED;
	s_add_i32 s40, 0, 0x18000
	s_add_i32 s41, 0, 0x1c000
	v_add_u32_e32 v142, s40, v188
	v_add_u32_e32 v158, s41, v188
	ds_read_b128 v[130:133], v142
	ds_read_b128 v[134:137], v142 offset:1024
	ds_read_b128 v[138:141], v142 offset:2048
	ds_read_b128 v[142:145], v142 offset:3072
	ds_read_b128 v[146:149], v158
	ds_read_b128 v[150:153], v158 offset:1024
	ds_read_b128 v[154:157], v158 offset:2048
	ds_read_b128 v[158:161], v158 offset:3072
	s_add_u32 s36, s36, 0x40000
	s_addc_u32 s37, s37, 0
	s_mov_b32 m0, s65
	v_lshl_add_u64 v[228:229], s[36:37], 0, v[162:163]
	ds_read_b128 v[172:175], v189 offset:32768
	ds_read_b128 v[176:179], v189 offset:33792
	ds_read_b128 v[180:183], v189 offset:34816
	ds_read_b128 v[184:187], v189 offset:35840
	ds_read_b128 v[190:193], v189 offset:36864
	ds_read_b128 v[208:211], v189 offset:37888
	ds_read_b128 v[212:215], v189 offset:38912
	ds_read_b128 v[216:219], v189 offset:39936
	global_load_lds_dwordx4 v[228:229], off
	v_lshl_add_u64 v[228:229], s[36:37], 0, v[164:165]
	s_mov_b32 m0, s62
	s_nop 0
	global_load_lds_dwordx4 v[228:229], off
	s_waitcnt vmcnt(8)
	s_waitcnt lgkmcnt(0)
	s_barrier
	s_waitcnt lgkmcnt(0)
	v_mfma_f32_16x16x32_bf16 v[126:129], v[130:133], v[172:175], v[126:129]
	v_mfma_f32_16x16x32_bf16 v[122:125], v[138:141], v[172:175], v[122:125]
	v_mfma_f32_16x16x32_bf16 v[118:121], v[130:133], v[180:183], v[118:121]
	v_mfma_f32_16x16x32_bf16 v[114:117], v[138:141], v[180:183], v[114:117]
	v_mfma_f32_16x16x32_bf16 v[102:105], v[130:133], v[190:193], v[102:105]
	v_mfma_f32_16x16x32_bf16 v[98:101], v[138:141], v[190:193], v[98:101]
	v_mfma_f32_16x16x32_bf16 v[86:89], v[130:133], v[212:215], v[86:89]
	v_mfma_f32_16x16x32_bf16 v[82:85], v[138:141], v[212:215], v[82:85]
	v_mfma_f32_16x16x32_bf16 v[126:129], v[134:137], v[176:179], v[126:129]
	v_mfma_f32_16x16x32_bf16 v[122:125], v[142:145], v[176:179], v[122:125]
	v_mfma_f32_16x16x32_bf16 v[118:121], v[134:137], v[184:187], v[118:121]
	v_mfma_f32_16x16x32_bf16 v[114:117], v[142:145], v[184:187], v[114:117]
	v_mfma_f32_16x16x32_bf16 v[102:105], v[134:137], v[208:211], v[102:105]
	v_mfma_f32_16x16x32_bf16 v[98:101], v[142:145], v[208:211], v[98:101]
	v_mfma_f32_16x16x32_bf16 v[86:89], v[134:137], v[216:219], v[86:89]
	v_mfma_f32_16x16x32_bf16 v[82:85], v[142:145], v[216:219], v[82:85]
	v_mfma_f32_16x16x32_bf16 v[110:113], v[146:149], v[172:175], v[110:113]
	v_mfma_f32_16x16x32_bf16 v[106:109], v[154:157], v[172:175], v[106:109]
	v_mfma_f32_16x16x32_bf16 v[94:97], v[146:149], v[180:183], v[94:97]
	v_mfma_f32_16x16x32_bf16 v[90:93], v[154:157], v[180:183], v[90:93]
	v_mfma_f32_16x16x32_bf16 v[78:81], v[146:149], v[190:193], v[78:81]
	v_mfma_f32_16x16x32_bf16 v[74:77], v[154:157], v[190:193], v[74:77]
	v_mfma_f32_16x16x32_bf16 v[70:73], v[146:149], v[212:215], v[70:73]
	v_mfma_f32_16x16x32_bf16 v[66:69], v[154:157], v[212:215], v[66:69]
	v_mfma_f32_16x16x32_bf16 v[110:113], v[150:153], v[176:179], v[110:113]
	v_mfma_f32_16x16x32_bf16 v[106:109], v[158:161], v[176:179], v[106:109]
	v_mfma_f32_16x16x32_bf16 v[94:97], v[150:153], v[184:187], v[94:97]
	v_mfma_f32_16x16x32_bf16 v[90:93], v[158:161], v[184:187], v[90:93]
	v_mfma_f32_16x16x32_bf16 v[78:81], v[150:153], v[208:211], v[78:81]
	v_mfma_f32_16x16x32_bf16 v[74:77], v[158:161], v[208:211], v[74:77]
	v_mfma_f32_16x16x32_bf16 v[70:73], v[150:153], v[216:219], v[70:73]
	v_mfma_f32_16x16x32_bf16 v[66:69], v[158:161], v[216:219], v[66:69]
	s_barrier
; #define PG8_STAGE(bufoff, gbase, voff) do { _Pragma("unroll") for (int _i = 0; _i < 2; ++_i) \
;         __builtin_amdgcn_global_load_lds((const unsigned*)((const char*)(gbase) + (voff)[_i]), (PG8_LAS unsigned*)(lds + (bufoff) + ldsw + _i * 8192), 16, 0, 0); } while (0)
; #define PG8_LDA(dst, b, h) do { _Pragma("unroll") for (int m = 0; m < 4; ++m) _Pragma("unroll") for (int k = 0; k < 2; ++k) dst[m][k] = *(const PG8_LAS bf16x8*)(lds + PG8_SA(b, h) + aoff + m * 2048 + k * 1024); } while (0)
; #define PG8_MMA(ai, bj, At, Bt) do { __builtin_amdgcn_s_setprio(1); _Pragma("unroll") for (int m = 0; m < 4; ++m) _Pragma("unroll") for (int n = 0; n < 2; ++n) _Pragma("unroll") for (int k = 0; k < 2; ++k) \
;         acc[ai][bj][m][n] = __builtin_amdgcn_mfma_f32_16x16x32_bf16(Bt[n][k], At[m][k], acc[ai][bj][m][n], 0, 0, 0); __builtin_amdgcn_s_setprio(0); } while (0)
; #define PG8_WAIT_V(n) asm volatile("s_waitcnt vmcnt(" #n ")" ::: "memory")
; #define PG8_WAIT_L(n) asm volatile("s_waitcnt lgkmcnt(" #n ")" ::: "memory")
; #define PG8_BAR __builtin_amdgcn_s_barrier()
; #define PG8_SCHED __builtin_amdgcn_sched_barrier(0)
; template <class Epi, class Sched, bool ALIGN_EPI = false, bool SP2 = false>
; __device__ __forceinline__ void gemm_phase(PG8_LAS unsigned char* lds, const Gemm g, const Sched& S, const Epi& E, int wid_in) {
;     ...
;         for (int t = 0; t < nt; t += 2) {
;             const bool last = (t == nt - 2);
;             const char* a1 = cA + (size_t)(t + 1) * kstep;
;             const char* a2 = last ? nA : cA + (size_t)(t + 2) * kstep; const char* b2 = last ? nB : cB + (size_t)(t + 2) * kstep;
;             const char* a3 = a2 + kstep; const char* b3 = b2 + kstep;
;             if (last && has_next) S.a_ready(nxt);
;     ...
;             PG8_LDA(At, 1, 1); PG8_STAGE(PG8_SB(1, 0), b3, voffB); PG8_STAGE(PG8_SB(1, 1), b3 + hstep, voffB); PG8_STAGE(PG8_SA(1, 0), a3, voffA);
;             PG8_WAIT_V(8); PG8_WAIT_L(0); PG8_BAR; PG8_MMA(1, 0, At, B0); PG8_MMA(1, 1, At, B1); PG8_BAR; PG8_SCHED;
	s_add_i32 s36, s40, s59
	v_lshl_add_u64 v[220:221], v[220:221], 0, s[94:95]
	s_mov_b32 m0, s36
	ds_read_b128 v[172:175], v189 offset:49152
	ds_read_b128 v[176:179], v189 offset:50176
	ds_read_b128 v[180:183], v189 offset:51200
	ds_read_b128 v[184:187], v189 offset:52224
	ds_read_b128 v[190:193], v189 offset:53248
	ds_read_b128 v[208:211], v189 offset:54272
	ds_read_b128 v[212:215], v189 offset:55296
	ds_read_b128 v[216:219], v189 offset:56320
	global_load_lds_dwordx4 v[220:221], off
	s_add_i32 m0, s36, 0x2000
	s_add_u32 s34, s34, 0x40080
	v_lshl_add_u64 v[220:221], v[222:223], 0, s[94:95]
	s_addc_u32 s35, s35, 0
	s_add_i32 s36, s41, s59
	global_load_lds_dwordx4 v[220:221], off
	v_lshl_add_u64 v[220:221], s[34:35], 0, v[0:1]
	s_mov_b32 m0, s36
	s_nop 0
	global_load_lds_dwordx4 v[220:221], off
	v_lshl_add_u64 v[220:221], s[34:35], 0, v[166:167]
	s_add_i32 m0, s36, 0x2000
	s_nop 0
	global_load_lds_dwordx4 v[220:221], off
	v_lshl_add_u64 v[220:221], v[224:225], 0, s[94:95]
	s_mov_b32 m0, s88
	s_nop 0
	global_load_lds_dwordx4 v[220:221], off
	v_lshl_add_u64 v[220:221], v[226:227], 0, s[94:95]
	s_mov_b32 m0, s89
	s_nop 0
	global_load_lds_dwordx4 v[220:221], off
	s_waitcnt vmcnt(8)
	s_waitcnt lgkmcnt(0)
	s_barrier
	s_waitcnt lgkmcnt(0)
	v_mfma_f32_16x16x32_bf16 v[62:65], v[130:133], v[172:175], v[62:65]
	v_mfma_f32_16x16x32_bf16 v[58:61], v[138:141], v[172:175], v[58:61]
	v_mfma_f32_16x16x32_bf16 v[54:57], v[130:133], v[180:183], v[54:57]
	v_mfma_f32_16x16x32_bf16 v[50:53], v[138:141], v[180:183], v[50:53]
	v_mfma_f32_16x16x32_bf16 v[38:41], v[130:133], v[190:193], v[38:41]
	v_mfma_f32_16x16x32_bf16 v[34:37], v[138:141], v[190:193], v[34:37]
	v_mfma_f32_16x16x32_bf16 v[22:25], v[130:133], v[212:215], v[22:25]
	v_mfma_f32_16x16x32_bf16 v[18:21], v[138:141], v[212:215], v[18:21]
	v_mfma_f32_16x16x32_bf16 v[62:65], v[134:137], v[176:179], v[62:65]
	v_mfma_f32_16x16x32_bf16 v[58:61], v[142:145], v[176:179], v[58:61]
	v_mfma_f32_16x16x32_bf16 v[54:57], v[134:137], v[184:187], v[54:57]
	v_mfma_f32_16x16x32_bf16 v[50:53], v[142:145], v[184:187], v[50:53]
	v_mfma_f32_16x16x32_bf16 v[38:41], v[134:137], v[208:211], v[38:41]
	v_mfma_f32_16x16x32_bf16 v[34:37], v[142:145], v[208:211], v[34:37]
	v_mfma_f32_16x16x32_bf16 v[22:25], v[134:137], v[216:219], v[22:25]
	v_mfma_f32_16x16x32_bf16 v[18:21], v[142:145], v[216:219], v[18:21]
	v_mfma_f32_16x16x32_bf16 v[46:49], v[146:149], v[172:175], v[46:49]
	v_mfma_f32_16x16x32_bf16 v[42:45], v[154:157], v[172:175], v[42:45]
	v_mfma_f32_16x16x32_bf16 v[30:33], v[146:149], v[180:183], v[30:33]
	v_mfma_f32_16x16x32_bf16 v[26:29], v[154:157], v[180:183], v[26:29]
	v_mfma_f32_16x16x32_bf16 v[14:17], v[146:149], v[190:193], v[14:17]
	v_mfma_f32_16x16x32_bf16 v[10:13], v[154:157], v[190:193], v[10:13]
	v_mfma_f32_16x16x32_bf16 v[6:9], v[146:149], v[212:215], v[6:9]
	v_mfma_f32_16x16x32_bf16 v[2:5], v[154:157], v[212:215], v[2:5]
	v_mfma_f32_16x16x32_bf16 v[46:49], v[150:153], v[176:179], v[46:49]
	v_mfma_f32_16x16x32_bf16 v[42:45], v[158:161], v[176:179], v[42:45]
	v_mfma_f32_16x16x32_bf16 v[30:33], v[150:153], v[184:187], v[30:33]
	v_mfma_f32_16x16x32_bf16 v[26:29], v[158:161], v[184:187], v[26:29]
	v_mfma_f32_16x16x32_bf16 v[14:17], v[150:153], v[208:211], v[14:17]
	v_mfma_f32_16x16x32_bf16 v[10:13], v[158:161], v[208:211], v[10:13]
	v_mfma_f32_16x16x32_bf16 v[6:9], v[150:153], v[216:219], v[6:9]
	v_mfma_f32_16x16x32_bf16 v[2:5], v[158:161], v[216:219], v[2:5]
	s_barrier
	s_add_u32 vcc_hi, vcc_hi, 0x100
	s_addc_u32 s63, s63, 0
	s_add_u32 s30, s30, 0x100
	s_addc_u32 s31, s31, 0
	s_cmp_ge_i32 s56, s1
	s_mov_b32 s34, s56
	s_cbranch_scc0 .LBB0_848
	s_setprio 0
	s_and_b64 vcc, exec, s[12:13]
	s_cbranch_vccz .LBB0_851
	s_barrier

; #define PG8_STAGE(bufoff, gbase, voff) do { _Pragma("unroll") for (int _i = 0; _i < 2; ++_i) \
;         __builtin_amdgcn_global_load_lds((const unsigned*)((const char*)(gbase) + (voff)[_i]), (PG8_LAS unsigned*)(lds + (bufoff) + ldsw + _i * 8192), 16, 0, 0); } while (0)
; #define PG8_LDA(dst, b, h) do { _Pragma("unroll") for (int m = 0; m < 4; ++m) _Pragma("unroll") for (int k = 0; k < 2; ++k) dst[m][k] = *(const PG8_LAS bf16x8*)(lds + PG8_SA(b, h) + aoff + m * 2048 + k * 1024); } while (0)
; #define PG8_LDB(dst, b, h) do { _Pragma("unroll") for (int n = 0; n < 2; ++n) _Pragma("unroll") for (int k = 0; k < 2; ++k) dst[n][k] = *(const PG8_LAS bf16x8*)(lds + PG8_SB(b, h) + boff + n * 2048 + k * 1024); } while (0)
; #define PG8_MMA(ai, bj, At, Bt) do { __builtin_amdgcn_s_setprio(1); _Pragma("unroll") for (int m = 0; m < 4; ++m) _Pragma("unroll") for (int n = 0; n < 2; ++n) _Pragma("unroll") for (int k = 0; k < 2; ++k) \
;         acc[ai][bj][m][n] = __builtin_amdgcn_mfma_f32_16x16x32_bf16(Bt[n][k], At[m][k], acc[ai][bj][m][n], 0, 0, 0); __builtin_amdgcn_s_setprio(0); } while (0)
; #define PG8_WAIT_V(n) asm volatile("s_waitcnt vmcnt(" #n ")" ::: "memory")
; #define PG8_BAR __builtin_amdgcn_s_barrier()
; template <class Epi, class Sched, bool ALIGN_EPI = false, bool SP2 = false>
; __device__ __forceinline__ void gemm_phase(PG8_LAS unsigned char* lds, const Gemm g, const Sched& S, const Epi& E, int wid_in) {
;     ...
;         for (int t = 0; t < nt; t += 2) {
;             const bool last = (t == nt - 2);
;             const char* a1 = cA + (size_t)(t + 1) * kstep;
;             const char* a2 = last ? nA : cA + (size_t)(t + 2) * kstep; const char* b2 = last ? nB : cB + (size_t)(t + 2) * kstep;
;             const char* a3 = a2 + kstep; const char* b3 = b2 + kstep;
;             if (last && has_next) S.a_ready(nxt);
;             if constexpr (SP2) {
;             PG8_LDB(B0, 0, 0); PG8_LDB(B1, 0, 1); PG8_SCHED; PG8_LDA(At, 0, 0); PG8_STAGE(PG8_SA(1, 1), a1 + hstep, voffA);
;             PG8_WAIT_V(8); PG8_WAIT_L(0); PG8_BAR; PG8_MMA(0, 0, At, B0); PG8_MMA(0, 1, At, B1); PG8_BAR; PG8_SCHED;
;             PG8_LDA(At, 0, 1); PG8_STAGE(PG8_SB(0, 0), b2, voffB); PG8_STAGE(PG8_SB(0, 1), b2 + hstep, voffB); PG8_STAGE(PG8_SA(0, 0), a2, voffA);
;             PG8_WAIT_V(8); PG8_WAIT_L(0); PG8_BAR; PG8_MMA(1, 0, At, B0); PG8_MMA(1, 1, At, B1); PG8_BAR; PG8_SCHED;
.Lprio_skip_2:
.LBB0_880:
	s_add_i32 s56, s34, 2
	s_add_u32 s35, s30, 0xfffc0080
	s_addc_u32 s36, s31, -1
	s_add_i32 s40, 0, 0x10000
	s_cmp_eq_u32 vcc_lo, s34
	s_cselect_b32 s37, s15, s36
	s_cselect_b32 s36, s19, s35
	s_cselect_b32 s35, s17, s63
	s_cselect_b32 s34, s27, vcc_hi
	s_add_i32 s42, 0, 0x14000
	v_add_u32_e32 v142, s40, v195
	v_add_u32_e32 v158, s42, v195
	ds_read_b128 v[130:133], v142
	ds_read_b128 v[134:137], v142 offset:1024
	ds_read_b128 v[138:141], v142 offset:2048
	ds_read_b128 v[142:145], v142 offset:3072
	ds_read_b128 v[146:149], v158
	ds_read_b128 v[150:153], v158 offset:1024
	ds_read_b128 v[154:157], v158 offset:2048
	ds_read_b128 v[158:161], v158 offset:3072
	v_lshl_add_u64 v[218:219], s[30:31], 0, v[216:217]
	s_add_i32 m0, s29, 0xc000
	ds_read_b128 v[162:165], v251
	ds_read_b128 v[166:169], v251 offset:1024
	ds_read_b128 v[170:173], v251 offset:2048
	ds_read_b128 v[174:177], v251 offset:3072
	ds_read_b128 v[178:181], v251 offset:4096
	ds_read_b128 v[182:185], v251 offset:5120
	ds_read_b128 v[186:189], v251 offset:6144
	ds_read_b128 v[190:193], v251 offset:7168
	global_load_lds_dwordx4 v[218:219], off
	v_lshl_add_u64 v[218:219], s[30:31], 0, v[214:215]
	s_add_i32 m0, s29, 0xe000
	s_nop 0
	global_load_lds_dwordx4 v[218:219], off
	s_waitcnt vmcnt(8)
	s_waitcnt lgkmcnt(0)
	s_barrier
	s_waitcnt lgkmcnt(0)
	v_mfma_f32_16x16x32_bf16 v[126:129], v[130:133], v[162:165], v[126:129]
	v_mfma_f32_16x16x32_bf16 v[122:125], v[138:141], v[162:165], v[122:125]
	v_mfma_f32_16x16x32_bf16 v[118:121], v[130:133], v[170:173], v[118:121]
	v_mfma_f32_16x16x32_bf16 v[114:117], v[138:141], v[170:173], v[114:117]
	v_mfma_f32_16x16x32_bf16 v[102:105], v[130:133], v[178:181], v[102:105]
	v_mfma_f32_16x16x32_bf16 v[98:101], v[138:141], v[178:181], v[98:101]
	v_mfma_f32_16x16x32_bf16 v[86:89], v[130:133], v[186:189], v[86:89]
	v_mfma_f32_16x16x32_bf16 v[82:85], v[138:141], v[186:189], v[82:85]
	v_mfma_f32_16x16x32_bf16 v[126:129], v[134:137], v[166:169], v[126:129]
	v_mfma_f32_16x16x32_bf16 v[122:125], v[142:145], v[166:169], v[122:125]
	v_mfma_f32_16x16x32_bf16 v[118:121], v[134:137], v[174:177], v[118:121]
	v_mfma_f32_16x16x32_bf16 v[114:117], v[142:145], v[174:177], v[114:117]
	v_mfma_f32_16x16x32_bf16 v[102:105], v[134:137], v[182:185], v[102:105]
	v_mfma_f32_16x16x32_bf16 v[98:101], v[142:145], v[182:185], v[98:101]
	v_mfma_f32_16x16x32_bf16 v[86:89], v[134:137], v[190:193], v[86:89]
	v_mfma_f32_16x16x32_bf16 v[82:85], v[142:145], v[190:193], v[82:85]
	v_mfma_f32_16x16x32_bf16 v[110:113], v[146:149], v[162:165], v[110:113]
	v_mfma_f32_16x16x32_bf16 v[106:109], v[154:157], v[162:165], v[106:109]
	v_mfma_f32_16x16x32_bf16 v[94:97], v[146:149], v[170:173], v[94:97]
	v_mfma_f32_16x16x32_bf16 v[90:93], v[154:157], v[170:173], v[90:93]
	v_mfma_f32_16x16x32_bf16 v[78:81], v[146:149], v[178:181], v[78:81]
	v_mfma_f32_16x16x32_bf16 v[74:77], v[154:157], v[178:181], v[74:77]
	v_mfma_f32_16x16x32_bf16 v[70:73], v[146:149], v[186:189], v[70:73]
	v_mfma_f32_16x16x32_bf16 v[66:69], v[154:157], v[186:189], v[66:69]
	v_mfma_f32_16x16x32_bf16 v[110:113], v[150:153], v[166:169], v[110:113]
	v_mfma_f32_16x16x32_bf16 v[106:109], v[158:161], v[166:169], v[106:109]
	v_mfma_f32_16x16x32_bf16 v[94:97], v[150:153], v[174:177], v[94:97]
	v_mfma_f32_16x16x32_bf16 v[90:93], v[158:161], v[174:177], v[90:93]
	v_mfma_f32_16x16x32_bf16 v[78:81], v[150:153], v[182:185], v[78:81]
	v_mfma_f32_16x16x32_bf16 v[74:77], v[158:161], v[182:185], v[74:77]
	v_mfma_f32_16x16x32_bf16 v[70:73], v[150:153], v[190:193], v[70:73]
	v_mfma_f32_16x16x32_bf16 v[66:69], v[158:161], v[190:193], v[66:69]
	s_barrier
	s_add_i32 s40, s40, s59
	v_lshl_add_u64 v[218:219], s[34:35], 0, v[0:1]
	s_mov_b32 m0, s40
	ds_read_b128 v[162:165], v251 offset:16384
	ds_read_b128 v[166:169], v251 offset:17408
	ds_read_b128 v[170:173], v251 offset:18432
	ds_read_b128 v[174:177], v251 offset:19456
	ds_read_b128 v[178:181], v251 offset:20480
	ds_read_b128 v[182:185], v251 offset:21504
	ds_read_b128 v[186:189], v251 offset:22528
	ds_read_b128 v[190:193], v251 offset:23552
	global_load_lds_dwordx4 v[218:219], off
	s_add_i32 m0, s40, 0x2000
	s_add_u32 s40, s34, 0x40000
	v_lshl_add_u64 v[220:221], s[34:35], 0, v[212:213]
	s_addc_u32 s41, s35, 0
	s_add_i32 s42, s42, s59
	global_load_lds_dwordx4 v[220:221], off
	v_lshl_add_u64 v[222:223], s[40:41], 0, v[0:1]
	s_mov_b32 m0, s42
	v_lshl_add_u64 v[224:225], s[36:37], 0, v[210:211]
	global_load_lds_dwordx4 v[222:223], off
	v_lshl_add_u64 v[222:223], s[40:41], 0, v[212:213]
	s_add_i32 m0, s42, 0x2000
	s_nop 0
	global_load_lds_dwordx4 v[222:223], off
	v_lshl_add_u64 v[222:223], s[36:37], 0, v[208:209]
	s_mov_b32 m0, s29
	s_nop 0
	global_load_lds_dwordx4 v[222:223], off
	s_mov_b32 m0, s48
	s_nop 0
	global_load_lds_dwordx4 v[224:225], off
	s_waitcnt vmcnt(8)
	s_waitcnt lgkmcnt(0)
	s_barrier
; #define PG8_STAGE(bufoff, gbase, voff) do { _Pragma("unroll") for (int _i = 0; _i < 2; ++_i) \
;         __builtin_amdgcn_global_load_lds((const unsigned*)((const char*)(gbase) + (voff)[_i]), (PG8_LAS unsigned*)(lds + (bufoff) + ldsw + _i * 8192), 16, 0, 0); } while (0)
; #define PG8_LDA(dst, b, h) do { _Pragma("unroll") for (int m = 0; m < 4; ++m) _Pragma("unroll") for (int k = 0; k < 2; ++k) dst[m][k] = *(const PG8_LAS bf16x8*)(lds + PG8_SA(b, h) + aoff + m * 2048 + k * 1024); } while (0)
; #define PG8_LDB(dst, b, h) do { _Pragma("unroll") for (int n = 0; n < 2; ++n) _Pragma("unroll") for (int k = 0; k < 2; ++k) dst[n][k] = *(const PG8_LAS bf16x8*)(lds + PG8_SB(b, h) + boff + n * 2048 + k * 1024); } while (0)
; #define PG8_MMA(ai, bj, At, Bt) do { __builtin_amdgcn_s_setprio(1); _Pragma("unroll") for (int m = 0; m < 4; ++m) _Pragma("unroll") for (int n = 0; n < 2; ++n) _Pragma("unroll") for (int k = 0; k < 2; ++k) \
;         acc[ai][bj][m][n] = __builtin_amdgcn_mfma_f32_16x16x32_bf16(Bt[n][k], At[m][k], acc[ai][bj][m][n], 0, 0, 0); __builtin_amdgcn_s_setprio(0); } while (0)
; #define PG8_WAIT_V(n) asm volatile("s_waitcnt vmcnt(" #n ")" ::: "memory")
; #define PG8_WAIT_L(n) asm volatile("s_waitcnt lgkmcnt(" #n ")" ::: "memory")
; #define PG8_BAR __builtin_amdgcn_s_barrier()
; #define PG8_SCHED __builtin_amdgcn_sched_barrier(0)
; template <class Epi, class Sched, bool ALIGN_EPI = false, bool SP2 = false>
; __device__ __forceinline__ void gemm_phase(PG8_LAS unsigned char* lds, const Gemm g, const Sched& S, const Epi& E, int wid_in) {
;     ...
;             PG8_WAIT_V(8); PG8_WAIT_L(0); PG8_BAR; PG8_MMA(1, 0, At, B0); PG8_MMA(1, 1, At, B1); PG8_BAR; PG8_SCHED;
;             PG8_LDB(B0, 1, 0); PG8_LDB(B1, 1, 1); PG8_SCHED; PG8_LDA(At, 1, 0); PG8_STAGE(PG8_SA(0, 1), a2 + hstep, voffA);
;             PG8_WAIT_V(8); PG8_WAIT_L(0); PG8_BAR; PG8_MMA(0, 0, At, B0); PG8_MMA(0, 1, At, B1); PG8_BAR; PG8_SCHED;
	s_waitcnt lgkmcnt(0)
	v_mfma_f32_16x16x32_bf16 v[62:65], v[130:133], v[162:165], v[62:65]
	v_mfma_f32_16x16x32_bf16 v[58:61], v[138:141], v[162:165], v[58:61]
	v_mfma_f32_16x16x32_bf16 v[54:57], v[130:133], v[170:173], v[54:57]
	v_mfma_f32_16x16x32_bf16 v[50:53], v[138:141], v[170:173], v[50:53]
	v_mfma_f32_16x16x32_bf16 v[38:41], v[130:133], v[178:181], v[38:41]
	v_mfma_f32_16x16x32_bf16 v[34:37], v[138:141], v[178:181], v[34:37]
	v_mfma_f32_16x16x32_bf16 v[22:25], v[130:133], v[186:189], v[22:25]
	v_mfma_f32_16x16x32_bf16 v[18:21], v[138:141], v[186:189], v[18:21]
	v_mfma_f32_16x16x32_bf16 v[62:65], v[134:137], v[166:169], v[62:65]
	v_mfma_f32_16x16x32_bf16 v[58:61], v[142:145], v[166:169], v[58:61]
	v_mfma_f32_16x16x32_bf16 v[54:57], v[134:137], v[174:177], v[54:57]
	v_mfma_f32_16x16x32_bf16 v[50:53], v[142:145], v[174:177], v[50:53]
	v_mfma_f32_16x16x32_bf16 v[38:41], v[134:137], v[182:185], v[38:41]
	v_mfma_f32_16x16x32_bf16 v[34:37], v[142:145], v[182:185], v[34:37]
	v_mfma_f32_16x16x32_bf16 v[22:25], v[134:137], v[190:193], v[22:25]
	v_mfma_f32_16x16x32_bf16 v[18:21], v[142:145], v[190:193], v[18:21]
	v_mfma_f32_16x16x32_bf16 v[46:49], v[146:149], v[162:165], v[46:49]
	v_mfma_f32_16x16x32_bf16 v[42:45], v[154:157], v[162:165], v[42:45]
	v_mfma_f32_16x16x32_bf16 v[30:33], v[146:149], v[170:173], v[30:33]
	v_mfma_f32_16x16x32_bf16 v[26:29], v[154:157], v[170:173], v[26:29]
	v_mfma_f32_16x16x32_bf16 v[14:17], v[146:149], v[178:181], v[14:17]
	v_mfma_f32_16x16x32_bf16 v[10:13], v[154:157], v[178:181], v[10:13]
	v_mfma_f32_16x16x32_bf16 v[6:9], v[146:149], v[186:189], v[6:9]
	v_mfma_f32_16x16x32_bf16 v[2:5], v[154:157], v[186:189], v[2:5]
	v_mfma_f32_16x16x32_bf16 v[46:49], v[150:153], v[166:169], v[46:49]
	v_mfma_f32_16x16x32_bf16 v[42:45], v[158:161], v[166:169], v[42:45]
	v_mfma_f32_16x16x32_bf16 v[30:33], v[150:153], v[174:177], v[30:33]
	v_mfma_f32_16x16x32_bf16 v[26:29], v[158:161], v[174:177], v[26:29]
	v_mfma_f32_16x16x32_bf16 v[14:17], v[150:153], v[182:185], v[14:17]
	v_mfma_f32_16x16x32_bf16 v[10:13], v[158:161], v[182:185], v[10:13]
	v_mfma_f32_16x16x32_bf16 v[6:9], v[150:153], v[190:193], v[6:9]
	v_mfma_f32_16x16x32_bf16 v[2:5], v[158:161], v[190:193], v[2:5]
	s_barrier
	s_add_i32 s40, 0, 0x18000
	s_add_i32 s41, 0, 0x1c000
	v_add_u32_e32 v142, s40, v195
	v_add_u32_e32 v158, s41, v195
	ds_read_b128 v[130:133], v142
	ds_read_b128 v[134:137], v142 offset:1024
	ds_read_b128 v[138:141], v142 offset:2048
	ds_read_b128 v[142:145], v142 offset:3072
	ds_read_b128 v[146:149], v158
	ds_read_b128 v[150:153], v158 offset:1024
	ds_read_b128 v[154:157], v158 offset:2048
	ds_read_b128 v[158:161], v158 offset:3072
	s_add_u32 s36, s36, 0x40000
	s_addc_u32 s37, s37, 0
	s_mov_b32 m0, s61
	v_lshl_add_u64 v[226:227], s[36:37], 0, v[208:209]
	ds_read_b128 v[162:165], v251 offset:32768
	ds_read_b128 v[166:169], v251 offset:33792
	ds_read_b128 v[170:173], v251 offset:34816
	ds_read_b128 v[174:177], v251 offset:35840
	ds_read_b128 v[178:181], v251 offset:36864
	ds_read_b128 v[182:185], v251 offset:37888
	ds_read_b128 v[186:189], v251 offset:38912
	ds_read_b128 v[190:193], v251 offset:39936
	global_load_lds_dwordx4 v[226:227], off
	v_lshl_add_u64 v[226:227], s[36:37], 0, v[210:211]
	s_mov_b32 m0, s62
	s_nop 0
	global_load_lds_dwordx4 v[226:227], off
	s_waitcnt vmcnt(8)
	s_waitcnt lgkmcnt(0)
	s_barrier
	s_waitcnt lgkmcnt(0)
	v_mfma_f32_16x16x32_bf16 v[126:129], v[130:133], v[162:165], v[126:129]
	v_mfma_f32_16x16x32_bf16 v[122:125], v[138:141], v[162:165], v[122:125]
	v_mfma_f32_16x16x32_bf16 v[118:121], v[130:133], v[170:173], v[118:121]
	v_mfma_f32_16x16x32_bf16 v[114:117], v[138:141], v[170:173], v[114:117]
	v_mfma_f32_16x16x32_bf16 v[102:105], v[130:133], v[178:181], v[102:105]
	v_mfma_f32_16x16x32_bf16 v[98:101], v[138:141], v[178:181], v[98:101]
	v_mfma_f32_16x16x32_bf16 v[86:89], v[130:133], v[186:189], v[86:89]
	v_mfma_f32_16x16x32_bf16 v[82:85], v[138:141], v[186:189], v[82:85]
	v_mfma_f32_16x16x32_bf16 v[126:129], v[134:137], v[166:169], v[126:129]
	v_mfma_f32_16x16x32_bf16 v[122:125], v[142:145], v[166:169], v[122:125]
	v_mfma_f32_16x16x32_bf16 v[118:121], v[134:137], v[174:177], v[118:121]
	v_mfma_f32_16x16x32_bf16 v[114:117], v[142:145], v[174:177], v[114:117]
	v_mfma_f32_16x16x32_bf16 v[102:105], v[134:137], v[182:185], v[102:105]
	v_mfma_f32_16x16x32_bf16 v[98:101], v[142:145], v[182:185], v[98:101]
	v_mfma_f32_16x16x32_bf16 v[86:89], v[134:137], v[190:193], v[86:89]
	v_mfma_f32_16x16x32_bf16 v[82:85], v[142:145], v[190:193], v[82:85]
	v_mfma_f32_16x16x32_bf16 v[110:113], v[146:149], v[162:165], v[110:113]
	v_mfma_f32_16x16x32_bf16 v[106:109], v[154:157], v[162:165], v[106:109]
	v_mfma_f32_16x16x32_bf16 v[94:97], v[146:149], v[170:173], v[94:97]
	v_mfma_f32_16x16x32_bf16 v[90:93], v[154:157], v[170:173], v[90:93]
	v_mfma_f32_16x16x32_bf16 v[78:81], v[146:149], v[178:181], v[78:81]
	v_mfma_f32_16x16x32_bf16 v[74:77], v[154:157], v[178:181], v[74:77]
	v_mfma_f32_16x16x32_bf16 v[70:73], v[146:149], v[186:189], v[70:73]
	v_mfma_f32_16x16x32_bf16 v[66:69], v[154:157], v[186:189], v[66:69]
	v_mfma_f32_16x16x32_bf16 v[110:113], v[150:153], v[166:169], v[110:113]
	v_mfma_f32_16x16x32_bf16 v[106:109], v[158:161], v[166:169], v[106:109]
	v_mfma_f32_16x16x32_bf16 v[94:97], v[150:153], v[174:177], v[94:97]
	v_mfma_f32_16x16x32_bf16 v[90:93], v[158:161], v[174:177], v[90:93]
	v_mfma_f32_16x16x32_bf16 v[78:81], v[150:153], v[182:185], v[78:81]
	v_mfma_f32_16x16x32_bf16 v[74:77], v[158:161], v[182:185], v[74:77]
	v_mfma_f32_16x16x32_bf16 v[70:73], v[150:153], v[190:193], v[70:73]
	v_mfma_f32_16x16x32_bf16 v[66:69], v[158:161], v[190:193], v[66:69]
	s_barrier
; #define PG8_STAGE(bufoff, gbase, voff) do { _Pragma("unroll") for (int _i = 0; _i < 2; ++_i) \
;         __builtin_amdgcn_global_load_lds((const unsigned*)((const char*)(gbase) + (voff)[_i]), (PG8_LAS unsigned*)(lds + (bufoff) + ldsw + _i * 8192), 16, 0, 0); } while (0)
; #define PG8_LDA(dst, b, h) do { _Pragma("unroll") for (int m = 0; m < 4; ++m) _Pragma("unroll") for (int k = 0; k < 2; ++k) dst[m][k] = *(const PG8_LAS bf16x8*)(lds + PG8_SA(b, h) + aoff + m * 2048 + k * 1024); } while (0)
; #define PG8_MMA(ai, bj, At, Bt) do { __builtin_amdgcn_s_setprio(1); _Pragma("unroll") for (int m = 0; m < 4; ++m) _Pragma("unroll") for (int n = 0; n < 2; ++n) _Pragma("unroll") for (int k = 0; k < 2; ++k) \
;         acc[ai][bj][m][n] = __builtin_amdgcn_mfma_f32_16x16x32_bf16(Bt[n][k], At[m][k], acc[ai][bj][m][n], 0, 0, 0); __builtin_amdgcn_s_setprio(0); } while (0)
; #define PG8_WAIT_V(n) asm volatile("s_waitcnt vmcnt(" #n ")" ::: "memory")
; #define PG8_WAIT_L(n) asm volatile("s_waitcnt lgkmcnt(" #n ")" ::: "memory")
; #define PG8_BAR __builtin_amdgcn_s_barrier()
; #define PG8_SCHED __builtin_amdgcn_sched_barrier(0)
; template <class Epi, class Sched, bool ALIGN_EPI = false, bool SP2 = false>
; __device__ __forceinline__ void gemm_phase(PG8_LAS unsigned char* lds, const Gemm g, const Sched& S, const Epi& E, int wid_in) {
;     ...
;         for (int t = 0; t < nt; t += 2) {
;             const bool last = (t == nt - 2);
;             const char* a1 = cA + (size_t)(t + 1) * kstep;
;             const char* a2 = last ? nA : cA + (size_t)(t + 2) * kstep; const char* b2 = last ? nB : cB + (size_t)(t + 2) * kstep;
;             const char* a3 = a2 + kstep; const char* b3 = b2 + kstep;
;             if (last && has_next) S.a_ready(nxt);
;     ...
;             PG8_LDA(At, 1, 1); PG8_STAGE(PG8_SB(1, 0), b3, voffB); PG8_STAGE(PG8_SB(1, 1), b3 + hstep, voffB); PG8_STAGE(PG8_SA(1, 0), a3, voffA);
;             PG8_WAIT_V(8); PG8_WAIT_L(0); PG8_BAR; PG8_MMA(1, 0, At, B0); PG8_MMA(1, 1, At, B1); PG8_BAR; PG8_SCHED;
	s_add_i32 s36, s40, s59
	v_lshl_add_u64 v[218:219], v[218:219], 0, s[94:95]
	s_mov_b32 m0, s36
	ds_read_b128 v[162:165], v251 offset:49152
	ds_read_b128 v[166:169], v251 offset:50176
	ds_read_b128 v[170:173], v251 offset:51200
	ds_read_b128 v[174:177], v251 offset:52224
	ds_read_b128 v[178:181], v251 offset:53248
	ds_read_b128 v[182:185], v251 offset:54272
	ds_read_b128 v[186:189], v251 offset:55296
	ds_read_b128 v[190:193], v251 offset:56320
	global_load_lds_dwordx4 v[218:219], off
	s_add_i32 m0, s36, 0x2000
	s_add_u32 s34, s34, 0x40080
	v_lshl_add_u64 v[218:219], v[220:221], 0, s[94:95]
	s_addc_u32 s35, s35, 0
	s_add_i32 s36, s41, s59
	global_load_lds_dwordx4 v[218:219], off
	v_lshl_add_u64 v[218:219], s[34:35], 0, v[0:1]
	s_mov_b32 m0, s36
	s_nop 0
	global_load_lds_dwordx4 v[218:219], off
	v_lshl_add_u64 v[218:219], s[34:35], 0, v[212:213]
	s_add_i32 m0, s36, 0x2000
	s_nop 0
	global_load_lds_dwordx4 v[218:219], off
	v_lshl_add_u64 v[218:219], v[222:223], 0, s[94:95]
	s_mov_b32 m0, s89
	s_nop 0
	global_load_lds_dwordx4 v[218:219], off
	v_lshl_add_u64 v[218:219], v[224:225], 0, s[94:95]
	s_mov_b32 m0, s90
	s_nop 0
	global_load_lds_dwordx4 v[218:219], off
	s_waitcnt vmcnt(8)
	s_waitcnt lgkmcnt(0)
	s_barrier
	s_waitcnt lgkmcnt(0)
	v_mfma_f32_16x16x32_bf16 v[62:65], v[130:133], v[162:165], v[62:65]
	v_mfma_f32_16x16x32_bf16 v[58:61], v[138:141], v[162:165], v[58:61]
	v_mfma_f32_16x16x32_bf16 v[54:57], v[130:133], v[170:173], v[54:57]
	v_mfma_f32_16x16x32_bf16 v[50:53], v[138:141], v[170:173], v[50:53]
	v_mfma_f32_16x16x32_bf16 v[38:41], v[130:133], v[178:181], v[38:41]
	v_mfma_f32_16x16x32_bf16 v[34:37], v[138:141], v[178:181], v[34:37]
	v_mfma_f32_16x16x32_bf16 v[22:25], v[130:133], v[186:189], v[22:25]
	v_mfma_f32_16x16x32_bf16 v[18:21], v[138:141], v[186:189], v[18:21]
	v_mfma_f32_16x16x32_bf16 v[62:65], v[134:137], v[166:169], v[62:65]
	v_mfma_f32_16x16x32_bf16 v[58:61], v[142:145], v[166:169], v[58:61]
	v_mfma_f32_16x16x32_bf16 v[54:57], v[134:137], v[174:177], v[54:57]
	v_mfma_f32_16x16x32_bf16 v[50:53], v[142:145], v[174:177], v[50:53]
	v_mfma_f32_16x16x32_bf16 v[38:41], v[134:137], v[182:185], v[38:41]
	v_mfma_f32_16x16x32_bf16 v[34:37], v[142:145], v[182:185], v[34:37]
	v_mfma_f32_16x16x32_bf16 v[22:25], v[134:137], v[190:193], v[22:25]
	v_mfma_f32_16x16x32_bf16 v[18:21], v[142:145], v[190:193], v[18:21]
	v_mfma_f32_16x16x32_bf16 v[46:49], v[146:149], v[162:165], v[46:49]
	v_mfma_f32_16x16x32_bf16 v[42:45], v[154:157], v[162:165], v[42:45]
	v_mfma_f32_16x16x32_bf16 v[30:33], v[146:149], v[170:173], v[30:33]
	v_mfma_f32_16x16x32_bf16 v[26:29], v[154:157], v[170:173], v[26:29]
	v_mfma_f32_16x16x32_bf16 v[14:17], v[146:149], v[178:181], v[14:17]
	v_mfma_f32_16x16x32_bf16 v[10:13], v[154:157], v[178:181], v[10:13]
	v_mfma_f32_16x16x32_bf16 v[6:9], v[146:149], v[186:189], v[6:9]
	v_mfma_f32_16x16x32_bf16 v[2:5], v[154:157], v[186:189], v[2:5]
	v_mfma_f32_16x16x32_bf16 v[46:49], v[150:153], v[166:169], v[46:49]
	v_mfma_f32_16x16x32_bf16 v[42:45], v[158:161], v[166:169], v[42:45]
	v_mfma_f32_16x16x32_bf16 v[30:33], v[150:153], v[174:177], v[30:33]
	v_mfma_f32_16x16x32_bf16 v[26:29], v[158:161], v[174:177], v[26:29]
	v_mfma_f32_16x16x32_bf16 v[14:17], v[150:153], v[182:185], v[14:17]
	v_mfma_f32_16x16x32_bf16 v[10:13], v[158:161], v[182:185], v[10:13]
	v_mfma_f32_16x16x32_bf16 v[6:9], v[150:153], v[190:193], v[6:9]
	v_mfma_f32_16x16x32_bf16 v[2:5], v[158:161], v[190:193], v[2:5]
	s_barrier
	s_add_u32 vcc_hi, vcc_hi, 0x100
	s_addc_u32 s63, s63, 0
	s_add_u32 s30, s30, 0x100
	s_addc_u32 s31, s31, 0
	s_cmp_ge_i32 s56, s1
	s_mov_b32 s34, s56
	s_cbranch_scc0 .LBB0_880
	s_setprio 0
	s_and_b64 vcc, exec, s[12:13]
	s_cbranch_vccz .LBB0_883
	s_barrier

; #define PG8_STAGE(bufoff, gbase, voff) do { _Pragma("unroll") for (int _i = 0; _i < 2; ++_i) \
;         __builtin_amdgcn_global_load_lds((const unsigned*)((const char*)(gbase) + (voff)[_i]), (PG8_LAS unsigned*)(lds + (bufoff) + ldsw + _i * 8192), 16, 0, 0); } while (0)
; #define PG8_LDA(dst, b, h) do { _Pragma("unroll") for (int m = 0; m < 4; ++m) _Pragma("unroll") for (int k = 0; k < 2; ++k) dst[m][k] = *(const PG8_LAS bf16x8*)(lds + PG8_SA(b, h) + aoff + m * 2048 + k * 1024); } while (0)
; #define PG8_LDB(dst, b, h) do { _Pragma("unroll") for (int n = 0; n < 2; ++n) _Pragma("unroll") for (int k = 0; k < 2; ++k) dst[n][k] = *(const PG8_LAS bf16x8*)(lds + PG8_SB(b, h) + boff + n * 2048 + k * 1024); } while (0)
; #define PG8_WAIT_V(n) asm volatile("s_waitcnt vmcnt(" #n ")" ::: "memory")
; #define PG8_WAIT_L(n) asm volatile("s_waitcnt lgkmcnt(" #n ")" ::: "memory")
; template <class Epi, class Sched, bool ALIGN_EPI = false, bool SP2 = false>
; __device__ __forceinline__ void gemm_phase(PG8_LAS unsigned char* lds, const Gemm g, const Sched& S, const Epi& E, int wid_in) {
;     ...
;         const bool has_next = S.next(ui + 1, nxt);
;         const char* nA = has_next ? (const char*)g.A + (size_t)nxt.pm * tstep + (size_t)nxt.kt0 * kstep : cA; const char* nB = has_next ? (const char*)g.Bt + (size_t)nxt.pn * tstep + (size_t)nxt.kt0 * kstep : cB;
;         const int nt = cur.nkt;
;         for (int t = 0; t < nt; t += 2) {
;             const bool last = (t == nt - 2);
;             const char* a1 = cA + (size_t)(t + 1) * kstep;
;             const char* a2 = last ? nA : cA + (size_t)(t + 2) * kstep; const char* b2 = last ? nB : cB + (size_t)(t + 2) * kstep;
;             const char* a3 = a2 + kstep; const char* b3 = b2 + kstep;
;             if (last && has_next) S.a_ready(nxt);
;             if constexpr (SP2) {
;             PG8_LDB(B0, 0, 0); PG8_LDB(B1, 0, 1); PG8_SCHED; PG8_LDA(At, 0, 0); PG8_STAGE(PG8_SA(1, 1), a1 + hstep, voffA);
;             PG8_WAIT_V(8); PG8_WAIT_L(0); PG8_BAR; PG8_MMA(0, 0, At, B0); PG8_MMA(0, 1, At, B1); PG8_BAR; PG8_SCHED;
;     ...
; #pragma unroll
;         for (int a = 0; a < 2; ++a)
; #pragma unroll
;             for (int b = 0; b < 2; ++b)
; #pragma unroll
;                 for (int m = 0; m < 4; ++m)
; #pragma unroll
;                     for (int n = 0; n < 2; ++n) acc[a][b][m][n] = (f32x4){0.f, 0.f, 0.f, 0.f};
.LBB0_1020:
	s_add_i32 s17, s90, -2
	s_add_u32 s19, s30, 0x100
	s_addc_u32 s21, s31, 0
	s_add_u32 s30, s34, 0x80080
	v_mov_b32_e32 v2, 0
	s_addc_u32 s31, s35, 0
	s_mov_b32 s27, 0
	v_mov_b32_e32 v3, v2
	v_mov_b32_e32 v4, v2
	v_mov_b32_e32 v5, v2
	v_mov_b32_e32 v6, v2
	v_mov_b32_e32 v7, v2
	v_mov_b32_e32 v8, v2
	v_mov_b32_e32 v9, v2
	v_mov_b32_e32 v10, v2
	v_mov_b32_e32 v11, v2
	v_mov_b32_e32 v12, v2
	v_mov_b32_e32 v13, v2
	v_mov_b32_e32 v14, v2
	v_mov_b32_e32 v15, v2
	v_mov_b32_e32 v16, v2
	v_mov_b32_e32 v17, v2
	v_mov_b32_e32 v26, v2
	v_mov_b32_e32 v27, v2
	v_mov_b32_e32 v28, v2
	v_mov_b32_e32 v29, v2
	v_mov_b32_e32 v30, v2
	v_mov_b32_e32 v31, v2
	v_mov_b32_e32 v32, v2
	v_mov_b32_e32 v33, v2
	v_mov_b32_e32 v42, v2
	v_mov_b32_e32 v43, v2
	v_mov_b32_e32 v44, v2
	v_mov_b32_e32 v45, v2
	v_mov_b32_e32 v46, v2
	v_mov_b32_e32 v47, v2
	v_mov_b32_e32 v48, v2
	v_mov_b32_e32 v49, v2
	v_mov_b32_e32 v18, v2
	v_mov_b32_e32 v19, v2
	v_mov_b32_e32 v20, v2
	v_mov_b32_e32 v21, v2
	v_mov_b32_e32 v22, v2
	v_mov_b32_e32 v23, v2
	v_mov_b32_e32 v24, v2
	v_mov_b32_e32 v25, v2
	v_mov_b32_e32 v34, v2
	v_mov_b32_e32 v35, v2
	v_mov_b32_e32 v36, v2
	v_mov_b32_e32 v37, v2
	v_mov_b32_e32 v38, v2
	v_mov_b32_e32 v39, v2
	v_mov_b32_e32 v40, v2
	v_mov_b32_e32 v41, v2
	v_mov_b32_e32 v50, v2
	v_mov_b32_e32 v51, v2
	v_mov_b32_e32 v52, v2
	v_mov_b32_e32 v53, v2
	v_mov_b32_e32 v54, v2
	v_mov_b32_e32 v55, v2
	v_mov_b32_e32 v56, v2
	v_mov_b32_e32 v57, v2
	v_mov_b32_e32 v58, v2
	v_mov_b32_e32 v59, v2
	v_mov_b32_e32 v60, v2
	v_mov_b32_e32 v61, v2
	v_mov_b32_e32 v62, v2
	v_mov_b32_e32 v63, v2
	v_mov_b32_e32 v64, v2
	v_mov_b32_e32 v65, v2
	v_mov_b32_e32 v66, v2
	v_mov_b32_e32 v67, v2
	v_mov_b32_e32 v68, v2
	v_mov_b32_e32 v69, v2
	v_mov_b32_e32 v70, v2
	v_mov_b32_e32 v71, v2
	v_mov_b32_e32 v72, v2
	v_mov_b32_e32 v73, v2
	v_mov_b32_e32 v74, v2
	v_mov_b32_e32 v75, v2
	v_mov_b32_e32 v76, v2
	v_mov_b32_e32 v77, v2
	v_mov_b32_e32 v78, v2
	v_mov_b32_e32 v79, v2
	v_mov_b32_e32 v80, v2
	v_mov_b32_e32 v81, v2
	v_mov_b32_e32 v90, v2
	v_mov_b32_e32 v91, v2
	v_mov_b32_e32 v92, v2
	v_mov_b32_e32 v93, v2
	v_mov_b32_e32 v94, v2
	v_mov_b32_e32 v95, v2
	v_mov_b32_e32 v96, v2
	v_mov_b32_e32 v97, v2
	v_mov_b32_e32 v106, v2
	v_mov_b32_e32 v107, v2
	v_mov_b32_e32 v108, v2
	v_mov_b32_e32 v109, v2
	v_mov_b32_e32 v110, v2
	v_mov_b32_e32 v111, v2
	v_mov_b32_e32 v112, v2
	v_mov_b32_e32 v113, v2
	v_mov_b32_e32 v82, v2
	v_mov_b32_e32 v83, v2
	v_mov_b32_e32 v84, v2
	v_mov_b32_e32 v85, v2
	v_mov_b32_e32 v86, v2
	v_mov_b32_e32 v87, v2
	v_mov_b32_e32 v88, v2
	v_mov_b32_e32 v89, v2
	v_mov_b32_e32 v98, v2
	v_mov_b32_e32 v99, v2
	v_mov_b32_e32 v100, v2
	v_mov_b32_e32 v101, v2
	v_mov_b32_e32 v102, v2
	v_mov_b32_e32 v103, v2
	v_mov_b32_e32 v104, v2
	v_mov_b32_e32 v105, v2
	v_mov_b32_e32 v114, v2
	v_mov_b32_e32 v115, v2
	v_mov_b32_e32 v116, v2
	v_mov_b32_e32 v117, v2
	v_mov_b32_e32 v118, v2
	v_mov_b32_e32 v119, v2
	v_mov_b32_e32 v120, v2
	v_mov_b32_e32 v121, v2
	v_mov_b32_e32 v122, v2
	v_mov_b32_e32 v123, v2
	v_mov_b32_e32 v124, v2
	v_mov_b32_e32 v125, v2
	v_mov_b32_e32 v126, v2
	v_mov_b32_e32 v127, v2
	v_mov_b32_e32 v128, v2
	v_mov_b32_e32 v129, v2
	s_cmp_ge_u32 s47, 4
	s_cbranch_scc0 .Lprio_skip_3
	s_setprio 1
.Lprio_skip_3:
.LBB0_1021:
	s_add_i32 s56, s27, 2
	s_add_u32 s34, s30, 0xfff80080
	s_addc_u32 s35, s31, -1
	s_add_i32 s40, 0, 0x10000
	s_cmp_eq_u32 s17, s27
	s_cselect_b32 s37, s23, s35
	s_cselect_b32 s36, s22, s34
	s_cselect_b32 s35, s25, s21
	s_cselect_b32 s34, s24, s19
	s_add_i32 s27, 0, 0x14000
	v_add_u32_e32 v142, s40, v176
	v_add_u32_e32 v168, s27, v176
	ds_read_b128 v[130:133], v142
	ds_read_b128 v[134:137], v142 offset:1024
	ds_read_b128 v[138:141], v142 offset:2048
	ds_read_b128 v[142:145], v142 offset:3072
	ds_read_b128 v[146:149], v168
	ds_read_b128 v[160:163], v168 offset:1024
	ds_read_b128 v[164:167], v168 offset:2048
	ds_read_b128 v[168:171], v168 offset:3072
	v_lshl_add_u64 v[220:221], s[30:31], 0, v[158:159]
	s_add_i32 m0, s29, 0xc000
	ds_read_b128 v[172:175], v177
	ds_read_b128 v[178:181], v177 offset:1024
	ds_read_b128 v[182:185], v177 offset:2048
	ds_read_b128 v[186:189], v177 offset:3072
	ds_read_b128 v[190:193], v177 offset:4096
	ds_read_b128 v[208:211], v177 offset:5120
	ds_read_b128 v[212:215], v177 offset:6144
	ds_read_b128 v[216:219], v177 offset:7168
	global_load_lds_dwordx4 v[220:221], off
	v_lshl_add_u64 v[220:221], s[30:31], 0, v[156:157]
	s_add_i32 m0, s29, 0xe000
	s_nop 0
	global_load_lds_dwordx4 v[220:221], off
	s_waitcnt vmcnt(8)
	s_waitcnt lgkmcnt(0)
	s_barrier
; #define PG8_STAGE(bufoff, gbase, voff) do { _Pragma("unroll") for (int _i = 0; _i < 2; ++_i) \
;         __builtin_amdgcn_global_load_lds((const unsigned*)((const char*)(gbase) + (voff)[_i]), (PG8_LAS unsigned*)(lds + (bufoff) + ldsw + _i * 8192), 16, 0, 0); } while (0)
; #define PG8_LDA(dst, b, h) do { _Pragma("unroll") for (int m = 0; m < 4; ++m) _Pragma("unroll") for (int k = 0; k < 2; ++k) dst[m][k] = *(const PG8_LAS bf16x8*)(lds + PG8_SA(b, h) + aoff + m * 2048 + k * 1024); } while (0)
; #define PG8_LDB(dst, b, h) do { _Pragma("unroll") for (int n = 0; n < 2; ++n) _Pragma("unroll") for (int k = 0; k < 2; ++k) dst[n][k] = *(const PG8_LAS bf16x8*)(lds + PG8_SB(b, h) + boff + n * 2048 + k * 1024); } while (0)
; #define PG8_MMA(ai, bj, At, Bt) do { __builtin_amdgcn_s_setprio(1); _Pragma("unroll") for (int m = 0; m < 4; ++m) _Pragma("unroll") for (int n = 0; n < 2; ++n) _Pragma("unroll") for (int k = 0; k < 2; ++k) \
;         acc[ai][bj][m][n] = __builtin_amdgcn_mfma_f32_16x16x32_bf16(Bt[n][k], At[m][k], acc[ai][bj][m][n], 0, 0, 0); __builtin_amdgcn_s_setprio(0); } while (0)
; #define PG8_WAIT_V(n) asm volatile("s_waitcnt vmcnt(" #n ")" ::: "memory")
; #define PG8_WAIT_L(n) asm volatile("s_waitcnt lgkmcnt(" #n ")" ::: "memory")
; #define PG8_BAR __builtin_amdgcn_s_barrier()
; #define PG8_SCHED __builtin_amdgcn_sched_barrier(0)
; template <class Epi, class Sched, bool ALIGN_EPI = false, bool SP2 = false>
; __device__ __forceinline__ void gemm_phase(PG8_LAS unsigned char* lds, const Gemm g, const Sched& S, const Epi& E, int wid_in) {
;     ...
;             PG8_WAIT_V(8); PG8_WAIT_L(0); PG8_BAR; PG8_MMA(0, 0, At, B0); PG8_MMA(0, 1, At, B1); PG8_BAR; PG8_SCHED;
;             PG8_LDA(At, 0, 1); PG8_STAGE(PG8_SB(0, 0), b2, voffB); PG8_STAGE(PG8_SB(0, 1), b2 + hstep, voffB); PG8_STAGE(PG8_SA(0, 0), a2, voffA);
;             PG8_WAIT_V(8); PG8_WAIT_L(0); PG8_BAR; PG8_MMA(1, 0, At, B0); PG8_MMA(1, 1, At, B1); PG8_BAR; PG8_SCHED;
;             PG8_LDB(B0, 1, 0); PG8_LDB(B1, 1, 1); PG8_SCHED; PG8_LDA(At, 1, 0); PG8_STAGE(PG8_SA(0, 1), a2 + hstep, voffA);
	s_waitcnt lgkmcnt(0)
	v_mfma_f32_16x16x32_bf16 v[126:129], v[130:133], v[172:175], v[126:129]
	v_mfma_f32_16x16x32_bf16 v[122:125], v[138:141], v[172:175], v[122:125]
	v_mfma_f32_16x16x32_bf16 v[118:121], v[130:133], v[182:185], v[118:121]
	v_mfma_f32_16x16x32_bf16 v[114:117], v[138:141], v[182:185], v[114:117]
	v_mfma_f32_16x16x32_bf16 v[102:105], v[130:133], v[190:193], v[102:105]
	v_mfma_f32_16x16x32_bf16 v[98:101], v[138:141], v[190:193], v[98:101]
	v_mfma_f32_16x16x32_bf16 v[86:89], v[130:133], v[212:215], v[86:89]
	v_mfma_f32_16x16x32_bf16 v[82:85], v[138:141], v[212:215], v[82:85]
	v_mfma_f32_16x16x32_bf16 v[126:129], v[134:137], v[178:181], v[126:129]
	v_mfma_f32_16x16x32_bf16 v[122:125], v[142:145], v[178:181], v[122:125]
	v_mfma_f32_16x16x32_bf16 v[118:121], v[134:137], v[186:189], v[118:121]
	v_mfma_f32_16x16x32_bf16 v[114:117], v[142:145], v[186:189], v[114:117]
	v_mfma_f32_16x16x32_bf16 v[102:105], v[134:137], v[208:211], v[102:105]
	v_mfma_f32_16x16x32_bf16 v[98:101], v[142:145], v[208:211], v[98:101]
	v_mfma_f32_16x16x32_bf16 v[86:89], v[134:137], v[216:219], v[86:89]
	v_mfma_f32_16x16x32_bf16 v[82:85], v[142:145], v[216:219], v[82:85]
	v_mfma_f32_16x16x32_bf16 v[110:113], v[146:149], v[172:175], v[110:113]
	v_mfma_f32_16x16x32_bf16 v[106:109], v[164:167], v[172:175], v[106:109]
	v_mfma_f32_16x16x32_bf16 v[94:97], v[146:149], v[182:185], v[94:97]
	v_mfma_f32_16x16x32_bf16 v[90:93], v[164:167], v[182:185], v[90:93]
	v_mfma_f32_16x16x32_bf16 v[78:81], v[146:149], v[190:193], v[78:81]
	v_mfma_f32_16x16x32_bf16 v[74:77], v[164:167], v[190:193], v[74:77]
	v_mfma_f32_16x16x32_bf16 v[70:73], v[146:149], v[212:215], v[70:73]
	v_mfma_f32_16x16x32_bf16 v[66:69], v[164:167], v[212:215], v[66:69]
	v_mfma_f32_16x16x32_bf16 v[110:113], v[160:163], v[178:181], v[110:113]
	v_mfma_f32_16x16x32_bf16 v[106:109], v[168:171], v[178:181], v[106:109]
	v_mfma_f32_16x16x32_bf16 v[94:97], v[160:163], v[186:189], v[94:97]
	v_mfma_f32_16x16x32_bf16 v[90:93], v[168:171], v[186:189], v[90:93]
	v_mfma_f32_16x16x32_bf16 v[78:81], v[160:163], v[208:211], v[78:81]
	v_mfma_f32_16x16x32_bf16 v[74:77], v[168:171], v[208:211], v[74:77]
	v_mfma_f32_16x16x32_bf16 v[70:73], v[160:163], v[216:219], v[70:73]
	v_mfma_f32_16x16x32_bf16 v[66:69], v[168:171], v[216:219], v[66:69]
	s_barrier
	s_add_i32 s40, s40, s59
	v_lshl_add_u64 v[220:221], s[34:35], 0, v[0:1]
	s_mov_b32 m0, s40
	ds_read_b128 v[172:175], v177 offset:16384
	ds_read_b128 v[178:181], v177 offset:17408
	ds_read_b128 v[182:185], v177 offset:18432
	ds_read_b128 v[186:189], v177 offset:19456
	ds_read_b128 v[190:193], v177 offset:20480
	ds_read_b128 v[208:211], v177 offset:21504
	ds_read_b128 v[212:215], v177 offset:22528
	ds_read_b128 v[216:219], v177 offset:23552
	global_load_lds_dwordx4 v[220:221], off
	s_add_i32 m0, s40, 0x2000
	s_add_u32 s40, s34, 0x80000
	v_lshl_add_u64 v[222:223], s[34:35], 0, v[154:155]
	s_addc_u32 s41, s35, 0
	s_add_i32 s27, s27, s59
	global_load_lds_dwordx4 v[222:223], off
	v_lshl_add_u64 v[224:225], s[40:41], 0, v[0:1]
	s_mov_b32 m0, s27
	v_lshl_add_u64 v[226:227], s[36:37], 0, v[152:153]
	global_load_lds_dwordx4 v[224:225], off
	v_lshl_add_u64 v[224:225], s[40:41], 0, v[154:155]
	s_add_i32 m0, s27, 0x2000
	s_nop 0
	global_load_lds_dwordx4 v[224:225], off
	v_lshl_add_u64 v[224:225], s[36:37], 0, v[150:151]
	s_mov_b32 m0, s29
	s_nop 0
	global_load_lds_dwordx4 v[224:225], off
	s_mov_b32 m0, s52
	s_nop 0
	global_load_lds_dwordx4 v[226:227], off
	s_waitcnt vmcnt(8)
	s_waitcnt lgkmcnt(0)
	s_barrier
	s_waitcnt lgkmcnt(0)
	v_mfma_f32_16x16x32_bf16 v[62:65], v[130:133], v[172:175], v[62:65]
	v_mfma_f32_16x16x32_bf16 v[58:61], v[138:141], v[172:175], v[58:61]
	v_mfma_f32_16x16x32_bf16 v[54:57], v[130:133], v[182:185], v[54:57]
	v_mfma_f32_16x16x32_bf16 v[50:53], v[138:141], v[182:185], v[50:53]
	v_mfma_f32_16x16x32_bf16 v[38:41], v[130:133], v[190:193], v[38:41]
	v_mfma_f32_16x16x32_bf16 v[34:37], v[138:141], v[190:193], v[34:37]
	v_mfma_f32_16x16x32_bf16 v[22:25], v[130:133], v[212:215], v[22:25]
	v_mfma_f32_16x16x32_bf16 v[18:21], v[138:141], v[212:215], v[18:21]
	v_mfma_f32_16x16x32_bf16 v[62:65], v[134:137], v[178:181], v[62:65]
	v_mfma_f32_16x16x32_bf16 v[58:61], v[142:145], v[178:181], v[58:61]
	v_mfma_f32_16x16x32_bf16 v[54:57], v[134:137], v[186:189], v[54:57]
	v_mfma_f32_16x16x32_bf16 v[50:53], v[142:145], v[186:189], v[50:53]
	v_mfma_f32_16x16x32_bf16 v[38:41], v[134:137], v[208:211], v[38:41]
	v_mfma_f32_16x16x32_bf16 v[34:37], v[142:145], v[208:211], v[34:37]
	v_mfma_f32_16x16x32_bf16 v[22:25], v[134:137], v[216:219], v[22:25]
	v_mfma_f32_16x16x32_bf16 v[18:21], v[142:145], v[216:219], v[18:21]
	v_mfma_f32_16x16x32_bf16 v[46:49], v[146:149], v[172:175], v[46:49]
	v_mfma_f32_16x16x32_bf16 v[42:45], v[164:167], v[172:175], v[42:45]
	v_mfma_f32_16x16x32_bf16 v[30:33], v[146:149], v[182:185], v[30:33]
	v_mfma_f32_16x16x32_bf16 v[26:29], v[164:167], v[182:185], v[26:29]
	v_mfma_f32_16x16x32_bf16 v[14:17], v[146:149], v[190:193], v[14:17]
	v_mfma_f32_16x16x32_bf16 v[10:13], v[164:167], v[190:193], v[10:13]
	v_mfma_f32_16x16x32_bf16 v[6:9], v[146:149], v[212:215], v[6:9]
	v_mfma_f32_16x16x32_bf16 v[2:5], v[164:167], v[212:215], v[2:5]
	v_mfma_f32_16x16x32_bf16 v[46:49], v[160:163], v[178:181], v[46:49]
	v_mfma_f32_16x16x32_bf16 v[42:45], v[168:171], v[178:181], v[42:45]
	v_mfma_f32_16x16x32_bf16 v[30:33], v[160:163], v[186:189], v[30:33]
	v_mfma_f32_16x16x32_bf16 v[26:29], v[168:171], v[186:189], v[26:29]
	v_mfma_f32_16x16x32_bf16 v[14:17], v[160:163], v[208:211], v[14:17]
	v_mfma_f32_16x16x32_bf16 v[10:13], v[168:171], v[208:211], v[10:13]
	v_mfma_f32_16x16x32_bf16 v[6:9], v[160:163], v[216:219], v[6:9]
	v_mfma_f32_16x16x32_bf16 v[2:5], v[168:171], v[216:219], v[2:5]
	s_barrier
; #define PG8_STAGE(bufoff, gbase, voff) do { _Pragma("unroll") for (int _i = 0; _i < 2; ++_i) \
;         __builtin_amdgcn_global_load_lds((const unsigned*)((const char*)(gbase) + (voff)[_i]), (PG8_LAS unsigned*)(lds + (bufoff) + ldsw + _i * 8192), 16, 0, 0); } while (0)
; #define PG8_LDA(dst, b, h) do { _Pragma("unroll") for (int m = 0; m < 4; ++m) _Pragma("unroll") for (int k = 0; k < 2; ++k) dst[m][k] = *(const PG8_LAS bf16x8*)(lds + PG8_SA(b, h) + aoff + m * 2048 + k * 1024); } while (0)
; #define PG8_LDB(dst, b, h) do { _Pragma("unroll") for (int n = 0; n < 2; ++n) _Pragma("unroll") for (int k = 0; k < 2; ++k) dst[n][k] = *(const PG8_LAS bf16x8*)(lds + PG8_SB(b, h) + boff + n * 2048 + k * 1024); } while (0)
; #define PG8_MMA(ai, bj, At, Bt) do { __builtin_amdgcn_s_setprio(1); _Pragma("unroll") for (int m = 0; m < 4; ++m) _Pragma("unroll") for (int n = 0; n < 2; ++n) _Pragma("unroll") for (int k = 0; k < 2; ++k) \
;         acc[ai][bj][m][n] = __builtin_amdgcn_mfma_f32_16x16x32_bf16(Bt[n][k], At[m][k], acc[ai][bj][m][n], 0, 0, 0); __builtin_amdgcn_s_setprio(0); } while (0)
; #define PG8_WAIT_V(n) asm volatile("s_waitcnt vmcnt(" #n ")" ::: "memory")
; #define PG8_WAIT_L(n) asm volatile("s_waitcnt lgkmcnt(" #n ")" ::: "memory")
; #define PG8_BAR __builtin_amdgcn_s_barrier()
; #define PG8_SCHED __builtin_amdgcn_sched_barrier(0)
; template <class Epi, class Sched, bool ALIGN_EPI = false, bool SP2 = false>
; __device__ __forceinline__ void gemm_phase(PG8_LAS unsigned char* lds, const Gemm g, const Sched& S, const Epi& E, int wid_in) {
;     ...
;             PG8_LDB(B0, 1, 0); PG8_LDB(B1, 1, 1); PG8_SCHED; PG8_LDA(At, 1, 0); PG8_STAGE(PG8_SA(0, 1), a2 + hstep, voffA);
;             PG8_WAIT_V(8); PG8_WAIT_L(0); PG8_BAR; PG8_MMA(0, 0, At, B0); PG8_MMA(0, 1, At, B1); PG8_BAR; PG8_SCHED;
	s_add_i32 s27, 0, 0x18000
	s_add_i32 s40, 0, 0x1c000
	v_add_u32_e32 v142, s27, v176
	v_add_u32_e32 v168, s40, v176
	ds_read_b128 v[130:133], v142
	ds_read_b128 v[134:137], v142 offset:1024
	ds_read_b128 v[138:141], v142 offset:2048
	ds_read_b128 v[142:145], v142 offset:3072
	ds_read_b128 v[146:149], v168
	ds_read_b128 v[160:163], v168 offset:1024
	ds_read_b128 v[164:167], v168 offset:2048
	ds_read_b128 v[168:171], v168 offset:3072
	s_add_u32 s36, s36, 0x80000
	s_addc_u32 s37, s37, 0
	s_mov_b32 m0, s53
	v_lshl_add_u64 v[228:229], s[36:37], 0, v[150:151]
	ds_read_b128 v[172:175], v177 offset:32768
	ds_read_b128 v[178:181], v177 offset:33792
	ds_read_b128 v[182:185], v177 offset:34816
	ds_read_b128 v[186:189], v177 offset:35840
	ds_read_b128 v[190:193], v177 offset:36864
	ds_read_b128 v[208:211], v177 offset:37888
	ds_read_b128 v[212:215], v177 offset:38912
	ds_read_b128 v[216:219], v177 offset:39936
	global_load_lds_dwordx4 v[228:229], off
	v_lshl_add_u64 v[228:229], s[36:37], 0, v[152:153]
	s_mov_b32 m0, s61
	s_nop 0
	global_load_lds_dwordx4 v[228:229], off
	s_waitcnt vmcnt(8)
	s_waitcnt lgkmcnt(0)
	s_barrier
	s_waitcnt lgkmcnt(0)
	v_mfma_f32_16x16x32_bf16 v[126:129], v[130:133], v[172:175], v[126:129]
	v_mfma_f32_16x16x32_bf16 v[122:125], v[138:141], v[172:175], v[122:125]
	v_mfma_f32_16x16x32_bf16 v[118:121], v[130:133], v[182:185], v[118:121]
	v_mfma_f32_16x16x32_bf16 v[114:117], v[138:141], v[182:185], v[114:117]
	v_mfma_f32_16x16x32_bf16 v[102:105], v[130:133], v[190:193], v[102:105]
	v_mfma_f32_16x16x32_bf16 v[98:101], v[138:141], v[190:193], v[98:101]
	v_mfma_f32_16x16x32_bf16 v[86:89], v[130:133], v[212:215], v[86:89]
	v_mfma_f32_16x16x32_bf16 v[82:85], v[138:141], v[212:215], v[82:85]
	v_mfma_f32_16x16x32_bf16 v[126:129], v[134:137], v[178:181], v[126:129]
	v_mfma_f32_16x16x32_bf16 v[122:125], v[142:145], v[178:181], v[122:125]
	v_mfma_f32_16x16x32_bf16 v[118:121], v[134:137], v[186:189], v[118:121]
	v_mfma_f32_16x16x32_bf16 v[114:117], v[142:145], v[186:189], v[114:117]
	v_mfma_f32_16x16x32_bf16 v[102:105], v[134:137], v[208:211], v[102:105]
	v_mfma_f32_16x16x32_bf16 v[98:101], v[142:145], v[208:211], v[98:101]
	v_mfma_f32_16x16x32_bf16 v[86:89], v[134:137], v[216:219], v[86:89]
	v_mfma_f32_16x16x32_bf16 v[82:85], v[142:145], v[216:219], v[82:85]
	v_mfma_f32_16x16x32_bf16 v[110:113], v[146:149], v[172:175], v[110:113]
	v_mfma_f32_16x16x32_bf16 v[106:109], v[164:167], v[172:175], v[106:109]
	v_mfma_f32_16x16x32_bf16 v[94:97], v[146:149], v[182:185], v[94:97]
	v_mfma_f32_16x16x32_bf16 v[90:93], v[164:167], v[182:185], v[90:93]
	v_mfma_f32_16x16x32_bf16 v[78:81], v[146:149], v[190:193], v[78:81]
	v_mfma_f32_16x16x32_bf16 v[74:77], v[164:167], v[190:193], v[74:77]
	v_mfma_f32_16x16x32_bf16 v[70:73], v[146:149], v[212:215], v[70:73]
	v_mfma_f32_16x16x32_bf16 v[66:69], v[164:167], v[212:215], v[66:69]
	v_mfma_f32_16x16x32_bf16 v[110:113], v[160:163], v[178:181], v[110:113]
	v_mfma_f32_16x16x32_bf16 v[106:109], v[168:171], v[178:181], v[106:109]
	v_mfma_f32_16x16x32_bf16 v[94:97], v[160:163], v[186:189], v[94:97]
	v_mfma_f32_16x16x32_bf16 v[90:93], v[168:171], v[186:189], v[90:93]
	v_mfma_f32_16x16x32_bf16 v[78:81], v[160:163], v[208:211], v[78:81]
	v_mfma_f32_16x16x32_bf16 v[74:77], v[168:171], v[208:211], v[74:77]
	v_mfma_f32_16x16x32_bf16 v[70:73], v[160:163], v[216:219], v[70:73]
	v_mfma_f32_16x16x32_bf16 v[66:69], v[168:171], v[216:219], v[66:69]
	s_barrier
; #define PG8_STAGE(bufoff, gbase, voff) do { _Pragma("unroll") for (int _i = 0; _i < 2; ++_i) \
;         __builtin_amdgcn_global_load_lds((const unsigned*)((const char*)(gbase) + (voff)[_i]), (PG8_LAS unsigned*)(lds + (bufoff) + ldsw + _i * 8192), 16, 0, 0); } while (0)
; #define PG8_LDA(dst, b, h) do { _Pragma("unroll") for (int m = 0; m < 4; ++m) _Pragma("unroll") for (int k = 0; k < 2; ++k) dst[m][k] = *(const PG8_LAS bf16x8*)(lds + PG8_SA(b, h) + aoff + m * 2048 + k * 1024); } while (0)
; #define PG8_MMA(ai, bj, At, Bt) do { __builtin_amdgcn_s_setprio(1); _Pragma("unroll") for (int m = 0; m < 4; ++m) _Pragma("unroll") for (int n = 0; n < 2; ++n) _Pragma("unroll") for (int k = 0; k < 2; ++k) \
;         acc[ai][bj][m][n] = __builtin_amdgcn_mfma_f32_16x16x32_bf16(Bt[n][k], At[m][k], acc[ai][bj][m][n], 0, 0, 0); __builtin_amdgcn_s_setprio(0); } while (0)
; #define PG8_WAIT_V(n) asm volatile("s_waitcnt vmcnt(" #n ")" ::: "memory")
; #define PG8_WAIT_L(n) asm volatile("s_waitcnt lgkmcnt(" #n ")" ::: "memory")
; #define PG8_BAR __builtin_amdgcn_s_barrier()
; #define PG8_SCHED __builtin_amdgcn_sched_barrier(0)
; template <class Epi, class Sched, bool ALIGN_EPI = false, bool SP2 = false>
; __device__ __forceinline__ void gemm_phase(PG8_LAS unsigned char* lds, const Gemm g, const Sched& S, const Epi& E, int wid_in) {
;     ...
;         for (int t = 0; t < nt; t += 2) {
;             const bool last = (t == nt - 2);
;             const char* a1 = cA + (size_t)(t + 1) * kstep;
;             const char* a2 = last ? nA : cA + (size_t)(t + 2) * kstep; const char* b2 = last ? nB : cB + (size_t)(t + 2) * kstep;
;             const char* a3 = a2 + kstep; const char* b3 = b2 + kstep;
;             if (last && has_next) S.a_ready(nxt);
;     ...
;             PG8_LDA(At, 1, 1); PG8_STAGE(PG8_SB(1, 0), b3, voffB); PG8_STAGE(PG8_SB(1, 1), b3 + hstep, voffB); PG8_STAGE(PG8_SA(1, 0), a3, voffA);
;             PG8_WAIT_V(8); PG8_WAIT_L(0); PG8_BAR; PG8_MMA(1, 0, At, B0); PG8_MMA(1, 1, At, B1); PG8_BAR; PG8_SCHED;
	s_add_i32 s27, s27, s59
	v_lshl_add_u64 v[220:221], v[220:221], 0, s[94:95]
	s_mov_b32 m0, s27
	ds_read_b128 v[172:175], v177 offset:49152
	ds_read_b128 v[178:181], v177 offset:50176
	ds_read_b128 v[182:185], v177 offset:51200
	ds_read_b128 v[186:189], v177 offset:52224
	ds_read_b128 v[190:193], v177 offset:53248
	ds_read_b128 v[208:211], v177 offset:54272
	ds_read_b128 v[212:215], v177 offset:55296
	ds_read_b128 v[216:219], v177 offset:56320
	global_load_lds_dwordx4 v[220:221], off
	s_add_i32 m0, s27, 0x2000
	s_add_u32 s34, s34, 0x80080
	v_lshl_add_u64 v[220:221], v[222:223], 0, s[94:95]
	s_addc_u32 s35, s35, 0
	s_add_i32 s27, s40, s59
	global_load_lds_dwordx4 v[220:221], off
	v_lshl_add_u64 v[220:221], s[34:35], 0, v[0:1]
	s_mov_b32 m0, s27
	s_nop 0
	global_load_lds_dwordx4 v[220:221], off
	v_lshl_add_u64 v[220:221], s[34:35], 0, v[154:155]
	s_add_i32 m0, s27, 0x2000
	s_nop 0
	global_load_lds_dwordx4 v[220:221], off
	v_lshl_add_u64 v[220:221], v[224:225], 0, s[94:95]
	s_mov_b32 m0, s73
	s_nop 0
	global_load_lds_dwordx4 v[220:221], off
	v_lshl_add_u64 v[220:221], v[226:227], 0, s[94:95]
	s_mov_b32 m0, s80
	s_nop 0
	global_load_lds_dwordx4 v[220:221], off
	s_waitcnt vmcnt(8)
	s_waitcnt lgkmcnt(0)
	s_barrier
	s_waitcnt lgkmcnt(0)
	v_mfma_f32_16x16x32_bf16 v[62:65], v[130:133], v[172:175], v[62:65]
	v_mfma_f32_16x16x32_bf16 v[58:61], v[138:141], v[172:175], v[58:61]
	v_mfma_f32_16x16x32_bf16 v[54:57], v[130:133], v[182:185], v[54:57]
	v_mfma_f32_16x16x32_bf16 v[50:53], v[138:141], v[182:185], v[50:53]
	v_mfma_f32_16x16x32_bf16 v[38:41], v[130:133], v[190:193], v[38:41]
	v_mfma_f32_16x16x32_bf16 v[34:37], v[138:141], v[190:193], v[34:37]
	v_mfma_f32_16x16x32_bf16 v[22:25], v[130:133], v[212:215], v[22:25]
	v_mfma_f32_16x16x32_bf16 v[18:21], v[138:141], v[212:215], v[18:21]
	v_mfma_f32_16x16x32_bf16 v[62:65], v[134:137], v[178:181], v[62:65]
	v_mfma_f32_16x16x32_bf16 v[58:61], v[142:145], v[178:181], v[58:61]
	v_mfma_f32_16x16x32_bf16 v[54:57], v[134:137], v[186:189], v[54:57]
	v_mfma_f32_16x16x32_bf16 v[50:53], v[142:145], v[186:189], v[50:53]
	v_mfma_f32_16x16x32_bf16 v[38:41], v[134:137], v[208:211], v[38:41]
	v_mfma_f32_16x16x32_bf16 v[34:37], v[142:145], v[208:211], v[34:37]
	v_mfma_f32_16x16x32_bf16 v[22:25], v[134:137], v[216:219], v[22:25]
	v_mfma_f32_16x16x32_bf16 v[18:21], v[142:145], v[216:219], v[18:21]
	v_mfma_f32_16x16x32_bf16 v[46:49], v[146:149], v[172:175], v[46:49]
	v_mfma_f32_16x16x32_bf16 v[42:45], v[164:167], v[172:175], v[42:45]
	v_mfma_f32_16x16x32_bf16 v[30:33], v[146:149], v[182:185], v[30:33]
	v_mfma_f32_16x16x32_bf16 v[26:29], v[164:167], v[182:185], v[26:29]
	v_mfma_f32_16x16x32_bf16 v[14:17], v[146:149], v[190:193], v[14:17]
	v_mfma_f32_16x16x32_bf16 v[10:13], v[164:167], v[190:193], v[10:13]
	v_mfma_f32_16x16x32_bf16 v[6:9], v[146:149], v[212:215], v[6:9]
	v_mfma_f32_16x16x32_bf16 v[2:5], v[164:167], v[212:215], v[2:5]
	v_mfma_f32_16x16x32_bf16 v[46:49], v[160:163], v[178:181], v[46:49]
	v_mfma_f32_16x16x32_bf16 v[42:45], v[168:171], v[178:181], v[42:45]
	v_mfma_f32_16x16x32_bf16 v[30:33], v[160:163], v[186:189], v[30:33]
	v_mfma_f32_16x16x32_bf16 v[26:29], v[168:171], v[186:189], v[26:29]
	v_mfma_f32_16x16x32_bf16 v[14:17], v[160:163], v[208:211], v[14:17]
	v_mfma_f32_16x16x32_bf16 v[10:13], v[168:171], v[208:211], v[10:13]
	v_mfma_f32_16x16x32_bf16 v[6:9], v[160:163], v[216:219], v[6:9]
	v_mfma_f32_16x16x32_bf16 v[2:5], v[168:171], v[216:219], v[2:5]
	s_barrier
	s_add_u32 s19, s19, 0x100
	s_addc_u32 s21, s21, 0
	s_add_u32 s30, s30, 0x100
	s_addc_u32 s31, s31, 0
	s_cmp_ge_i32 s56, s90
	s_mov_b32 s27, s56
	s_cbranch_scc0 .LBB0_1021
	s_setprio 0
	s_and_b64 vcc, exec, s[14:15]
	s_cbranch_vccz .LBB0_1024
	s_barrier

; #define PG8_STAGE(bufoff, gbase, voff) do { _Pragma("unroll") for (int _i = 0; _i < 2; ++_i) \
;         __builtin_amdgcn_global_load_lds((const unsigned*)((const char*)(gbase) + (voff)[_i]), (PG8_LAS unsigned*)(lds + (bufoff) + ldsw + _i * 8192), 16, 0, 0); } while (0)
; #define PG8_LDA(dst, b, h) do { _Pragma("unroll") for (int m = 0; m < 4; ++m) _Pragma("unroll") for (int k = 0; k < 2; ++k) dst[m][k] = *(const PG8_LAS bf16x8*)(lds + PG8_SA(b, h) + aoff + m * 2048 + k * 1024); } while (0)
; #define PG8_LDB(dst, b, h) do { _Pragma("unroll") for (int n = 0; n < 2; ++n) _Pragma("unroll") for (int k = 0; k < 2; ++k) dst[n][k] = *(const PG8_LAS bf16x8*)(lds + PG8_SB(b, h) + boff + n * 2048 + k * 1024); } while (0)
; #define PG8_WAIT_V(n) asm volatile("s_waitcnt vmcnt(" #n ")" ::: "memory")
; #define PG8_WAIT_L(n) asm volatile("s_waitcnt lgkmcnt(" #n ")" ::: "memory")
; template <class Epi, class Sched, bool ALIGN_EPI = false, bool SP2 = false>
; __device__ __forceinline__ void gemm_phase(PG8_LAS unsigned char* lds, const Gemm g, const Sched& S, const Epi& E, int wid_in) {
;     ...
;         const bool has_next = S.next(ui + 1, nxt);
;         const char* nA = has_next ? (const char*)g.A + (size_t)nxt.pm * tstep + (size_t)nxt.kt0 * kstep : cA; const char* nB = has_next ? (const char*)g.Bt + (size_t)nxt.pn * tstep + (size_t)nxt.kt0 * kstep : cB;
;         const int nt = cur.nkt;
;         for (int t = 0; t < nt; t += 2) {
;             const bool last = (t == nt - 2);
;             const char* a1 = cA + (size_t)(t + 1) * kstep;
;             const char* a2 = last ? nA : cA + (size_t)(t + 2) * kstep; const char* b2 = last ? nB : cB + (size_t)(t + 2) * kstep;
;             const char* a3 = a2 + kstep; const char* b3 = b2 + kstep;
;             if (last && has_next) S.a_ready(nxt);
;             if constexpr (SP2) {
;             PG8_LDB(B0, 0, 0); PG8_LDB(B1, 0, 1); PG8_SCHED; PG8_LDA(At, 0, 0); PG8_STAGE(PG8_SA(1, 1), a1 + hstep, voffA);
;             PG8_WAIT_V(8); PG8_WAIT_L(0); PG8_BAR; PG8_MMA(0, 0, At, B0); PG8_MMA(0, 1, At, B1); PG8_BAR; PG8_SCHED;
;     ...
; #pragma unroll
;         for (int a = 0; a < 2; ++a)
; #pragma unroll
;             for (int b = 0; b < 2; ++b)
; #pragma unroll
;                 for (int m = 0; m < 4; ++m)
; #pragma unroll
;                     for (int n = 0; n < 2; ++n) acc[a][b][m][n] = (f32x4){0.f, 0.f, 0.f, 0.f};
.LBB0_1152:
	s_ashr_i32 s19, s18, 31
	s_lshl_b64 s[20:21], s[18:19], 20
	s_add_u32 s20, s0, s20
	s_addc_u32 s21, s1, s21
	s_and_b64 s[22:23], s[8:9], exec
	s_cselect_b32 s19, s21, s25
	s_cselect_b32 s64, s20, s24
	s_ashr_i32 s17, s16, 31
	s_lshl_b64 s[22:23], s[16:17], 20
	s_add_u32 s22, s30, s22
	s_addc_u32 s23, s31, s23
	s_and_b64 s[28:29], s[8:9], exec
	s_cselect_b32 s17, s23, s27
	s_cselect_b32 s65, s22, s26
	s_add_u32 s72, s26, 0x100
	s_addc_u32 s63, s27, 0
	s_add_u32 s24, s24, 0x80080
	v_mov_b32_e32 v2, 0
	s_addc_u32 s25, s25, 0
	s_mov_b32 s73, -2
	v_mov_b32_e32 v3, v2
	v_mov_b32_e32 v4, v2
	v_mov_b32_e32 v5, v2
	v_mov_b32_e32 v6, v2
	v_mov_b32_e32 v7, v2
	v_mov_b32_e32 v8, v2
	v_mov_b32_e32 v9, v2
	v_mov_b32_e32 v18, v2
	v_mov_b32_e32 v19, v2
	v_mov_b32_e32 v20, v2
	v_mov_b32_e32 v21, v2
	v_mov_b32_e32 v22, v2
	v_mov_b32_e32 v23, v2
	v_mov_b32_e32 v24, v2
	v_mov_b32_e32 v25, v2
	v_mov_b32_e32 v34, v2
	v_mov_b32_e32 v35, v2
	v_mov_b32_e32 v36, v2
	v_mov_b32_e32 v37, v2
	v_mov_b32_e32 v38, v2
	v_mov_b32_e32 v39, v2
	v_mov_b32_e32 v40, v2
	v_mov_b32_e32 v41, v2
	v_mov_b32_e32 v50, v2
	v_mov_b32_e32 v51, v2
	v_mov_b32_e32 v52, v2
	v_mov_b32_e32 v53, v2
	v_mov_b32_e32 v54, v2
	v_mov_b32_e32 v55, v2
	v_mov_b32_e32 v56, v2
	v_mov_b32_e32 v57, v2
	v_mov_b32_e32 v10, v2
	v_mov_b32_e32 v11, v2
	v_mov_b32_e32 v12, v2
	v_mov_b32_e32 v13, v2
	v_mov_b32_e32 v14, v2
	v_mov_b32_e32 v15, v2
	v_mov_b32_e32 v16, v2
	v_mov_b32_e32 v17, v2
	v_mov_b32_e32 v26, v2
	v_mov_b32_e32 v27, v2
	v_mov_b32_e32 v28, v2
	v_mov_b32_e32 v29, v2
	v_mov_b32_e32 v30, v2
	v_mov_b32_e32 v31, v2
	v_mov_b32_e32 v32, v2
	v_mov_b32_e32 v33, v2
	v_mov_b32_e32 v42, v2
	v_mov_b32_e32 v43, v2
	v_mov_b32_e32 v44, v2
	v_mov_b32_e32 v45, v2
	v_mov_b32_e32 v46, v2
	v_mov_b32_e32 v47, v2
	v_mov_b32_e32 v48, v2
	v_mov_b32_e32 v49, v2
	v_mov_b32_e32 v58, v2
	v_mov_b32_e32 v59, v2
	v_mov_b32_e32 v60, v2
	v_mov_b32_e32 v61, v2
	v_mov_b32_e32 v62, v2
	v_mov_b32_e32 v63, v2
	v_mov_b32_e32 v64, v2
	v_mov_b32_e32 v65, v2
	v_mov_b32_e32 v66, v2
	v_mov_b32_e32 v67, v2
	v_mov_b32_e32 v68, v2
	v_mov_b32_e32 v69, v2
	v_mov_b32_e32 v70, v2
	v_mov_b32_e32 v71, v2
	v_mov_b32_e32 v72, v2
	v_mov_b32_e32 v73, v2
	v_mov_b32_e32 v82, v2
	v_mov_b32_e32 v83, v2
	v_mov_b32_e32 v84, v2
	v_mov_b32_e32 v85, v2
	v_mov_b32_e32 v86, v2
	v_mov_b32_e32 v87, v2
	v_mov_b32_e32 v88, v2
	v_mov_b32_e32 v89, v2
	v_mov_b32_e32 v98, v2
	v_mov_b32_e32 v99, v2
	v_mov_b32_e32 v100, v2
	v_mov_b32_e32 v101, v2
	v_mov_b32_e32 v102, v2
	v_mov_b32_e32 v103, v2
	v_mov_b32_e32 v104, v2
	v_mov_b32_e32 v105, v2
	v_mov_b32_e32 v114, v2
	v_mov_b32_e32 v115, v2
	v_mov_b32_e32 v116, v2
	v_mov_b32_e32 v117, v2
	v_mov_b32_e32 v118, v2
	v_mov_b32_e32 v119, v2
	v_mov_b32_e32 v120, v2
	v_mov_b32_e32 v121, v2
	v_mov_b32_e32 v74, v2
	v_mov_b32_e32 v75, v2
	v_mov_b32_e32 v76, v2
	v_mov_b32_e32 v77, v2
	v_mov_b32_e32 v78, v2
	v_mov_b32_e32 v79, v2
	v_mov_b32_e32 v80, v2
	v_mov_b32_e32 v81, v2
	v_mov_b32_e32 v90, v2
	v_mov_b32_e32 v91, v2
	v_mov_b32_e32 v92, v2
	v_mov_b32_e32 v93, v2
	v_mov_b32_e32 v94, v2
	v_mov_b32_e32 v95, v2
	v_mov_b32_e32 v96, v2
	v_mov_b32_e32 v97, v2
	v_mov_b32_e32 v106, v2
	v_mov_b32_e32 v107, v2
	v_mov_b32_e32 v108, v2
	v_mov_b32_e32 v109, v2
	v_mov_b32_e32 v110, v2
	v_mov_b32_e32 v111, v2
	v_mov_b32_e32 v112, v2
	v_mov_b32_e32 v113, v2
	v_mov_b32_e32 v122, v2
	v_mov_b32_e32 v123, v2
	v_mov_b32_e32 v124, v2
	v_mov_b32_e32 v125, v2
	v_mov_b32_e32 v126, v2
	v_mov_b32_e32 v127, v2
	v_mov_b32_e32 v128, v2
	v_mov_b32_e32 v129, v2
	s_cmp_ge_u32 s47, 4
	s_cbranch_scc0 .Lprio_skip_4
	s_setprio 1
.Lprio_skip_4:
.LBB0_1153:
	s_add_u32 s26, s24, 0xfff80080
	s_addc_u32 s27, s25, -1
	s_add_i32 s40, 0, 0x10000
	s_cmp_eq_u32 s73, 28
	s_cselect_b32 s29, s19, s27
	s_cselect_b32 s28, s64, s26
	v_add_u32_e32 v140, s40, v142
	s_cselect_b32 s27, s17, s63
	s_cselect_b32 s26, s65, s72
	s_add_i32 s42, 0, 0x14000
	ds_read_b128 v[144:147], v140
	ds_read_b128 v[148:151], v140 offset:1024
	ds_read_b128 v[152:155], v140 offset:2048
	ds_read_b128 v[156:159], v140 offset:3072
	v_add_u32_e32 v140, s42, v142
	ds_read_b128 v[160:163], v140
	ds_read_b128 v[164:167], v140 offset:1024
	ds_read_b128 v[168:171], v140 offset:2048
	ds_read_b128 v[172:175], v140 offset:3072
	v_lshl_add_u64 v[140:141], s[24:25], 0, v[138:139]
	s_add_i32 m0, s34, 0xc000
	ds_read_b128 v[176:179], v143
	ds_read_b128 v[180:183], v143 offset:1024
	ds_read_b128 v[184:187], v143 offset:2048
	ds_read_b128 v[188:191], v143 offset:3072
	ds_read_b128 v[208:211], v143 offset:4096
	ds_read_b128 v[212:215], v143 offset:5120
	ds_read_b128 v[216:219], v143 offset:6144
	ds_read_b128 v[220:223], v143 offset:7168
	global_load_lds_dwordx4 v[140:141], off
	v_lshl_add_u64 v[140:141], s[24:25], 0, v[136:137]
	s_add_i32 m0, s34, 0xe000
	s_nop 0
	global_load_lds_dwordx4 v[140:141], off
	s_waitcnt vmcnt(8)
	s_waitcnt lgkmcnt(0)
	s_barrier
; #define PG8_STAGE(bufoff, gbase, voff) do { _Pragma("unroll") for (int _i = 0; _i < 2; ++_i) \
;         __builtin_amdgcn_global_load_lds((const unsigned*)((const char*)(gbase) + (voff)[_i]), (PG8_LAS unsigned*)(lds + (bufoff) + ldsw + _i * 8192), 16, 0, 0); } while (0)
; #define PG8_LDA(dst, b, h) do { _Pragma("unroll") for (int m = 0; m < 4; ++m) _Pragma("unroll") for (int k = 0; k < 2; ++k) dst[m][k] = *(const PG8_LAS bf16x8*)(lds + PG8_SA(b, h) + aoff + m * 2048 + k * 1024); } while (0)
; #define PG8_LDB(dst, b, h) do { _Pragma("unroll") for (int n = 0; n < 2; ++n) _Pragma("unroll") for (int k = 0; k < 2; ++k) dst[n][k] = *(const PG8_LAS bf16x8*)(lds + PG8_SB(b, h) + boff + n * 2048 + k * 1024); } while (0)
; #define PG8_MMA(ai, bj, At, Bt) do { __builtin_amdgcn_s_setprio(1); _Pragma("unroll") for (int m = 0; m < 4; ++m) _Pragma("unroll") for (int n = 0; n < 2; ++n) _Pragma("unroll") for (int k = 0; k < 2; ++k) \
;         acc[ai][bj][m][n] = __builtin_amdgcn_mfma_f32_16x16x32_bf16(Bt[n][k], At[m][k], acc[ai][bj][m][n], 0, 0, 0); __builtin_amdgcn_s_setprio(0); } while (0)
; #define PG8_WAIT_V(n) asm volatile("s_waitcnt vmcnt(" #n ")" ::: "memory")
; #define PG8_WAIT_L(n) asm volatile("s_waitcnt lgkmcnt(" #n ")" ::: "memory")
; #define PG8_BAR __builtin_amdgcn_s_barrier()
; #define PG8_SCHED __builtin_amdgcn_sched_barrier(0)
; template <class Epi, class Sched, bool ALIGN_EPI = false, bool SP2 = false>
; __device__ __forceinline__ void gemm_phase(PG8_LAS unsigned char* lds, const Gemm g, const Sched& S, const Epi& E, int wid_in) {
;     ...
;             PG8_WAIT_V(8); PG8_WAIT_L(0); PG8_BAR; PG8_MMA(0, 0, At, B0); PG8_MMA(0, 1, At, B1); PG8_BAR; PG8_SCHED;
;             PG8_LDA(At, 0, 1); PG8_STAGE(PG8_SB(0, 0), b2, voffB); PG8_STAGE(PG8_SB(0, 1), b2 + hstep, voffB); PG8_STAGE(PG8_SA(0, 0), a2, voffA);
;             PG8_WAIT_V(8); PG8_WAIT_L(0); PG8_BAR; PG8_MMA(1, 0, At, B0); PG8_MMA(1, 1, At, B1); PG8_BAR; PG8_SCHED;
;             PG8_LDB(B0, 1, 0); PG8_LDB(B1, 1, 1); PG8_SCHED; PG8_LDA(At, 1, 0); PG8_STAGE(PG8_SA(0, 1), a2 + hstep, voffA);
	s_waitcnt lgkmcnt(0)
	v_mfma_f32_16x16x32_bf16 v[126:129], v[144:147], v[176:179], v[126:129]
	v_mfma_f32_16x16x32_bf16 v[122:125], v[152:155], v[176:179], v[122:125]
	v_mfma_f32_16x16x32_bf16 v[110:113], v[144:147], v[184:187], v[110:113]
	v_mfma_f32_16x16x32_bf16 v[106:109], v[152:155], v[184:187], v[106:109]
	v_mfma_f32_16x16x32_bf16 v[94:97], v[144:147], v[208:211], v[94:97]
	v_mfma_f32_16x16x32_bf16 v[90:93], v[152:155], v[208:211], v[90:93]
	v_mfma_f32_16x16x32_bf16 v[78:81], v[144:147], v[216:219], v[78:81]
	v_mfma_f32_16x16x32_bf16 v[74:77], v[152:155], v[216:219], v[74:77]
	v_mfma_f32_16x16x32_bf16 v[126:129], v[148:151], v[180:183], v[126:129]
	v_mfma_f32_16x16x32_bf16 v[122:125], v[156:159], v[180:183], v[122:125]
	v_mfma_f32_16x16x32_bf16 v[110:113], v[148:151], v[188:191], v[110:113]
	v_mfma_f32_16x16x32_bf16 v[106:109], v[156:159], v[188:191], v[106:109]
	v_mfma_f32_16x16x32_bf16 v[94:97], v[148:151], v[212:215], v[94:97]
	v_mfma_f32_16x16x32_bf16 v[90:93], v[156:159], v[212:215], v[90:93]
	v_mfma_f32_16x16x32_bf16 v[78:81], v[148:151], v[220:223], v[78:81]
	v_mfma_f32_16x16x32_bf16 v[74:77], v[156:159], v[220:223], v[74:77]
	v_mfma_f32_16x16x32_bf16 v[118:121], v[160:163], v[176:179], v[118:121]
	v_mfma_f32_16x16x32_bf16 v[114:117], v[168:171], v[176:179], v[114:117]
	v_mfma_f32_16x16x32_bf16 v[102:105], v[160:163], v[184:187], v[102:105]
	v_mfma_f32_16x16x32_bf16 v[98:101], v[168:171], v[184:187], v[98:101]
	v_mfma_f32_16x16x32_bf16 v[86:89], v[160:163], v[208:211], v[86:89]
	v_mfma_f32_16x16x32_bf16 v[82:85], v[168:171], v[208:211], v[82:85]
	v_mfma_f32_16x16x32_bf16 v[70:73], v[160:163], v[216:219], v[70:73]
	v_mfma_f32_16x16x32_bf16 v[66:69], v[168:171], v[216:219], v[66:69]
	v_mfma_f32_16x16x32_bf16 v[118:121], v[164:167], v[180:183], v[118:121]
	v_mfma_f32_16x16x32_bf16 v[114:117], v[172:175], v[180:183], v[114:117]
	v_mfma_f32_16x16x32_bf16 v[102:105], v[164:167], v[188:191], v[102:105]
	v_mfma_f32_16x16x32_bf16 v[98:101], v[172:175], v[188:191], v[98:101]
	v_mfma_f32_16x16x32_bf16 v[86:89], v[164:167], v[212:215], v[86:89]
	v_mfma_f32_16x16x32_bf16 v[82:85], v[172:175], v[212:215], v[82:85]
	v_mfma_f32_16x16x32_bf16 v[70:73], v[164:167], v[220:223], v[70:73]
	v_mfma_f32_16x16x32_bf16 v[66:69], v[172:175], v[220:223], v[66:69]
	s_barrier
	s_add_i32 s40, s40, s59
	v_lshl_add_u64 v[140:141], s[26:27], 0, v[0:1]
	s_mov_b32 m0, s40
	ds_read_b128 v[176:179], v143 offset:16384
	ds_read_b128 v[180:183], v143 offset:17408
	ds_read_b128 v[184:187], v143 offset:18432
	ds_read_b128 v[188:191], v143 offset:19456
	ds_read_b128 v[208:211], v143 offset:20480
	ds_read_b128 v[212:215], v143 offset:21504
	ds_read_b128 v[216:219], v143 offset:22528
	ds_read_b128 v[220:223], v143 offset:23552
	global_load_lds_dwordx4 v[140:141], off
	s_add_i32 m0, s40, 0x2000
	s_add_u32 s40, s26, 0x80000
	v_lshl_add_u64 v[192:193], s[26:27], 0, v[130:131]
	s_addc_u32 s41, s27, 0
	s_add_i32 s42, s42, s59
	global_load_lds_dwordx4 v[192:193], off
	v_lshl_add_u64 v[224:225], s[40:41], 0, v[0:1]
	s_mov_b32 m0, s42
	v_lshl_add_u64 v[226:227], s[28:29], 0, v[132:133]
	global_load_lds_dwordx4 v[224:225], off
	v_lshl_add_u64 v[224:225], s[40:41], 0, v[130:131]
	s_add_i32 m0, s42, 0x2000
	s_nop 0
	global_load_lds_dwordx4 v[224:225], off
	v_lshl_add_u64 v[224:225], s[28:29], 0, v[134:135]
	s_mov_b32 m0, s34
	s_nop 0
	global_load_lds_dwordx4 v[224:225], off
	s_mov_b32 m0, s35
	s_nop 0
	global_load_lds_dwordx4 v[226:227], off
	s_waitcnt vmcnt(8)
	s_waitcnt lgkmcnt(0)
	s_barrier
	s_waitcnt lgkmcnt(0)
	v_mfma_f32_16x16x32_bf16 v[62:65], v[144:147], v[176:179], v[62:65]
	v_mfma_f32_16x16x32_bf16 v[58:61], v[152:155], v[176:179], v[58:61]
	v_mfma_f32_16x16x32_bf16 v[46:49], v[144:147], v[184:187], v[46:49]
	v_mfma_f32_16x16x32_bf16 v[42:45], v[152:155], v[184:187], v[42:45]
	v_mfma_f32_16x16x32_bf16 v[30:33], v[144:147], v[208:211], v[30:33]
	v_mfma_f32_16x16x32_bf16 v[26:29], v[152:155], v[208:211], v[26:29]
	v_mfma_f32_16x16x32_bf16 v[14:17], v[144:147], v[216:219], v[14:17]
	v_mfma_f32_16x16x32_bf16 v[10:13], v[152:155], v[216:219], v[10:13]
	v_mfma_f32_16x16x32_bf16 v[62:65], v[148:151], v[180:183], v[62:65]
	v_mfma_f32_16x16x32_bf16 v[58:61], v[156:159], v[180:183], v[58:61]
	v_mfma_f32_16x16x32_bf16 v[46:49], v[148:151], v[188:191], v[46:49]
	v_mfma_f32_16x16x32_bf16 v[42:45], v[156:159], v[188:191], v[42:45]
	v_mfma_f32_16x16x32_bf16 v[30:33], v[148:151], v[212:215], v[30:33]
	v_mfma_f32_16x16x32_bf16 v[26:29], v[156:159], v[212:215], v[26:29]
	v_mfma_f32_16x16x32_bf16 v[14:17], v[148:151], v[220:223], v[14:17]
	v_mfma_f32_16x16x32_bf16 v[10:13], v[156:159], v[220:223], v[10:13]
	v_mfma_f32_16x16x32_bf16 v[54:57], v[160:163], v[176:179], v[54:57]
	v_mfma_f32_16x16x32_bf16 v[50:53], v[168:171], v[176:179], v[50:53]
	v_mfma_f32_16x16x32_bf16 v[38:41], v[160:163], v[184:187], v[38:41]
	v_mfma_f32_16x16x32_bf16 v[34:37], v[168:171], v[184:187], v[34:37]
	v_mfma_f32_16x16x32_bf16 v[22:25], v[160:163], v[208:211], v[22:25]
	v_mfma_f32_16x16x32_bf16 v[18:21], v[168:171], v[208:211], v[18:21]
	v_mfma_f32_16x16x32_bf16 v[6:9], v[160:163], v[216:219], v[6:9]
	v_mfma_f32_16x16x32_bf16 v[2:5], v[168:171], v[216:219], v[2:5]
	v_mfma_f32_16x16x32_bf16 v[54:57], v[164:167], v[180:183], v[54:57]
	v_mfma_f32_16x16x32_bf16 v[50:53], v[172:175], v[180:183], v[50:53]
	v_mfma_f32_16x16x32_bf16 v[38:41], v[164:167], v[188:191], v[38:41]
	v_mfma_f32_16x16x32_bf16 v[34:37], v[172:175], v[188:191], v[34:37]
	v_mfma_f32_16x16x32_bf16 v[22:25], v[164:167], v[212:215], v[22:25]
	v_mfma_f32_16x16x32_bf16 v[18:21], v[172:175], v[212:215], v[18:21]
	v_mfma_f32_16x16x32_bf16 v[6:9], v[164:167], v[220:223], v[6:9]
	v_mfma_f32_16x16x32_bf16 v[2:5], v[172:175], v[220:223], v[2:5]
	s_barrier
; #define PG8_STAGE(bufoff, gbase, voff) do { _Pragma("unroll") for (int _i = 0; _i < 2; ++_i) \
;         __builtin_amdgcn_global_load_lds((const unsigned*)((const char*)(gbase) + (voff)[_i]), (PG8_LAS unsigned*)(lds + (bufoff) + ldsw + _i * 8192), 16, 0, 0); } while (0)
; #define PG8_LDA(dst, b, h) do { _Pragma("unroll") for (int m = 0; m < 4; ++m) _Pragma("unroll") for (int k = 0; k < 2; ++k) dst[m][k] = *(const PG8_LAS bf16x8*)(lds + PG8_SA(b, h) + aoff + m * 2048 + k * 1024); } while (0)
; #define PG8_LDB(dst, b, h) do { _Pragma("unroll") for (int n = 0; n < 2; ++n) _Pragma("unroll") for (int k = 0; k < 2; ++k) dst[n][k] = *(const PG8_LAS bf16x8*)(lds + PG8_SB(b, h) + boff + n * 2048 + k * 1024); } while (0)
; #define PG8_MMA(ai, bj, At, Bt) do { __builtin_amdgcn_s_setprio(1); _Pragma("unroll") for (int m = 0; m < 4; ++m) _Pragma("unroll") for (int n = 0; n < 2; ++n) _Pragma("unroll") for (int k = 0; k < 2; ++k) \
;         acc[ai][bj][m][n] = __builtin_amdgcn_mfma_f32_16x16x32_bf16(Bt[n][k], At[m][k], acc[ai][bj][m][n], 0, 0, 0); __builtin_amdgcn_s_setprio(0); } while (0)
; #define PG8_WAIT_V(n) asm volatile("s_waitcnt vmcnt(" #n ")" ::: "memory")
; #define PG8_WAIT_L(n) asm volatile("s_waitcnt lgkmcnt(" #n ")" ::: "memory")
; #define PG8_BAR __builtin_amdgcn_s_barrier()
; #define PG8_SCHED __builtin_amdgcn_sched_barrier(0)
; template <class Epi, class Sched, bool ALIGN_EPI = false, bool SP2 = false>
; __device__ __forceinline__ void gemm_phase(PG8_LAS unsigned char* lds, const Gemm g, const Sched& S, const Epi& E, int wid_in) {
;     ...
;             PG8_LDB(B0, 1, 0); PG8_LDB(B1, 1, 1); PG8_SCHED; PG8_LDA(At, 1, 0); PG8_STAGE(PG8_SA(0, 1), a2 + hstep, voffA);
;             PG8_WAIT_V(8); PG8_WAIT_L(0); PG8_BAR; PG8_MMA(0, 0, At, B0); PG8_MMA(0, 1, At, B1); PG8_BAR; PG8_SCHED;
	s_add_i32 s40, 0, 0x18000
	s_add_i32 s41, 0, 0x1c000
	v_add_u32_e32 v156, s40, v142
	v_add_u32_e32 v172, s41, v142
	ds_read_b128 v[144:147], v156
	ds_read_b128 v[148:151], v156 offset:1024
	ds_read_b128 v[152:155], v156 offset:2048
	ds_read_b128 v[156:159], v156 offset:3072
	ds_read_b128 v[160:163], v172
	ds_read_b128 v[164:167], v172 offset:1024
	ds_read_b128 v[168:171], v172 offset:2048
	ds_read_b128 v[172:175], v172 offset:3072
	s_add_u32 s28, s28, 0x80000
	s_addc_u32 s29, s29, 0
	s_mov_b32 m0, s36
	v_lshl_add_u64 v[228:229], s[28:29], 0, v[134:135]
	ds_read_b128 v[176:179], v143 offset:32768
	ds_read_b128 v[180:183], v143 offset:33792
	ds_read_b128 v[184:187], v143 offset:34816
	ds_read_b128 v[188:191], v143 offset:35840
	ds_read_b128 v[208:211], v143 offset:36864
	ds_read_b128 v[212:215], v143 offset:37888
	ds_read_b128 v[216:219], v143 offset:38912
	ds_read_b128 v[220:223], v143 offset:39936
	global_load_lds_dwordx4 v[228:229], off
	v_lshl_add_u64 v[228:229], s[28:29], 0, v[132:133]
	s_mov_b32 m0, s37
	s_nop 0
	global_load_lds_dwordx4 v[228:229], off
	s_waitcnt vmcnt(8)
	s_waitcnt lgkmcnt(0)
	s_barrier
	s_waitcnt lgkmcnt(0)
	v_mfma_f32_16x16x32_bf16 v[126:129], v[144:147], v[176:179], v[126:129]
	v_mfma_f32_16x16x32_bf16 v[122:125], v[152:155], v[176:179], v[122:125]
	v_mfma_f32_16x16x32_bf16 v[110:113], v[144:147], v[184:187], v[110:113]
	v_mfma_f32_16x16x32_bf16 v[106:109], v[152:155], v[184:187], v[106:109]
	v_mfma_f32_16x16x32_bf16 v[94:97], v[144:147], v[208:211], v[94:97]
	v_mfma_f32_16x16x32_bf16 v[90:93], v[152:155], v[208:211], v[90:93]
	v_mfma_f32_16x16x32_bf16 v[78:81], v[144:147], v[216:219], v[78:81]
	v_mfma_f32_16x16x32_bf16 v[74:77], v[152:155], v[216:219], v[74:77]
	v_mfma_f32_16x16x32_bf16 v[126:129], v[148:151], v[180:183], v[126:129]
	v_mfma_f32_16x16x32_bf16 v[122:125], v[156:159], v[180:183], v[122:125]
	v_mfma_f32_16x16x32_bf16 v[110:113], v[148:151], v[188:191], v[110:113]
	v_mfma_f32_16x16x32_bf16 v[106:109], v[156:159], v[188:191], v[106:109]
	v_mfma_f32_16x16x32_bf16 v[94:97], v[148:151], v[212:215], v[94:97]
	v_mfma_f32_16x16x32_bf16 v[90:93], v[156:159], v[212:215], v[90:93]
	v_mfma_f32_16x16x32_bf16 v[78:81], v[148:151], v[220:223], v[78:81]
	v_mfma_f32_16x16x32_bf16 v[74:77], v[156:159], v[220:223], v[74:77]
	v_mfma_f32_16x16x32_bf16 v[118:121], v[160:163], v[176:179], v[118:121]
	v_mfma_f32_16x16x32_bf16 v[114:117], v[168:171], v[176:179], v[114:117]
	v_mfma_f32_16x16x32_bf16 v[102:105], v[160:163], v[184:187], v[102:105]
	v_mfma_f32_16x16x32_bf16 v[98:101], v[168:171], v[184:187], v[98:101]
	v_mfma_f32_16x16x32_bf16 v[86:89], v[160:163], v[208:211], v[86:89]
	v_mfma_f32_16x16x32_bf16 v[82:85], v[168:171], v[208:211], v[82:85]
	v_mfma_f32_16x16x32_bf16 v[70:73], v[160:163], v[216:219], v[70:73]
	v_mfma_f32_16x16x32_bf16 v[66:69], v[168:171], v[216:219], v[66:69]
	v_mfma_f32_16x16x32_bf16 v[118:121], v[164:167], v[180:183], v[118:121]
	v_mfma_f32_16x16x32_bf16 v[114:117], v[172:175], v[180:183], v[114:117]
	v_mfma_f32_16x16x32_bf16 v[102:105], v[164:167], v[188:191], v[102:105]
	v_mfma_f32_16x16x32_bf16 v[98:101], v[172:175], v[188:191], v[98:101]
	v_mfma_f32_16x16x32_bf16 v[86:89], v[164:167], v[212:215], v[86:89]
	v_mfma_f32_16x16x32_bf16 v[82:85], v[172:175], v[212:215], v[82:85]
	v_mfma_f32_16x16x32_bf16 v[70:73], v[164:167], v[220:223], v[70:73]
	v_mfma_f32_16x16x32_bf16 v[66:69], v[172:175], v[220:223], v[66:69]
	s_barrier
; #define PG8_STAGE(bufoff, gbase, voff) do { _Pragma("unroll") for (int _i = 0; _i < 2; ++_i) \
;         __builtin_amdgcn_global_load_lds((const unsigned*)((const char*)(gbase) + (voff)[_i]), (PG8_LAS unsigned*)(lds + (bufoff) + ldsw + _i * 8192), 16, 0, 0); } while (0)
; #define PG8_LDA(dst, b, h) do { _Pragma("unroll") for (int m = 0; m < 4; ++m) _Pragma("unroll") for (int k = 0; k < 2; ++k) dst[m][k] = *(const PG8_LAS bf16x8*)(lds + PG8_SA(b, h) + aoff + m * 2048 + k * 1024); } while (0)
; #define PG8_MMA(ai, bj, At, Bt) do { __builtin_amdgcn_s_setprio(1); _Pragma("unroll") for (int m = 0; m < 4; ++m) _Pragma("unroll") for (int n = 0; n < 2; ++n) _Pragma("unroll") for (int k = 0; k < 2; ++k) \
;         acc[ai][bj][m][n] = __builtin_amdgcn_mfma_f32_16x16x32_bf16(Bt[n][k], At[m][k], acc[ai][bj][m][n], 0, 0, 0); __builtin_amdgcn_s_setprio(0); } while (0)
; #define PG8_WAIT_V(n) asm volatile("s_waitcnt vmcnt(" #n ")" ::: "memory")
; #define PG8_WAIT_L(n) asm volatile("s_waitcnt lgkmcnt(" #n ")" ::: "memory")
; #define PG8_BAR __builtin_amdgcn_s_barrier()
; #define PG8_SCHED __builtin_amdgcn_sched_barrier(0)
; template <class Epi, class Sched, bool ALIGN_EPI = false, bool SP2 = false>
; __device__ __forceinline__ void gemm_phase(PG8_LAS unsigned char* lds, const Gemm g, const Sched& S, const Epi& E, int wid_in) {
;     ...
;         for (int t = 0; t < nt; t += 2) {
;             const bool last = (t == nt - 2);
;             const char* a1 = cA + (size_t)(t + 1) * kstep;
;             const char* a2 = last ? nA : cA + (size_t)(t + 2) * kstep; const char* b2 = last ? nB : cB + (size_t)(t + 2) * kstep;
;             const char* a3 = a2 + kstep; const char* b3 = b2 + kstep;
;             if (last && has_next) S.a_ready(nxt);
;     ...
;             PG8_LDA(At, 1, 1); PG8_STAGE(PG8_SB(1, 0), b3, voffB); PG8_STAGE(PG8_SB(1, 1), b3 + hstep, voffB); PG8_STAGE(PG8_SA(1, 0), a3, voffA);
;             PG8_WAIT_V(8); PG8_WAIT_L(0); PG8_BAR; PG8_MMA(1, 0, At, B0); PG8_MMA(1, 1, At, B1); PG8_BAR; PG8_SCHED;
	s_add_i32 s28, s40, s59
	v_lshl_add_u64 v[140:141], v[140:141], 0, s[94:95]
	s_mov_b32 m0, s28
	ds_read_b128 v[176:179], v143 offset:49152
	ds_read_b128 v[180:183], v143 offset:50176
	ds_read_b128 v[184:187], v143 offset:51200
	ds_read_b128 v[188:191], v143 offset:52224
	ds_read_b128 v[208:211], v143 offset:53248
	ds_read_b128 v[212:215], v143 offset:54272
	ds_read_b128 v[216:219], v143 offset:55296
	ds_read_b128 v[220:223], v143 offset:56320
	global_load_lds_dwordx4 v[140:141], off
	s_add_i32 m0, s28, 0x2000
	s_add_u32 s26, s26, 0x80080
	v_lshl_add_u64 v[140:141], v[192:193], 0, s[94:95]
	s_addc_u32 s27, s27, 0
	s_add_i32 s28, s41, s59
	global_load_lds_dwordx4 v[140:141], off
	v_lshl_add_u64 v[140:141], s[26:27], 0, v[0:1]
	s_mov_b32 m0, s28
	s_nop 0
	global_load_lds_dwordx4 v[140:141], off
	v_lshl_add_u64 v[140:141], s[26:27], 0, v[130:131]
	s_add_i32 m0, s28, 0x2000
	s_nop 0
	global_load_lds_dwordx4 v[140:141], off
	v_lshl_add_u64 v[140:141], v[224:225], 0, s[94:95]
	s_mov_b32 m0, s48
	s_nop 0
	global_load_lds_dwordx4 v[140:141], off
	v_lshl_add_u64 v[140:141], v[226:227], 0, s[94:95]
	s_mov_b32 m0, s52
	s_nop 0
	global_load_lds_dwordx4 v[140:141], off
	s_waitcnt vmcnt(8)
	s_waitcnt lgkmcnt(0)
	s_barrier
	s_waitcnt lgkmcnt(0)
	v_mfma_f32_16x16x32_bf16 v[62:65], v[144:147], v[176:179], v[62:65]
	v_mfma_f32_16x16x32_bf16 v[58:61], v[152:155], v[176:179], v[58:61]
	v_mfma_f32_16x16x32_bf16 v[46:49], v[144:147], v[184:187], v[46:49]
	v_mfma_f32_16x16x32_bf16 v[42:45], v[152:155], v[184:187], v[42:45]
	v_mfma_f32_16x16x32_bf16 v[30:33], v[144:147], v[208:211], v[30:33]
	v_mfma_f32_16x16x32_bf16 v[26:29], v[152:155], v[208:211], v[26:29]
	v_mfma_f32_16x16x32_bf16 v[14:17], v[144:147], v[216:219], v[14:17]
	v_mfma_f32_16x16x32_bf16 v[10:13], v[152:155], v[216:219], v[10:13]
	v_mfma_f32_16x16x32_bf16 v[62:65], v[148:151], v[180:183], v[62:65]
	v_mfma_f32_16x16x32_bf16 v[58:61], v[156:159], v[180:183], v[58:61]
	v_mfma_f32_16x16x32_bf16 v[46:49], v[148:151], v[188:191], v[46:49]
	v_mfma_f32_16x16x32_bf16 v[42:45], v[156:159], v[188:191], v[42:45]
	v_mfma_f32_16x16x32_bf16 v[30:33], v[148:151], v[212:215], v[30:33]
	v_mfma_f32_16x16x32_bf16 v[26:29], v[156:159], v[212:215], v[26:29]
	v_mfma_f32_16x16x32_bf16 v[14:17], v[148:151], v[220:223], v[14:17]
	v_mfma_f32_16x16x32_bf16 v[10:13], v[156:159], v[220:223], v[10:13]
	v_mfma_f32_16x16x32_bf16 v[54:57], v[160:163], v[176:179], v[54:57]
	v_mfma_f32_16x16x32_bf16 v[50:53], v[168:171], v[176:179], v[50:53]
	v_mfma_f32_16x16x32_bf16 v[38:41], v[160:163], v[184:187], v[38:41]
	v_mfma_f32_16x16x32_bf16 v[34:37], v[168:171], v[184:187], v[34:37]
	v_mfma_f32_16x16x32_bf16 v[22:25], v[160:163], v[208:211], v[22:25]
	v_mfma_f32_16x16x32_bf16 v[18:21], v[168:171], v[208:211], v[18:21]
	v_mfma_f32_16x16x32_bf16 v[6:9], v[160:163], v[216:219], v[6:9]
	v_mfma_f32_16x16x32_bf16 v[2:5], v[168:171], v[216:219], v[2:5]
	v_mfma_f32_16x16x32_bf16 v[54:57], v[164:167], v[180:183], v[54:57]
	v_mfma_f32_16x16x32_bf16 v[50:53], v[172:175], v[180:183], v[50:53]
	v_mfma_f32_16x16x32_bf16 v[38:41], v[164:167], v[188:191], v[38:41]
	v_mfma_f32_16x16x32_bf16 v[34:37], v[172:175], v[188:191], v[34:37]
	v_mfma_f32_16x16x32_bf16 v[22:25], v[164:167], v[212:215], v[22:25]
	v_mfma_f32_16x16x32_bf16 v[18:21], v[172:175], v[212:215], v[18:21]
	v_mfma_f32_16x16x32_bf16 v[6:9], v[164:167], v[220:223], v[6:9]
	v_mfma_f32_16x16x32_bf16 v[2:5], v[172:175], v[220:223], v[2:5]
	s_barrier
	s_add_i32 s73, s73, 2
	s_add_u32 s72, s72, 0x100
	s_addc_u32 s63, s63, 0
	s_add_u32 s24, s24, 0x100
	s_addc_u32 s25, s25, 0
	s_cmp_gt_u32 s73, 29
	s_cbranch_scc0 .LBB0_1153
	s_setprio 0
	s_and_b64 vcc, exec, s[14:15]
	s_cbranch_vccz .LBB0_1156
	s_barrier

; #define PG8_STAGE(bufoff, gbase, voff) do { _Pragma("unroll") for (int _i = 0; _i < 2; ++_i) \
;         __builtin_amdgcn_global_load_lds((const unsigned*)((const char*)(gbase) + (voff)[_i]), (PG8_LAS unsigned*)(lds + (bufoff) + ldsw + _i * 8192), 16, 0, 0); } while (0)
; #define PG8_LDA(dst, b, h) do { _Pragma("unroll") for (int m = 0; m < 4; ++m) _Pragma("unroll") for (int k = 0; k < 2; ++k) dst[m][k] = *(const PG8_LAS bf16x8*)(lds + PG8_SA(b, h) + aoff + m * 2048 + k * 1024); } while (0)
; #define PG8_LDB(dst, b, h) do { _Pragma("unroll") for (int n = 0; n < 2; ++n) _Pragma("unroll") for (int k = 0; k < 2; ++k) dst[n][k] = *(const PG8_LAS bf16x8*)(lds + PG8_SB(b, h) + boff + n * 2048 + k * 1024); } while (0)
; #define PG8_WAIT_V(n) asm volatile("s_waitcnt vmcnt(" #n ")" ::: "memory")
; #define PG8_WAIT_L(n) asm volatile("s_waitcnt lgkmcnt(" #n ")" ::: "memory")
; template <class Epi, class Sched, bool ALIGN_EPI = false, bool SP2 = false>
; __device__ __forceinline__ void gemm_phase(PG8_LAS unsigned char* lds, const Gemm g, const Sched& S, const Epi& E, int wid_in) {
;     ...
;         const bool has_next = S.next(ui + 1, nxt);
;         const char* nA = has_next ? (const char*)g.A + (size_t)nxt.pm * tstep + (size_t)nxt.kt0 * kstep : cA; const char* nB = has_next ? (const char*)g.Bt + (size_t)nxt.pn * tstep + (size_t)nxt.kt0 * kstep : cB;
;         const int nt = cur.nkt;
;         for (int t = 0; t < nt; t += 2) {
;             const bool last = (t == nt - 2);
;             const char* a1 = cA + (size_t)(t + 1) * kstep;
;             const char* a2 = last ? nA : cA + (size_t)(t + 2) * kstep; const char* b2 = last ? nB : cB + (size_t)(t + 2) * kstep;
;             const char* a3 = a2 + kstep; const char* b3 = b2 + kstep;
;             if (last && has_next) S.a_ready(nxt);
;             if constexpr (SP2) {
;             PG8_LDB(B0, 0, 0); PG8_LDB(B1, 0, 1); PG8_SCHED; PG8_LDA(At, 0, 0); PG8_STAGE(PG8_SA(1, 1), a1 + hstep, voffA);
;             PG8_WAIT_V(8); PG8_WAIT_L(0); PG8_BAR; PG8_MMA(0, 0, At, B0); PG8_MMA(0, 1, At, B1); PG8_BAR; PG8_SCHED;
;     ...
; #pragma unroll
;         for (int a = 0; a < 2; ++a)
; #pragma unroll
;             for (int b = 0; b < 2; ++b)
; #pragma unroll
;                 for (int m = 0; m < 4; ++m)
; #pragma unroll
;                     for (int n = 0; n < 2; ++n) acc[a][b][m][n] = (f32x4){0.f, 0.f, 0.f, 0.f};
.LBB0_1232:
	s_add_i32 s17, s90, -2
	s_add_u32 s19, s30, 0x100
	s_addc_u32 s21, s31, 0
	s_add_u32 s30, s34, 0x200080
	v_mov_b32_e32 v2, 0
	s_addc_u32 s31, s35, 0
	s_mov_b32 s27, 0
	v_mov_b32_e32 v3, v2
	v_mov_b32_e32 v4, v2
	v_mov_b32_e32 v5, v2
	v_mov_b32_e32 v6, v2
	v_mov_b32_e32 v7, v2
	v_mov_b32_e32 v8, v2
	v_mov_b32_e32 v9, v2
	v_mov_b32_e32 v10, v2
	v_mov_b32_e32 v11, v2
	v_mov_b32_e32 v12, v2
	v_mov_b32_e32 v13, v2
	v_mov_b32_e32 v14, v2
	v_mov_b32_e32 v15, v2
	v_mov_b32_e32 v16, v2
	v_mov_b32_e32 v17, v2
	v_mov_b32_e32 v26, v2
	v_mov_b32_e32 v27, v2
	v_mov_b32_e32 v28, v2
	v_mov_b32_e32 v29, v2
	v_mov_b32_e32 v30, v2
	v_mov_b32_e32 v31, v2
	v_mov_b32_e32 v32, v2
	v_mov_b32_e32 v33, v2
	v_mov_b32_e32 v42, v2
	v_mov_b32_e32 v43, v2
	v_mov_b32_e32 v44, v2
	v_mov_b32_e32 v45, v2
	v_mov_b32_e32 v46, v2
	v_mov_b32_e32 v47, v2
	v_mov_b32_e32 v48, v2
	v_mov_b32_e32 v49, v2
	v_mov_b32_e32 v18, v2
	v_mov_b32_e32 v19, v2
	v_mov_b32_e32 v20, v2
	v_mov_b32_e32 v21, v2
	v_mov_b32_e32 v22, v2
	v_mov_b32_e32 v23, v2
	v_mov_b32_e32 v24, v2
	v_mov_b32_e32 v25, v2
	v_mov_b32_e32 v34, v2
	v_mov_b32_e32 v35, v2
	v_mov_b32_e32 v36, v2
	v_mov_b32_e32 v37, v2
	v_mov_b32_e32 v38, v2
	v_mov_b32_e32 v39, v2
	v_mov_b32_e32 v40, v2
	v_mov_b32_e32 v41, v2
	v_mov_b32_e32 v50, v2
	v_mov_b32_e32 v51, v2
	v_mov_b32_e32 v52, v2
	v_mov_b32_e32 v53, v2
	v_mov_b32_e32 v54, v2
	v_mov_b32_e32 v55, v2
	v_mov_b32_e32 v56, v2
	v_mov_b32_e32 v57, v2
	v_mov_b32_e32 v58, v2
	v_mov_b32_e32 v59, v2
	v_mov_b32_e32 v60, v2
	v_mov_b32_e32 v61, v2
	v_mov_b32_e32 v62, v2
	v_mov_b32_e32 v63, v2
	v_mov_b32_e32 v64, v2
	v_mov_b32_e32 v65, v2
	v_mov_b32_e32 v66, v2
	v_mov_b32_e32 v67, v2
	v_mov_b32_e32 v68, v2
	v_mov_b32_e32 v69, v2
	v_mov_b32_e32 v70, v2
	v_mov_b32_e32 v71, v2
	v_mov_b32_e32 v72, v2
	v_mov_b32_e32 v73, v2
	v_mov_b32_e32 v74, v2
	v_mov_b32_e32 v75, v2
	v_mov_b32_e32 v76, v2
	v_mov_b32_e32 v77, v2
	v_mov_b32_e32 v78, v2
	v_mov_b32_e32 v79, v2
	v_mov_b32_e32 v80, v2
	v_mov_b32_e32 v81, v2
	v_mov_b32_e32 v90, v2
	v_mov_b32_e32 v91, v2
	v_mov_b32_e32 v92, v2
	v_mov_b32_e32 v93, v2
	v_mov_b32_e32 v94, v2
	v_mov_b32_e32 v95, v2
	v_mov_b32_e32 v96, v2
	v_mov_b32_e32 v97, v2
	v_mov_b32_e32 v106, v2
	v_mov_b32_e32 v107, v2
	v_mov_b32_e32 v108, v2
	v_mov_b32_e32 v109, v2
	v_mov_b32_e32 v110, v2
	v_mov_b32_e32 v111, v2
	v_mov_b32_e32 v112, v2
	v_mov_b32_e32 v113, v2
	v_mov_b32_e32 v82, v2
	v_mov_b32_e32 v83, v2
	v_mov_b32_e32 v84, v2
	v_mov_b32_e32 v85, v2
	v_mov_b32_e32 v86, v2
	v_mov_b32_e32 v87, v2
	v_mov_b32_e32 v88, v2
	v_mov_b32_e32 v89, v2
	v_mov_b32_e32 v98, v2
	v_mov_b32_e32 v99, v2
	v_mov_b32_e32 v100, v2
	v_mov_b32_e32 v101, v2
	v_mov_b32_e32 v102, v2
	v_mov_b32_e32 v103, v2
	v_mov_b32_e32 v104, v2
	v_mov_b32_e32 v105, v2
	v_mov_b32_e32 v114, v2
	v_mov_b32_e32 v115, v2
	v_mov_b32_e32 v116, v2
	v_mov_b32_e32 v117, v2
	v_mov_b32_e32 v118, v2
	v_mov_b32_e32 v119, v2
	v_mov_b32_e32 v120, v2
	v_mov_b32_e32 v121, v2
	v_mov_b32_e32 v122, v2
	v_mov_b32_e32 v123, v2
	v_mov_b32_e32 v124, v2
	v_mov_b32_e32 v125, v2
	v_mov_b32_e32 v126, v2
	v_mov_b32_e32 v127, v2
	v_mov_b32_e32 v128, v2
	v_mov_b32_e32 v129, v2
	s_cmp_ge_u32 s47, 4
	s_cbranch_scc0 .Lprio_skip_5
	s_setprio 1
.Lprio_skip_5:
.LBB0_1233:
	s_add_i32 s56, s27, 2
	s_add_u32 s34, s30, 0xffe00080
	s_addc_u32 s35, s31, -1
	s_add_i32 s40, 0, 0x10000
	s_cmp_eq_u32 s17, s27
	s_cselect_b32 s37, s23, s35
	s_cselect_b32 s36, s22, s34
	s_cselect_b32 s35, s25, s21
	s_cselect_b32 s34, s24, s19
	s_add_i32 s27, 0, 0x14000
	v_add_u32_e32 v142, s40, v176
	v_add_u32_e32 v168, s27, v176
	ds_read_b128 v[130:133], v142
	ds_read_b128 v[134:137], v142 offset:1024
	ds_read_b128 v[138:141], v142 offset:2048
	ds_read_b128 v[142:145], v142 offset:3072
	ds_read_b128 v[146:149], v168
	ds_read_b128 v[160:163], v168 offset:1024
	ds_read_b128 v[164:167], v168 offset:2048
	ds_read_b128 v[168:171], v168 offset:3072
	v_lshl_add_u64 v[220:221], s[30:31], 0, v[158:159]
	s_add_i32 m0, s29, 0xc000
	ds_read_b128 v[172:175], v177
	ds_read_b128 v[178:181], v177 offset:1024
	ds_read_b128 v[182:185], v177 offset:2048
	ds_read_b128 v[186:189], v177 offset:3072
	ds_read_b128 v[190:193], v177 offset:4096
	ds_read_b128 v[208:211], v177 offset:5120
	ds_read_b128 v[212:215], v177 offset:6144
	ds_read_b128 v[216:219], v177 offset:7168
	global_load_lds_dwordx4 v[220:221], off
	v_lshl_add_u64 v[220:221], s[30:31], 0, v[156:157]
	s_add_i32 m0, s29, 0xe000
	s_nop 0
	global_load_lds_dwordx4 v[220:221], off
	s_waitcnt vmcnt(8)
	s_waitcnt lgkmcnt(0)
	s_barrier
; #define PG8_STAGE(bufoff, gbase, voff) do { _Pragma("unroll") for (int _i = 0; _i < 2; ++_i) \
;         __builtin_amdgcn_global_load_lds((const unsigned*)((const char*)(gbase) + (voff)[_i]), (PG8_LAS unsigned*)(lds + (bufoff) + ldsw + _i * 8192), 16, 0, 0); } while (0)
; #define PG8_LDA(dst, b, h) do { _Pragma("unroll") for (int m = 0; m < 4; ++m) _Pragma("unroll") for (int k = 0; k < 2; ++k) dst[m][k] = *(const PG8_LAS bf16x8*)(lds + PG8_SA(b, h) + aoff + m * 2048 + k * 1024); } while (0)
; #define PG8_LDB(dst, b, h) do { _Pragma("unroll") for (int n = 0; n < 2; ++n) _Pragma("unroll") for (int k = 0; k < 2; ++k) dst[n][k] = *(const PG8_LAS bf16x8*)(lds + PG8_SB(b, h) + boff + n * 2048 + k * 1024); } while (0)
; #define PG8_MMA(ai, bj, At, Bt) do { __builtin_amdgcn_s_setprio(1); _Pragma("unroll") for (int m = 0; m < 4; ++m) _Pragma("unroll") for (int n = 0; n < 2; ++n) _Pragma("unroll") for (int k = 0; k < 2; ++k) \
;         acc[ai][bj][m][n] = __builtin_amdgcn_mfma_f32_16x16x32_bf16(Bt[n][k], At[m][k], acc[ai][bj][m][n], 0, 0, 0); __builtin_amdgcn_s_setprio(0); } while (0)
; #define PG8_WAIT_V(n) asm volatile("s_waitcnt vmcnt(" #n ")" ::: "memory")
; #define PG8_WAIT_L(n) asm volatile("s_waitcnt lgkmcnt(" #n ")" ::: "memory")
; #define PG8_BAR __builtin_amdgcn_s_barrier()
; #define PG8_SCHED __builtin_amdgcn_sched_barrier(0)
; template <class Epi, class Sched, bool ALIGN_EPI = false, bool SP2 = false>
; __device__ __forceinline__ void gemm_phase(PG8_LAS unsigned char* lds, const Gemm g, const Sched& S, const Epi& E, int wid_in) {
;     ...
;             PG8_WAIT_V(8); PG8_WAIT_L(0); PG8_BAR; PG8_MMA(0, 0, At, B0); PG8_MMA(0, 1, At, B1); PG8_BAR; PG8_SCHED;
;             PG8_LDA(At, 0, 1); PG8_STAGE(PG8_SB(0, 0), b2, voffB); PG8_STAGE(PG8_SB(0, 1), b2 + hstep, voffB); PG8_STAGE(PG8_SA(0, 0), a2, voffA);
;             PG8_WAIT_V(8); PG8_WAIT_L(0); PG8_BAR; PG8_MMA(1, 0, At, B0); PG8_MMA(1, 1, At, B1); PG8_BAR; PG8_SCHED;
;             PG8_LDB(B0, 1, 0); PG8_LDB(B1, 1, 1); PG8_SCHED; PG8_LDA(At, 1, 0); PG8_STAGE(PG8_SA(0, 1), a2 + hstep, voffA);
	s_waitcnt lgkmcnt(0)
	v_mfma_f32_16x16x32_bf16 v[126:129], v[130:133], v[172:175], v[126:129]
	v_mfma_f32_16x16x32_bf16 v[122:125], v[138:141], v[172:175], v[122:125]
	v_mfma_f32_16x16x32_bf16 v[118:121], v[130:133], v[182:185], v[118:121]
	v_mfma_f32_16x16x32_bf16 v[114:117], v[138:141], v[182:185], v[114:117]
	v_mfma_f32_16x16x32_bf16 v[102:105], v[130:133], v[190:193], v[102:105]
	v_mfma_f32_16x16x32_bf16 v[98:101], v[138:141], v[190:193], v[98:101]
	v_mfma_f32_16x16x32_bf16 v[86:89], v[130:133], v[212:215], v[86:89]
	v_mfma_f32_16x16x32_bf16 v[82:85], v[138:141], v[212:215], v[82:85]
	v_mfma_f32_16x16x32_bf16 v[126:129], v[134:137], v[178:181], v[126:129]
	v_mfma_f32_16x16x32_bf16 v[122:125], v[142:145], v[178:181], v[122:125]
	v_mfma_f32_16x16x32_bf16 v[118:121], v[134:137], v[186:189], v[118:121]
	v_mfma_f32_16x16x32_bf16 v[114:117], v[142:145], v[186:189], v[114:117]
	v_mfma_f32_16x16x32_bf16 v[102:105], v[134:137], v[208:211], v[102:105]
	v_mfma_f32_16x16x32_bf16 v[98:101], v[142:145], v[208:211], v[98:101]
	v_mfma_f32_16x16x32_bf16 v[86:89], v[134:137], v[216:219], v[86:89]
	v_mfma_f32_16x16x32_bf16 v[82:85], v[142:145], v[216:219], v[82:85]
	v_mfma_f32_16x16x32_bf16 v[110:113], v[146:149], v[172:175], v[110:113]
	v_mfma_f32_16x16x32_bf16 v[106:109], v[164:167], v[172:175], v[106:109]
	v_mfma_f32_16x16x32_bf16 v[94:97], v[146:149], v[182:185], v[94:97]
	v_mfma_f32_16x16x32_bf16 v[90:93], v[164:167], v[182:185], v[90:93]
	v_mfma_f32_16x16x32_bf16 v[78:81], v[146:149], v[190:193], v[78:81]
	v_mfma_f32_16x16x32_bf16 v[74:77], v[164:167], v[190:193], v[74:77]
	v_mfma_f32_16x16x32_bf16 v[70:73], v[146:149], v[212:215], v[70:73]
	v_mfma_f32_16x16x32_bf16 v[66:69], v[164:167], v[212:215], v[66:69]
	v_mfma_f32_16x16x32_bf16 v[110:113], v[160:163], v[178:181], v[110:113]
	v_mfma_f32_16x16x32_bf16 v[106:109], v[168:171], v[178:181], v[106:109]
	v_mfma_f32_16x16x32_bf16 v[94:97], v[160:163], v[186:189], v[94:97]
	v_mfma_f32_16x16x32_bf16 v[90:93], v[168:171], v[186:189], v[90:93]
	v_mfma_f32_16x16x32_bf16 v[78:81], v[160:163], v[208:211], v[78:81]
	v_mfma_f32_16x16x32_bf16 v[74:77], v[168:171], v[208:211], v[74:77]
	v_mfma_f32_16x16x32_bf16 v[70:73], v[160:163], v[216:219], v[70:73]
	v_mfma_f32_16x16x32_bf16 v[66:69], v[168:171], v[216:219], v[66:69]
	s_barrier
	s_add_i32 s40, s40, s59
	v_lshl_add_u64 v[220:221], s[34:35], 0, v[0:1]
	s_mov_b32 m0, s40
	ds_read_b128 v[172:175], v177 offset:16384
	ds_read_b128 v[178:181], v177 offset:17408
	ds_read_b128 v[182:185], v177 offset:18432
	ds_read_b128 v[186:189], v177 offset:19456
	ds_read_b128 v[190:193], v177 offset:20480
	ds_read_b128 v[208:211], v177 offset:21504
	ds_read_b128 v[212:215], v177 offset:22528
	ds_read_b128 v[216:219], v177 offset:23552
	global_load_lds_dwordx4 v[220:221], off
	s_add_i32 m0, s40, 0x2000
	s_add_u32 s40, s34, 0x200000
	v_lshl_add_u64 v[222:223], s[34:35], 0, v[154:155]
	s_addc_u32 s41, s35, 0
	s_add_i32 s27, s27, s59
	global_load_lds_dwordx4 v[222:223], off
	v_lshl_add_u64 v[224:225], s[40:41], 0, v[0:1]
	s_mov_b32 m0, s27
	v_lshl_add_u64 v[226:227], s[36:37], 0, v[152:153]
	global_load_lds_dwordx4 v[224:225], off
	v_lshl_add_u64 v[224:225], s[40:41], 0, v[154:155]
	s_add_i32 m0, s27, 0x2000
	s_nop 0
	global_load_lds_dwordx4 v[224:225], off
	v_lshl_add_u64 v[224:225], s[36:37], 0, v[150:151]
	s_mov_b32 m0, s29
	s_nop 0
	global_load_lds_dwordx4 v[224:225], off
	s_mov_b32 m0, s52
	s_nop 0
	global_load_lds_dwordx4 v[226:227], off
	s_waitcnt vmcnt(8)
	s_waitcnt lgkmcnt(0)
	s_barrier
	s_waitcnt lgkmcnt(0)
	v_mfma_f32_16x16x32_bf16 v[62:65], v[130:133], v[172:175], v[62:65]
	v_mfma_f32_16x16x32_bf16 v[58:61], v[138:141], v[172:175], v[58:61]
	v_mfma_f32_16x16x32_bf16 v[54:57], v[130:133], v[182:185], v[54:57]
	v_mfma_f32_16x16x32_bf16 v[50:53], v[138:141], v[182:185], v[50:53]
	v_mfma_f32_16x16x32_bf16 v[38:41], v[130:133], v[190:193], v[38:41]
	v_mfma_f32_16x16x32_bf16 v[34:37], v[138:141], v[190:193], v[34:37]
	v_mfma_f32_16x16x32_bf16 v[22:25], v[130:133], v[212:215], v[22:25]
	v_mfma_f32_16x16x32_bf16 v[18:21], v[138:141], v[212:215], v[18:21]
	v_mfma_f32_16x16x32_bf16 v[62:65], v[134:137], v[178:181], v[62:65]
	v_mfma_f32_16x16x32_bf16 v[58:61], v[142:145], v[178:181], v[58:61]
	v_mfma_f32_16x16x32_bf16 v[54:57], v[134:137], v[186:189], v[54:57]
	v_mfma_f32_16x16x32_bf16 v[50:53], v[142:145], v[186:189], v[50:53]
	v_mfma_f32_16x16x32_bf16 v[38:41], v[134:137], v[208:211], v[38:41]
	v_mfma_f32_16x16x32_bf16 v[34:37], v[142:145], v[208:211], v[34:37]
	v_mfma_f32_16x16x32_bf16 v[22:25], v[134:137], v[216:219], v[22:25]
	v_mfma_f32_16x16x32_bf16 v[18:21], v[142:145], v[216:219], v[18:21]
	v_mfma_f32_16x16x32_bf16 v[46:49], v[146:149], v[172:175], v[46:49]
	v_mfma_f32_16x16x32_bf16 v[42:45], v[164:167], v[172:175], v[42:45]
	v_mfma_f32_16x16x32_bf16 v[30:33], v[146:149], v[182:185], v[30:33]
	v_mfma_f32_16x16x32_bf16 v[26:29], v[164:167], v[182:185], v[26:29]
	v_mfma_f32_16x16x32_bf16 v[14:17], v[146:149], v[190:193], v[14:17]
	v_mfma_f32_16x16x32_bf16 v[10:13], v[164:167], v[190:193], v[10:13]
	v_mfma_f32_16x16x32_bf16 v[6:9], v[146:149], v[212:215], v[6:9]
	v_mfma_f32_16x16x32_bf16 v[2:5], v[164:167], v[212:215], v[2:5]
	v_mfma_f32_16x16x32_bf16 v[46:49], v[160:163], v[178:181], v[46:49]
	v_mfma_f32_16x16x32_bf16 v[42:45], v[168:171], v[178:181], v[42:45]
	v_mfma_f32_16x16x32_bf16 v[30:33], v[160:163], v[186:189], v[30:33]
	v_mfma_f32_16x16x32_bf16 v[26:29], v[168:171], v[186:189], v[26:29]
	v_mfma_f32_16x16x32_bf16 v[14:17], v[160:163], v[208:211], v[14:17]
	v_mfma_f32_16x16x32_bf16 v[10:13], v[168:171], v[208:211], v[10:13]
	v_mfma_f32_16x16x32_bf16 v[6:9], v[160:163], v[216:219], v[6:9]
	v_mfma_f32_16x16x32_bf16 v[2:5], v[168:171], v[216:219], v[2:5]
	s_barrier
; #define PG8_STAGE(bufoff, gbase, voff) do { _Pragma("unroll") for (int _i = 0; _i < 2; ++_i) \
;         __builtin_amdgcn_global_load_lds((const unsigned*)((const char*)(gbase) + (voff)[_i]), (PG8_LAS unsigned*)(lds + (bufoff) + ldsw + _i * 8192), 16, 0, 0); } while (0)
; #define PG8_LDA(dst, b, h) do { _Pragma("unroll") for (int m = 0; m < 4; ++m) _Pragma("unroll") for (int k = 0; k < 2; ++k) dst[m][k] = *(const PG8_LAS bf16x8*)(lds + PG8_SA(b, h) + aoff + m * 2048 + k * 1024); } while (0)
; #define PG8_LDB(dst, b, h) do { _Pragma("unroll") for (int n = 0; n < 2; ++n) _Pragma("unroll") for (int k = 0; k < 2; ++k) dst[n][k] = *(const PG8_LAS bf16x8*)(lds + PG8_SB(b, h) + boff + n * 2048 + k * 1024); } while (0)
; #define PG8_MMA(ai, bj, At, Bt) do { __builtin_amdgcn_s_setprio(1); _Pragma("unroll") for (int m = 0; m < 4; ++m) _Pragma("unroll") for (int n = 0; n < 2; ++n) _Pragma("unroll") for (int k = 0; k < 2; ++k) \
;         acc[ai][bj][m][n] = __builtin_amdgcn_mfma_f32_16x16x32_bf16(Bt[n][k], At[m][k], acc[ai][bj][m][n], 0, 0, 0); __builtin_amdgcn_s_setprio(0); } while (0)
; #define PG8_WAIT_V(n) asm volatile("s_waitcnt vmcnt(" #n ")" ::: "memory")
; #define PG8_WAIT_L(n) asm volatile("s_waitcnt lgkmcnt(" #n ")" ::: "memory")
; #define PG8_BAR __builtin_amdgcn_s_barrier()
; #define PG8_SCHED __builtin_amdgcn_sched_barrier(0)
; template <class Epi, class Sched, bool ALIGN_EPI = false, bool SP2 = false>
; __device__ __forceinline__ void gemm_phase(PG8_LAS unsigned char* lds, const Gemm g, const Sched& S, const Epi& E, int wid_in) {
;     ...
;             PG8_LDB(B0, 1, 0); PG8_LDB(B1, 1, 1); PG8_SCHED; PG8_LDA(At, 1, 0); PG8_STAGE(PG8_SA(0, 1), a2 + hstep, voffA);
;             PG8_WAIT_V(8); PG8_WAIT_L(0); PG8_BAR; PG8_MMA(0, 0, At, B0); PG8_MMA(0, 1, At, B1); PG8_BAR; PG8_SCHED;
	s_add_i32 s27, 0, 0x18000
	s_add_i32 s40, 0, 0x1c000
	v_add_u32_e32 v142, s27, v176
	v_add_u32_e32 v168, s40, v176
	ds_read_b128 v[130:133], v142
	ds_read_b128 v[134:137], v142 offset:1024
	ds_read_b128 v[138:141], v142 offset:2048
	ds_read_b128 v[142:145], v142 offset:3072
	ds_read_b128 v[146:149], v168
	ds_read_b128 v[160:163], v168 offset:1024
	ds_read_b128 v[164:167], v168 offset:2048
	ds_read_b128 v[168:171], v168 offset:3072
	s_add_u32 s36, s36, 0x200000
	s_addc_u32 s37, s37, 0
	s_mov_b32 m0, s53
	v_lshl_add_u64 v[228:229], s[36:37], 0, v[150:151]
	ds_read_b128 v[172:175], v177 offset:32768
	ds_read_b128 v[178:181], v177 offset:33792
	ds_read_b128 v[182:185], v177 offset:34816
	ds_read_b128 v[186:189], v177 offset:35840
	ds_read_b128 v[190:193], v177 offset:36864
	ds_read_b128 v[208:211], v177 offset:37888
	ds_read_b128 v[212:215], v177 offset:38912
	ds_read_b128 v[216:219], v177 offset:39936
	global_load_lds_dwordx4 v[228:229], off
	v_lshl_add_u64 v[228:229], s[36:37], 0, v[152:153]
	s_mov_b32 m0, s61
	s_nop 0
	global_load_lds_dwordx4 v[228:229], off
	s_waitcnt vmcnt(8)
	s_waitcnt lgkmcnt(0)
	s_barrier
	s_waitcnt lgkmcnt(0)
	v_mfma_f32_16x16x32_bf16 v[126:129], v[130:133], v[172:175], v[126:129]
	v_mfma_f32_16x16x32_bf16 v[122:125], v[138:141], v[172:175], v[122:125]
	v_mfma_f32_16x16x32_bf16 v[118:121], v[130:133], v[182:185], v[118:121]
	v_mfma_f32_16x16x32_bf16 v[114:117], v[138:141], v[182:185], v[114:117]
	v_mfma_f32_16x16x32_bf16 v[102:105], v[130:133], v[190:193], v[102:105]
	v_mfma_f32_16x16x32_bf16 v[98:101], v[138:141], v[190:193], v[98:101]
	v_mfma_f32_16x16x32_bf16 v[86:89], v[130:133], v[212:215], v[86:89]
	v_mfma_f32_16x16x32_bf16 v[82:85], v[138:141], v[212:215], v[82:85]
	v_mfma_f32_16x16x32_bf16 v[126:129], v[134:137], v[178:181], v[126:129]
	v_mfma_f32_16x16x32_bf16 v[122:125], v[142:145], v[178:181], v[122:125]
	v_mfma_f32_16x16x32_bf16 v[118:121], v[134:137], v[186:189], v[118:121]
	v_mfma_f32_16x16x32_bf16 v[114:117], v[142:145], v[186:189], v[114:117]
	v_mfma_f32_16x16x32_bf16 v[102:105], v[134:137], v[208:211], v[102:105]
	v_mfma_f32_16x16x32_bf16 v[98:101], v[142:145], v[208:211], v[98:101]
	v_mfma_f32_16x16x32_bf16 v[86:89], v[134:137], v[216:219], v[86:89]
	v_mfma_f32_16x16x32_bf16 v[82:85], v[142:145], v[216:219], v[82:85]
	v_mfma_f32_16x16x32_bf16 v[110:113], v[146:149], v[172:175], v[110:113]
	v_mfma_f32_16x16x32_bf16 v[106:109], v[164:167], v[172:175], v[106:109]
	v_mfma_f32_16x16x32_bf16 v[94:97], v[146:149], v[182:185], v[94:97]
	v_mfma_f32_16x16x32_bf16 v[90:93], v[164:167], v[182:185], v[90:93]
	v_mfma_f32_16x16x32_bf16 v[78:81], v[146:149], v[190:193], v[78:81]
	v_mfma_f32_16x16x32_bf16 v[74:77], v[164:167], v[190:193], v[74:77]
	v_mfma_f32_16x16x32_bf16 v[70:73], v[146:149], v[212:215], v[70:73]
	v_mfma_f32_16x16x32_bf16 v[66:69], v[164:167], v[212:215], v[66:69]
	v_mfma_f32_16x16x32_bf16 v[110:113], v[160:163], v[178:181], v[110:113]
	v_mfma_f32_16x16x32_bf16 v[106:109], v[168:171], v[178:181], v[106:109]
	v_mfma_f32_16x16x32_bf16 v[94:97], v[160:163], v[186:189], v[94:97]
	v_mfma_f32_16x16x32_bf16 v[90:93], v[168:171], v[186:189], v[90:93]
	v_mfma_f32_16x16x32_bf16 v[78:81], v[160:163], v[208:211], v[78:81]
	v_mfma_f32_16x16x32_bf16 v[74:77], v[168:171], v[208:211], v[74:77]
	v_mfma_f32_16x16x32_bf16 v[70:73], v[160:163], v[216:219], v[70:73]
	v_mfma_f32_16x16x32_bf16 v[66:69], v[168:171], v[216:219], v[66:69]
	s_barrier
; #define PG8_STAGE(bufoff, gbase, voff) do { _Pragma("unroll") for (int _i = 0; _i < 2; ++_i) \
;         __builtin_amdgcn_global_load_lds((const unsigned*)((const char*)(gbase) + (voff)[_i]), (PG8_LAS unsigned*)(lds + (bufoff) + ldsw + _i * 8192), 16, 0, 0); } while (0)
; #define PG8_LDA(dst, b, h) do { _Pragma("unroll") for (int m = 0; m < 4; ++m) _Pragma("unroll") for (int k = 0; k < 2; ++k) dst[m][k] = *(const PG8_LAS bf16x8*)(lds + PG8_SA(b, h) + aoff + m * 2048 + k * 1024); } while (0)
; #define PG8_MMA(ai, bj, At, Bt) do { __builtin_amdgcn_s_setprio(1); _Pragma("unroll") for (int m = 0; m < 4; ++m) _Pragma("unroll") for (int n = 0; n < 2; ++n) _Pragma("unroll") for (int k = 0; k < 2; ++k) \
;         acc[ai][bj][m][n] = __builtin_amdgcn_mfma_f32_16x16x32_bf16(Bt[n][k], At[m][k], acc[ai][bj][m][n], 0, 0, 0); __builtin_amdgcn_s_setprio(0); } while (0)
; #define PG8_WAIT_V(n) asm volatile("s_waitcnt vmcnt(" #n ")" ::: "memory")
; #define PG8_WAIT_L(n) asm volatile("s_waitcnt lgkmcnt(" #n ")" ::: "memory")
; #define PG8_BAR __builtin_amdgcn_s_barrier()
; #define PG8_SCHED __builtin_amdgcn_sched_barrier(0)
; template <class Epi, class Sched, bool ALIGN_EPI = false, bool SP2 = false>
; __device__ __forceinline__ void gemm_phase(PG8_LAS unsigned char* lds, const Gemm g, const Sched& S, const Epi& E, int wid_in) {
;     ...
;         for (int t = 0; t < nt; t += 2) {
;             const bool last = (t == nt - 2);
;             const char* a1 = cA + (size_t)(t + 1) * kstep;
;             const char* a2 = last ? nA : cA + (size_t)(t + 2) * kstep; const char* b2 = last ? nB : cB + (size_t)(t + 2) * kstep;
;             const char* a3 = a2 + kstep; const char* b3 = b2 + kstep;
;             if (last && has_next) S.a_ready(nxt);
;     ...
;             PG8_LDA(At, 1, 1); PG8_STAGE(PG8_SB(1, 0), b3, voffB); PG8_STAGE(PG8_SB(1, 1), b3 + hstep, voffB); PG8_STAGE(PG8_SA(1, 0), a3, voffA);
;             PG8_WAIT_V(8); PG8_WAIT_L(0); PG8_BAR; PG8_MMA(1, 0, At, B0); PG8_MMA(1, 1, At, B1); PG8_BAR; PG8_SCHED;
	s_add_i32 s27, s27, s59
	v_lshl_add_u64 v[220:221], v[220:221], 0, s[94:95]
	s_mov_b32 m0, s27
	ds_read_b128 v[172:175], v177 offset:49152
	ds_read_b128 v[178:181], v177 offset:50176
	ds_read_b128 v[182:185], v177 offset:51200
	ds_read_b128 v[186:189], v177 offset:52224
	ds_read_b128 v[190:193], v177 offset:53248
	ds_read_b128 v[208:211], v177 offset:54272
	ds_read_b128 v[212:215], v177 offset:55296
	ds_read_b128 v[216:219], v177 offset:56320
	global_load_lds_dwordx4 v[220:221], off
	s_add_i32 m0, s27, 0x2000
	s_add_u32 s34, s34, 0x200080
	v_lshl_add_u64 v[220:221], v[222:223], 0, s[94:95]
	s_addc_u32 s35, s35, 0
	s_add_i32 s27, s40, s59
	global_load_lds_dwordx4 v[220:221], off
	v_lshl_add_u64 v[220:221], s[34:35], 0, v[0:1]
	s_mov_b32 m0, s27
	s_nop 0
	global_load_lds_dwordx4 v[220:221], off
	v_lshl_add_u64 v[220:221], s[34:35], 0, v[154:155]
	s_add_i32 m0, s27, 0x2000
	s_nop 0
	global_load_lds_dwordx4 v[220:221], off
	v_lshl_add_u64 v[220:221], v[224:225], 0, s[94:95]
	s_mov_b32 m0, s73
	s_nop 0
	global_load_lds_dwordx4 v[220:221], off
	v_lshl_add_u64 v[220:221], v[226:227], 0, s[94:95]
	s_mov_b32 m0, s80
	s_nop 0
	global_load_lds_dwordx4 v[220:221], off
	s_waitcnt vmcnt(8)
	s_waitcnt lgkmcnt(0)
	s_barrier
	s_waitcnt lgkmcnt(0)
	v_mfma_f32_16x16x32_bf16 v[62:65], v[130:133], v[172:175], v[62:65]
	v_mfma_f32_16x16x32_bf16 v[58:61], v[138:141], v[172:175], v[58:61]
	v_mfma_f32_16x16x32_bf16 v[54:57], v[130:133], v[182:185], v[54:57]
	v_mfma_f32_16x16x32_bf16 v[50:53], v[138:141], v[182:185], v[50:53]
	v_mfma_f32_16x16x32_bf16 v[38:41], v[130:133], v[190:193], v[38:41]
	v_mfma_f32_16x16x32_bf16 v[34:37], v[138:141], v[190:193], v[34:37]
	v_mfma_f32_16x16x32_bf16 v[22:25], v[130:133], v[212:215], v[22:25]
	v_mfma_f32_16x16x32_bf16 v[18:21], v[138:141], v[212:215], v[18:21]
	v_mfma_f32_16x16x32_bf16 v[62:65], v[134:137], v[178:181], v[62:65]
	v_mfma_f32_16x16x32_bf16 v[58:61], v[142:145], v[178:181], v[58:61]
	v_mfma_f32_16x16x32_bf16 v[54:57], v[134:137], v[186:189], v[54:57]
	v_mfma_f32_16x16x32_bf16 v[50:53], v[142:145], v[186:189], v[50:53]
	v_mfma_f32_16x16x32_bf16 v[38:41], v[134:137], v[208:211], v[38:41]
	v_mfma_f32_16x16x32_bf16 v[34:37], v[142:145], v[208:211], v[34:37]
	v_mfma_f32_16x16x32_bf16 v[22:25], v[134:137], v[216:219], v[22:25]
	v_mfma_f32_16x16x32_bf16 v[18:21], v[142:145], v[216:219], v[18:21]
	v_mfma_f32_16x16x32_bf16 v[46:49], v[146:149], v[172:175], v[46:49]
	v_mfma_f32_16x16x32_bf16 v[42:45], v[164:167], v[172:175], v[42:45]
	v_mfma_f32_16x16x32_bf16 v[30:33], v[146:149], v[182:185], v[30:33]
	v_mfma_f32_16x16x32_bf16 v[26:29], v[164:167], v[182:185], v[26:29]
	v_mfma_f32_16x16x32_bf16 v[14:17], v[146:149], v[190:193], v[14:17]
	v_mfma_f32_16x16x32_bf16 v[10:13], v[164:167], v[190:193], v[10:13]
	v_mfma_f32_16x16x32_bf16 v[6:9], v[146:149], v[212:215], v[6:9]
	v_mfma_f32_16x16x32_bf16 v[2:5], v[164:167], v[212:215], v[2:5]
	v_mfma_f32_16x16x32_bf16 v[46:49], v[160:163], v[178:181], v[46:49]
	v_mfma_f32_16x16x32_bf16 v[42:45], v[168:171], v[178:181], v[42:45]
	v_mfma_f32_16x16x32_bf16 v[30:33], v[160:163], v[186:189], v[30:33]
	v_mfma_f32_16x16x32_bf16 v[26:29], v[168:171], v[186:189], v[26:29]
	v_mfma_f32_16x16x32_bf16 v[14:17], v[160:163], v[208:211], v[14:17]
	v_mfma_f32_16x16x32_bf16 v[10:13], v[168:171], v[208:211], v[10:13]
	v_mfma_f32_16x16x32_bf16 v[6:9], v[160:163], v[216:219], v[6:9]
	v_mfma_f32_16x16x32_bf16 v[2:5], v[168:171], v[216:219], v[2:5]
	s_barrier
	s_add_u32 s19, s19, 0x100
	s_addc_u32 s21, s21, 0
	s_add_u32 s30, s30, 0x100
	s_addc_u32 s31, s31, 0
	s_cmp_ge_i32 s56, s90
	s_mov_b32 s27, s56
	s_cbranch_scc0 .LBB0_1233
	s_setprio 0
	s_and_b64 vcc, exec, s[14:15]
	s_cbranch_vccz .LBB0_1236
	s_barrier
